# speedup vs baseline: 1.0185x; 1.0130x over previous
.Lh2_loop:
	ds_read_b128 v[140:143], v138
	ds_read_b128 v[144:147], v138 offset:1024
	ds_read_b128 v[148:151], v138 offset:2048
	ds_read_b128 v[152:155], v138 offset:3072
	s_add_u32 s8, s6, s65
	v_mov_b32_e32 v196, v129
	v_mov_b32_e32 v188, v130
	s_addc_u32 s9, s7, s66
	ds_read_b128 v[156:159], v134
	ds_read_b128 v[160:163], v134 offset:1024
	ds_read_b128 v[164:167], v133
	ds_read_b128 v[168:171], v133 offset:1024
	ds_read_b128 v[172:175], v132
	ds_read_b128 v[176:179], v132 offset:1024
	ds_read_b128 v[180:183], v131
	ds_read_b128 v[184:187], v131 offset:1024
	v_mov_b32_e32 v189, v197
	s_mov_b32 m0, s76
	s_mov_b32 m0, s75
	s_nop 0
	s_waitcnt lgkmcnt(8)
	s_barrier
	s_waitcnt lgkmcnt(0)
	s_setprio 1
	s_waitcnt lgkmcnt(0)
	v_mfma_f32_16x16x32_bf16 v[124:127], v[140:143], v[156:159], v[124:127]
	v_mfma_f32_16x16x32_bf16 v[120:123], v[148:151], v[156:159], v[120:123]
	v_mfma_f32_16x16x32_bf16 v[116:119], v[140:143], v[164:167], v[116:119]
	v_mfma_f32_16x16x32_bf16 v[112:115], v[148:151], v[164:167], v[112:115]
	v_mfma_f32_16x16x32_bf16 v[108:111], v[140:143], v[172:175], v[108:111]
	v_mfma_f32_16x16x32_bf16 v[104:107], v[148:151], v[172:175], v[104:107]
	v_mfma_f32_16x16x32_bf16 v[100:103], v[140:143], v[180:183], v[100:103]
	v_mfma_f32_16x16x32_bf16 v[96:99], v[148:151], v[180:183], v[96:99]
	v_mfma_f32_16x16x32_bf16 v[124:127], v[144:147], v[160:163], v[124:127]
	v_mfma_f32_16x16x32_bf16 v[120:123], v[152:155], v[160:163], v[120:123]
	v_mfma_f32_16x16x32_bf16 v[116:119], v[144:147], v[168:171], v[116:119]
	v_mfma_f32_16x16x32_bf16 v[112:115], v[152:155], v[168:171], v[112:115]
	v_mfma_f32_16x16x32_bf16 v[108:111], v[144:147], v[176:179], v[108:111]
	v_mfma_f32_16x16x32_bf16 v[104:107], v[152:155], v[176:179], v[104:107]
	v_mfma_f32_16x16x32_bf16 v[100:103], v[144:147], v[184:187], v[100:103]
	v_mfma_f32_16x16x32_bf16 v[96:99], v[152:155], v[184:187], v[96:99]
	s_setprio 0
	s_barrier
	s_add_u32 s10, s6, s36
	v_mov_b32_e32 v196, v129
	v_mov_b32_e32 v210, v130
	s_addc_u32 s11, s7, s37
	ds_read_b128 v[188:191], v137
	ds_read_b128 v[192:195], v137 offset:1024
	ds_read_b128 v[202:205], v137 offset:2048
	ds_read_b128 v[206:209], v137 offset:3072
	v_mov_b32_e32 v211, v197
	s_mov_b32 m0, s63
	s_add_u32 s98, s10, s46
	s_addc_u32 s99, s11, s47
	global_load_lds_dwordx4 v129, s[98:99]
	s_mov_b32 m0, s64
	s_nop 0
	global_load_lds_dwordx4 v130, s[98:99]
	s_barrier
	s_waitcnt lgkmcnt(0)
	s_setprio 1
	s_waitcnt lgkmcnt(0)
	v_mfma_f32_16x16x32_bf16 v[92:95], v[188:191], v[156:159], v[92:95]
	v_mfma_f32_16x16x32_bf16 v[88:91], v[202:205], v[156:159], v[88:91]
	v_mfma_f32_16x16x32_bf16 v[84:87], v[188:191], v[164:167], v[84:87]
	v_mfma_f32_16x16x32_bf16 v[80:83], v[202:205], v[164:167], v[80:83]
	v_mfma_f32_16x16x32_bf16 v[76:79], v[188:191], v[172:175], v[76:79]
	v_mfma_f32_16x16x32_bf16 v[72:75], v[202:205], v[172:175], v[72:75]
	v_mfma_f32_16x16x32_bf16 v[68:71], v[188:191], v[180:183], v[68:71]
	v_mfma_f32_16x16x32_bf16 v[64:67], v[202:205], v[180:183], v[64:67]
	v_mfma_f32_16x16x32_bf16 v[92:95], v[192:195], v[160:163], v[92:95]
	v_mfma_f32_16x16x32_bf16 v[88:91], v[206:209], v[160:163], v[88:91]
	v_mfma_f32_16x16x32_bf16 v[84:87], v[192:195], v[168:171], v[84:87]
	v_mfma_f32_16x16x32_bf16 v[80:83], v[206:209], v[168:171], v[80:83]
	v_mfma_f32_16x16x32_bf16 v[76:79], v[192:195], v[176:179], v[76:79]
	v_mfma_f32_16x16x32_bf16 v[72:75], v[206:209], v[176:179], v[72:75]
	v_mfma_f32_16x16x32_bf16 v[68:71], v[192:195], v[184:187], v[68:71]
	v_mfma_f32_16x16x32_bf16 v[64:67], v[206:209], v[184:187], v[64:67]
	s_setprio 0
	v_mov_b32_e32 v196, v129
	v_mov_b32_e32 v210, v130
	s_barrier
	v_mov_b32_e32 v211, v197
	s_mov_b32 m0, s62
	s_add_u32 s98, s8, s48
	s_addc_u32 s99, s9, s49
	global_load_lds_dwordx4 v129, s[98:99]
	s_mov_b32 m0, s67
	s_nop 0
	global_load_lds_dwordx4 v130, s[98:99]
	s_waitcnt vmcnt(4)
	s_barrier
	v_mov_b32_e32 v196, v129
	v_mov_b32_e32 v140, v130
	v_mov_b32_e32 v141, v197
	s_mov_b32 m0, s68
	s_add_u32 s98, s10, s50
	s_addc_u32 s99, s11, s51
	global_load_lds_dwordx4 v129, s[98:99]
	s_mov_b32 m0, s69
	s_nop 0
	global_load_lds_dwordx4 v130, s[98:99]
	s_barrier
	ds_read_b128 v[140:143], v136
	ds_read_b128 v[144:147], v136 offset:1024
	ds_read_b128 v[148:151], v136 offset:2048
	ds_read_b128 v[152:155], v136 offset:3072
	v_mov_b32_e32 v196, v129
	v_mov_b32_e32 v188, v130
	ds_read_b128 v[156:159], v134 offset:32768
	ds_read_b128 v[160:163], v134 offset:33792
	ds_read_b128 v[164:167], v133 offset:32768
	ds_read_b128 v[168:171], v133 offset:33792
	ds_read_b128 v[172:175], v132 offset:32768
	ds_read_b128 v[176:179], v132 offset:33792
	ds_read_b128 v[180:183], v131 offset:32768
	ds_read_b128 v[184:187], v131 offset:33792
	v_mov_b32_e32 v189, v197
	s_mov_b32 m0, s70
	s_mov_b32 m0, s71
	s_nop 0
	s_waitcnt lgkmcnt(8)
	s_barrier
	s_waitcnt lgkmcnt(0)
	s_setprio 1
	s_waitcnt lgkmcnt(0)
	v_mfma_f32_16x16x32_bf16 v[124:127], v[140:143], v[156:159], v[124:127]
	v_mfma_f32_16x16x32_bf16 v[120:123], v[148:151], v[156:159], v[120:123]
	v_mfma_f32_16x16x32_bf16 v[116:119], v[140:143], v[164:167], v[116:119]
	v_mfma_f32_16x16x32_bf16 v[112:115], v[148:151], v[164:167], v[112:115]
	v_mfma_f32_16x16x32_bf16 v[108:111], v[140:143], v[172:175], v[108:111]
	v_mfma_f32_16x16x32_bf16 v[104:107], v[148:151], v[172:175], v[104:107]
	v_mfma_f32_16x16x32_bf16 v[100:103], v[140:143], v[180:183], v[100:103]
	v_mfma_f32_16x16x32_bf16 v[96:99], v[148:151], v[180:183], v[96:99]
	v_mfma_f32_16x16x32_bf16 v[124:127], v[144:147], v[160:163], v[124:127]
	v_mfma_f32_16x16x32_bf16 v[120:123], v[152:155], v[160:163], v[120:123]
	v_mfma_f32_16x16x32_bf16 v[116:119], v[144:147], v[168:171], v[116:119]
	v_mfma_f32_16x16x32_bf16 v[112:115], v[152:155], v[168:171], v[112:115]
	v_mfma_f32_16x16x32_bf16 v[108:111], v[144:147], v[176:179], v[108:111]
	v_mfma_f32_16x16x32_bf16 v[104:107], v[152:155], v[176:179], v[104:107]
	v_mfma_f32_16x16x32_bf16 v[100:103], v[144:147], v[184:187], v[100:103]
	v_mfma_f32_16x16x32_bf16 v[96:99], v[152:155], v[184:187], v[96:99]
	s_setprio 0
	s_barrier
	v_mov_b32_e32 v196, v129
	v_mov_b32_e32 v210, v130
	ds_read_b128 v[188:191], v135
	ds_read_b128 v[192:195], v135 offset:1024
	ds_read_b128 v[202:205], v135 offset:2048
	ds_read_b128 v[206:209], v135 offset:3072
	v_mov_b32_e32 v211, v197
	s_mov_b32 m0, s28
	s_add_u32 s98, s10, s92
	s_addc_u32 s99, s11, s93
	global_load_lds_dwordx4 v129, s[98:99]
	s_mov_b32 m0, s29
	s_nop 0
	global_load_lds_dwordx4 v130, s[98:99]
	s_barrier
	s_waitcnt lgkmcnt(0)
	s_setprio 1
	s_waitcnt lgkmcnt(0)
	v_mfma_f32_16x16x32_bf16 v[92:95], v[188:191], v[156:159], v[92:95]
	v_mfma_f32_16x16x32_bf16 v[88:91], v[202:205], v[156:159], v[88:91]
	v_mfma_f32_16x16x32_bf16 v[84:87], v[188:191], v[164:167], v[84:87]
	v_mfma_f32_16x16x32_bf16 v[80:83], v[202:205], v[164:167], v[80:83]
	v_mfma_f32_16x16x32_bf16 v[76:79], v[188:191], v[172:175], v[76:79]
	v_mfma_f32_16x16x32_bf16 v[72:75], v[202:205], v[172:175], v[72:75]
	v_mfma_f32_16x16x32_bf16 v[68:71], v[188:191], v[180:183], v[68:71]
	v_mfma_f32_16x16x32_bf16 v[64:67], v[202:205], v[180:183], v[64:67]
	v_mfma_f32_16x16x32_bf16 v[92:95], v[192:195], v[160:163], v[92:95]
	v_mfma_f32_16x16x32_bf16 v[88:91], v[206:209], v[160:163], v[88:91]
	v_mfma_f32_16x16x32_bf16 v[84:87], v[192:195], v[168:171], v[84:87]
	v_mfma_f32_16x16x32_bf16 v[80:83], v[206:209], v[168:171], v[80:83]
	v_mfma_f32_16x16x32_bf16 v[76:79], v[192:195], v[176:179], v[76:79]
	v_mfma_f32_16x16x32_bf16 v[72:75], v[206:209], v[176:179], v[72:75]
	v_mfma_f32_16x16x32_bf16 v[68:71], v[192:195], v[184:187], v[68:71]
	v_mfma_f32_16x16x32_bf16 v[64:67], v[206:209], v[184:187], v[64:67]
	s_setprio 0
	v_mov_b32_e32 v196, v129
	v_mov_b32_e32 v210, v130
	s_barrier
	v_mov_b32_e32 v211, v197
	s_mov_b32 m0, s72
	s_add_u32 s98, s8, s96
	s_addc_u32 s99, s9, s97
	global_load_lds_dwordx4 v129, s[98:99]
	s_mov_b32 m0, s73
	s_nop 0
	global_load_lds_dwordx4 v130, s[98:99]
	s_waitcnt vmcnt(4)
	s_barrier
	v_mov_b32_e32 v196, v129
	v_mov_b32_e32 v140, v130
	v_mov_b32_e32 v141, v197
	s_mov_b32 m0, s33
	s_add_u32 s98, s10, vcc_lo
	s_addc_u32 s99, s11, vcc_hi
	global_load_lds_dwordx4 v129, s[98:99]
	s_mov_b32 m0, s74
	s_nop 0
	global_load_lds_dwordx4 v130, s[98:99]
	s_barrier
	s_add_i32 s38, s38, 2
	s_add_u32 s6, s6, 0x100
	s_addc_u32 s7, s7, 0
	s_cmpk_lt_u32 s38, 0x54
	s_cbranch_scc1 .Lh2_loop
	s_add_u32 s4, s4, 0x2b80
	s_addc_u32 s5, s5, 0
	s_mov_b32 m0, s76
	ds_read_b128 v[140:143], v138
	ds_read_b128 v[144:147], v138 offset:1024
	ds_read_b128 v[148:151], v138 offset:2048
	ds_read_b128 v[152:155], v138 offset:3072
	ds_read_b128 v[156:159], v134
	ds_read_b128 v[160:163], v134 offset:1024
	ds_read_b128 v[164:167], v133
	ds_read_b128 v[168:171], v133 offset:1024
	ds_read_b128 v[172:175], v132
	ds_read_b128 v[176:179], v132 offset:1024
	ds_read_b128 v[180:183], v131
	ds_read_b128 v[184:187], v131 offset:1024
	s_nop 0
	s_mov_b32 m0, s75
	s_nop 0
	s_barrier
	s_waitcnt lgkmcnt(0)
	s_setprio 1
	s_waitcnt lgkmcnt(0)
	v_mfma_f32_16x16x32_bf16 v[124:127], v[140:143], v[156:159], v[124:127]
	v_mfma_f32_16x16x32_bf16 v[120:123], v[148:151], v[156:159], v[120:123]
	v_mfma_f32_16x16x32_bf16 v[116:119], v[140:143], v[164:167], v[116:119]
	v_mfma_f32_16x16x32_bf16 v[112:115], v[148:151], v[164:167], v[112:115]
	v_mfma_f32_16x16x32_bf16 v[108:111], v[140:143], v[172:175], v[108:111]
	v_mfma_f32_16x16x32_bf16 v[100:103], v[140:143], v[180:183], v[100:103]
	v_mfma_f32_16x16x32_bf16 v[96:99], v[148:151], v[180:183], v[96:99]
	v_mfma_f32_16x16x32_bf16 v[124:127], v[144:147], v[160:163], v[124:127]
	v_mfma_f32_16x16x32_bf16 v[120:123], v[152:155], v[160:163], v[120:123]
	v_mfma_f32_16x16x32_bf16 v[116:119], v[144:147], v[168:171], v[116:119]
	v_mfma_f32_16x16x32_bf16 v[112:115], v[152:155], v[168:171], v[112:115]
	v_mfma_f32_16x16x32_bf16 v[108:111], v[144:147], v[176:179], v[108:111]
	v_mfma_f32_16x16x32_bf16 v[104:107], v[148:151], v[172:175], v[104:107]
	v_mfma_f32_16x16x32_bf16 v[100:103], v[144:147], v[184:187], v[100:103]
	v_mfma_f32_16x16x32_bf16 v[96:99], v[152:155], v[184:187], v[96:99]
	v_mfma_f32_16x16x32_bf16 v[188:191], v[152:155], v[176:179], v[104:107]
	s_setprio 0
	s_barrier
	s_nop 2
	ds_read_b128 v[104:107], v137
	ds_read_b128 v[192:195], v137 offset:1024
	ds_read_b128 v[202:205], v137 offset:2048
	ds_read_b128 v[206:209], v137 offset:3072
	s_barrier
	s_waitcnt lgkmcnt(0)
	s_setprio 1
	s_waitcnt lgkmcnt(0)
	v_mfma_f32_16x16x32_bf16 v[92:95], v[104:107], v[156:159], v[92:95]
	v_mfma_f32_16x16x32_bf16 v[88:91], v[202:205], v[156:159], v[88:91]
	v_mfma_f32_16x16x32_bf16 v[80:83], v[202:205], v[164:167], v[80:83]
	v_mfma_f32_16x16x32_bf16 v[72:75], v[202:205], v[172:175], v[72:75]
	v_mfma_f32_16x16x32_bf16 v[64:67], v[202:205], v[180:183], v[64:67]
	v_mfma_f32_16x16x32_bf16 v[92:95], v[192:195], v[160:163], v[92:95]
	v_mfma_f32_16x16x32_bf16 v[88:91], v[206:209], v[160:163], v[88:91]
	v_mfma_f32_16x16x32_bf16 v[84:87], v[104:107], v[164:167], v[84:87]
	v_mfma_f32_16x16x32_bf16 v[80:83], v[206:209], v[168:171], v[80:83]
	v_mfma_f32_16x16x32_bf16 v[76:79], v[104:107], v[172:175], v[76:79]
	v_mfma_f32_16x16x32_bf16 v[72:75], v[206:209], v[176:179], v[72:75]
	v_mfma_f32_16x16x32_bf16 v[68:71], v[104:107], v[180:183], v[68:71]
	v_mfma_f32_16x16x32_bf16 v[64:67], v[206:209], v[184:187], v[64:67]
	v_mfma_f32_16x16x32_bf16 v[156:159], v[192:195], v[168:171], v[84:87]
	v_mfma_f32_16x16x32_bf16 v[160:163], v[192:195], v[176:179], v[76:79]
	v_mfma_f32_16x16x32_bf16 v[164:167], v[192:195], v[184:187], v[68:71]
	s_setprio 0
	s_barrier
	s_nop 1
	s_waitcnt vmcnt(2)
	s_barrier
	s_waitcnt lgkmcnt(0)
	s_setprio 1
	s_waitcnt lgkmcnt(0)
	s_setprio 0
	s_setprio 1
	s_setprio 0
	s_barrier
	ds_read_b128 v[16:19], v136
	ds_read_b128 v[180:183], v136 offset:1024
	ds_read_b128 v[184:187], v136 offset:2048
	ds_read_b128 v[192:195], v136 offset:3072
	ds_read_b128 v[0:3], v134 offset:32768
	ds_read_b128 v[4:7], v134 offset:33792
	ds_read_b128 v[8:11], v133 offset:32768
	ds_read_b128 v[12:15], v133 offset:33792
	ds_read_b128 v[44:47], v132 offset:32768
	ds_read_b128 v[202:205], v132 offset:33792
	ds_read_b128 v[206:209], v131 offset:32768
	ds_read_b128 v[222:225], v131 offset:33792
	s_waitcnt vmcnt(0)
	s_barrier
	s_waitcnt lgkmcnt(0)
	s_setprio 1
	s_waitcnt lgkmcnt(0)
	v_mfma_f32_16x16x32_bf16 v[28:31], v[16:19], v[0:3], v[124:127]
	v_mfma_f32_16x16x32_bf16 v[52:55], v[180:183], v[4:7], v[28:31]
	v_mfma_f32_16x16x32_bf16 v[28:31], v[184:187], v[0:3], v[120:123]
	v_mfma_f32_16x16x32_bf16 v[104:107], v[192:195], v[4:7], v[28:31]
	v_mfma_f32_16x16x32_bf16 v[28:31], v[16:19], v[8:11], v[116:119]
	v_mfma_f32_16x16x32_bf16 v[68:71], v[180:183], v[12:15], v[28:31]
	v_mfma_f32_16x16x32_bf16 v[28:31], v[184:187], v[8:11], v[112:115]
	v_mfma_f32_16x16x32_bf16 v[116:119], v[192:195], v[12:15], v[28:31]
	v_mfma_f32_16x16x32_bf16 v[28:31], v[16:19], v[44:47], v[108:111]
	v_mfma_f32_16x16x32_bf16 v[76:79], v[180:183], v[202:205], v[28:31]
	v_mfma_f32_16x16x32_bf16 v[28:31], v[184:187], v[44:47], v[188:191]
	v_mfma_f32_16x16x32_bf16 v[108:111], v[192:195], v[202:205], v[28:31]
	v_mfma_f32_16x16x32_bf16 v[28:31], v[16:19], v[206:209], v[100:103]
	v_mfma_f32_16x16x32_bf16 v[84:87], v[180:183], v[222:225], v[28:31]
	v_mfma_f32_16x16x32_bf16 v[28:31], v[184:187], v[206:209], v[96:99]
	v_mfma_f32_16x16x32_bf16 v[96:99], v[192:195], v[222:225], v[28:31]
	s_setprio 0
	s_barrier
	ds_read_b128 v[188:191], v135
	ds_read_b128 v[228:231], v135 offset:1024
	ds_read_b128 v[232:235], v135 offset:2048
	ds_read_b128 v[236:239], v135 offset:3072
	s_waitcnt vmcnt(0)
	s_barrier
	s_waitcnt lgkmcnt(0)
	s_setprio 1
	s_waitcnt lgkmcnt(0)
	v_mfma_f32_16x16x32_bf16 v[28:31], v[188:191], v[0:3], v[92:95]
	v_mfma_f32_16x16x32_bf16 v[0:3], v[232:235], v[0:3], v[88:91]
	v_mfma_f32_16x16x32_bf16 v[28:31], v[228:231], v[4:7], v[28:31]
	v_mfma_f32_16x16x32_bf16 v[0:3], v[236:239], v[4:7], v[0:3]
	v_mfma_f32_16x16x32_bf16 v[4:7], v[188:191], v[8:11], v[156:159]
	v_mfma_f32_16x16x32_bf16 v[36:39], v[228:231], v[12:15], v[4:7]
	v_mfma_f32_16x16x32_bf16 v[4:7], v[232:235], v[8:11], v[80:83]
	v_mfma_f32_16x16x32_bf16 v[4:7], v[236:239], v[12:15], v[4:7]
	v_mfma_f32_16x16x32_bf16 v[8:11], v[188:191], v[44:47], v[160:163]
	v_mfma_f32_16x16x32_bf16 v[12:15], v[188:191], v[206:209], v[164:167]
	v_mfma_f32_16x16x32_bf16 v[40:43], v[228:231], v[202:205], v[8:11]
	v_mfma_f32_16x16x32_bf16 v[8:11], v[232:235], v[44:47], v[72:75]
	v_mfma_f32_16x16x32_bf16 v[44:47], v[228:231], v[222:225], v[12:15]
	v_mfma_f32_16x16x32_bf16 v[12:15], v[232:235], v[206:209], v[64:67]
	v_mfma_f32_16x16x32_bf16 v[8:11], v[236:239], v[202:205], v[8:11]
	v_mfma_f32_16x16x32_bf16 v[12:15], v[236:239], v[222:225], v[12:15]
	s_setprio 0
	s_barrier
	s_barrier
	s_waitcnt lgkmcnt(0)
	s_setprio 1
	s_waitcnt lgkmcnt(0)
	s_setprio 0
	s_setprio 1
	s_setprio 0
	s_movk_i32 s4, 0x100
	v_cmp_gt_u32_e32 vcc, s4, v128
	s_barrier
	s_and_saveexec_b64 s[4:5], vcc
	s_cbranch_execz .Lh2_epi
	s_barrier

.LBB0_138:
	ds_read_b128 v[140:143], v138
	ds_read_b128 v[144:147], v138 offset:1024
	ds_read_b128 v[148:151], v138 offset:2048
	ds_read_b128 v[152:155], v138 offset:3072
	s_add_u32 s8, s6, s65
	v_mov_b32_e32 v196, v129
	v_mov_b32_e32 v188, v130
	s_addc_u32 s9, s7, s66
	ds_read_b128 v[156:159], v134
	ds_read_b128 v[160:163], v134 offset:1024
	ds_read_b128 v[164:167], v133
	ds_read_b128 v[168:171], v133 offset:1024
	ds_read_b128 v[172:175], v132
	ds_read_b128 v[176:179], v132 offset:1024
	ds_read_b128 v[180:183], v131
	ds_read_b128 v[184:187], v131 offset:1024
	v_mov_b32_e32 v189, v197
	s_mov_b32 m0, s76
	s_add_u32 s98, s8, s44
	s_addc_u32 s99, s9, s45
	global_load_lds_dwordx4 v129, s[98:99]
	s_mov_b32 m0, s75
	s_nop 0
	global_load_lds_dwordx4 v130, s[98:99]
	s_waitcnt lgkmcnt(8)
	s_barrier
	s_waitcnt lgkmcnt(0)
	s_setprio 1
	s_waitcnt lgkmcnt(0)
	v_mfma_f32_16x16x32_bf16 v[124:127], v[140:143], v[156:159], v[124:127]
	v_mfma_f32_16x16x32_bf16 v[120:123], v[148:151], v[156:159], v[120:123]
	v_mfma_f32_16x16x32_bf16 v[116:119], v[140:143], v[164:167], v[116:119]
	v_mfma_f32_16x16x32_bf16 v[112:115], v[148:151], v[164:167], v[112:115]
	v_mfma_f32_16x16x32_bf16 v[108:111], v[140:143], v[172:175], v[108:111]
	v_mfma_f32_16x16x32_bf16 v[104:107], v[148:151], v[172:175], v[104:107]
	v_mfma_f32_16x16x32_bf16 v[100:103], v[140:143], v[180:183], v[100:103]
	v_mfma_f32_16x16x32_bf16 v[96:99], v[148:151], v[180:183], v[96:99]
	v_mfma_f32_16x16x32_bf16 v[124:127], v[144:147], v[160:163], v[124:127]
	v_mfma_f32_16x16x32_bf16 v[120:123], v[152:155], v[160:163], v[120:123]
	v_mfma_f32_16x16x32_bf16 v[116:119], v[144:147], v[168:171], v[116:119]
	v_mfma_f32_16x16x32_bf16 v[112:115], v[152:155], v[168:171], v[112:115]
	v_mfma_f32_16x16x32_bf16 v[108:111], v[144:147], v[176:179], v[108:111]
	v_mfma_f32_16x16x32_bf16 v[104:107], v[152:155], v[176:179], v[104:107]
	v_mfma_f32_16x16x32_bf16 v[100:103], v[144:147], v[184:187], v[100:103]
	v_mfma_f32_16x16x32_bf16 v[96:99], v[152:155], v[184:187], v[96:99]
	s_setprio 0
	s_barrier
	s_add_u32 s10, s6, s36
	v_mov_b32_e32 v196, v129
	v_mov_b32_e32 v210, v130
	s_addc_u32 s11, s7, s37
	ds_read_b128 v[188:191], v137
	ds_read_b128 v[192:195], v137 offset:1024
	ds_read_b128 v[202:205], v137 offset:2048
	ds_read_b128 v[206:209], v137 offset:3072
	v_mov_b32_e32 v211, v197
	s_mov_b32 m0, s63
	s_add_u32 s98, s10, s46
	s_addc_u32 s99, s11, s47
	global_load_lds_dwordx4 v129, s[98:99]
	s_mov_b32 m0, s64
	s_nop 0
	global_load_lds_dwordx4 v130, s[98:99]
	s_barrier
	s_waitcnt lgkmcnt(0)
	s_setprio 1
	s_waitcnt lgkmcnt(0)
	v_mfma_f32_16x16x32_bf16 v[92:95], v[188:191], v[156:159], v[92:95]
	v_mfma_f32_16x16x32_bf16 v[88:91], v[202:205], v[156:159], v[88:91]
	v_mfma_f32_16x16x32_bf16 v[84:87], v[188:191], v[164:167], v[84:87]
	v_mfma_f32_16x16x32_bf16 v[80:83], v[202:205], v[164:167], v[80:83]
	v_mfma_f32_16x16x32_bf16 v[76:79], v[188:191], v[172:175], v[76:79]
	v_mfma_f32_16x16x32_bf16 v[72:75], v[202:205], v[172:175], v[72:75]
	v_mfma_f32_16x16x32_bf16 v[68:71], v[188:191], v[180:183], v[68:71]
	v_mfma_f32_16x16x32_bf16 v[64:67], v[202:205], v[180:183], v[64:67]
	v_mfma_f32_16x16x32_bf16 v[92:95], v[192:195], v[160:163], v[92:95]
	v_mfma_f32_16x16x32_bf16 v[88:91], v[206:209], v[160:163], v[88:91]
	v_mfma_f32_16x16x32_bf16 v[84:87], v[192:195], v[168:171], v[84:87]
	v_mfma_f32_16x16x32_bf16 v[80:83], v[206:209], v[168:171], v[80:83]
	v_mfma_f32_16x16x32_bf16 v[76:79], v[192:195], v[176:179], v[76:79]
	v_mfma_f32_16x16x32_bf16 v[72:75], v[206:209], v[176:179], v[72:75]
	v_mfma_f32_16x16x32_bf16 v[68:71], v[192:195], v[184:187], v[68:71]
	v_mfma_f32_16x16x32_bf16 v[64:67], v[206:209], v[184:187], v[64:67]
	s_setprio 0
	v_mov_b32_e32 v196, v129
	v_mov_b32_e32 v210, v130
	s_barrier
	ds_read_b128 v[156:159], v134 offset:16384
	ds_read_b128 v[160:163], v134 offset:17408
	ds_read_b128 v[164:167], v133 offset:16384
	ds_read_b128 v[168:171], v133 offset:17408
	ds_read_b128 v[172:175], v132 offset:16384
	ds_read_b128 v[176:179], v132 offset:17408
	ds_read_b128 v[180:183], v131 offset:16384
	ds_read_b128 v[184:187], v131 offset:17408
	v_mov_b32_e32 v211, v197
	s_mov_b32 m0, s62
	s_add_u32 s98, s8, s48
	s_addc_u32 s99, s9, s49
	global_load_lds_dwordx4 v129, s[98:99]
	s_mov_b32 m0, s67
	s_nop 0
	global_load_lds_dwordx4 v130, s[98:99]
	s_barrier
	s_waitcnt lgkmcnt(0)
	s_setprio 1
	s_waitcnt lgkmcnt(0)
	v_mfma_f32_16x16x32_bf16 v[60:63], v[140:143], v[156:159], v[60:63]
	v_mfma_f32_16x16x32_bf16 v[56:59], v[148:151], v[156:159], v[56:59]
	v_mfma_f32_16x16x32_bf16 v[52:55], v[140:143], v[164:167], v[52:55]
	v_mfma_f32_16x16x32_bf16 v[48:51], v[148:151], v[164:167], v[48:51]
	v_mfma_f32_16x16x32_bf16 v[44:47], v[140:143], v[172:175], v[44:47]
	v_mfma_f32_16x16x32_bf16 v[40:43], v[148:151], v[172:175], v[40:43]
	v_mfma_f32_16x16x32_bf16 v[36:39], v[140:143], v[180:183], v[36:39]
	v_mfma_f32_16x16x32_bf16 v[32:35], v[148:151], v[180:183], v[32:35]
	v_mfma_f32_16x16x32_bf16 v[60:63], v[144:147], v[160:163], v[60:63]
	v_mfma_f32_16x16x32_bf16 v[56:59], v[152:155], v[160:163], v[56:59]
	v_mfma_f32_16x16x32_bf16 v[52:55], v[144:147], v[168:171], v[52:55]
	v_mfma_f32_16x16x32_bf16 v[48:51], v[152:155], v[168:171], v[48:51]
	v_mfma_f32_16x16x32_bf16 v[44:47], v[144:147], v[176:179], v[44:47]
	v_mfma_f32_16x16x32_bf16 v[40:43], v[152:155], v[176:179], v[40:43]
	v_mfma_f32_16x16x32_bf16 v[36:39], v[144:147], v[184:187], v[36:39]
	v_mfma_f32_16x16x32_bf16 v[32:35], v[152:155], v[184:187], v[32:35]
	s_setprio 0
	s_barrier
	v_mov_b32_e32 v196, v129
	v_mov_b32_e32 v140, v130
	v_mov_b32_e32 v141, v197
	s_mov_b32 m0, s68
	s_add_u32 s98, s10, s50
	s_addc_u32 s99, s11, s51
	global_load_lds_dwordx4 v129, s[98:99]
	s_mov_b32 m0, s69
	s_nop 0
	global_load_lds_dwordx4 v130, s[98:99]
	s_waitcnt vmcnt(6)
	s_barrier
	s_setprio 1
	v_mfma_f32_16x16x32_bf16 v[28:31], v[188:191], v[156:159], v[28:31]
	v_mfma_f32_16x16x32_bf16 v[24:27], v[202:205], v[156:159], v[24:27]
	v_mfma_f32_16x16x32_bf16 v[20:23], v[188:191], v[164:167], v[20:23]
	v_mfma_f32_16x16x32_bf16 v[16:19], v[202:205], v[164:167], v[16:19]
	v_mfma_f32_16x16x32_bf16 v[12:15], v[188:191], v[172:175], v[12:15]
	v_mfma_f32_16x16x32_bf16 v[8:11], v[202:205], v[172:175], v[8:11]
	v_mfma_f32_16x16x32_bf16 v[4:7], v[188:191], v[180:183], v[4:7]
	v_mfma_f32_16x16x32_bf16 v[0:3], v[202:205], v[180:183], v[0:3]
	v_mfma_f32_16x16x32_bf16 v[28:31], v[192:195], v[160:163], v[28:31]
	v_mfma_f32_16x16x32_bf16 v[24:27], v[206:209], v[160:163], v[24:27]
	v_mfma_f32_16x16x32_bf16 v[20:23], v[192:195], v[168:171], v[20:23]
	v_mfma_f32_16x16x32_bf16 v[16:19], v[206:209], v[168:171], v[16:19]
	v_mfma_f32_16x16x32_bf16 v[12:15], v[192:195], v[176:179], v[12:15]
	v_mfma_f32_16x16x32_bf16 v[8:11], v[206:209], v[176:179], v[8:11]
	v_mfma_f32_16x16x32_bf16 v[4:7], v[192:195], v[184:187], v[4:7]
	v_mfma_f32_16x16x32_bf16 v[0:3], v[206:209], v[184:187], v[0:3]
	s_setprio 0
	s_barrier
	ds_read_b128 v[140:143], v136
	ds_read_b128 v[144:147], v136 offset:1024
	ds_read_b128 v[148:151], v136 offset:2048
	ds_read_b128 v[152:155], v136 offset:3072
	v_mov_b32_e32 v196, v129
	v_mov_b32_e32 v188, v130
	ds_read_b128 v[156:159], v134 offset:32768
	ds_read_b128 v[160:163], v134 offset:33792
	ds_read_b128 v[164:167], v133 offset:32768
	ds_read_b128 v[168:171], v133 offset:33792
	ds_read_b128 v[172:175], v132 offset:32768
	ds_read_b128 v[176:179], v132 offset:33792
	ds_read_b128 v[180:183], v131 offset:32768
	ds_read_b128 v[184:187], v131 offset:33792
	v_mov_b32_e32 v189, v197
	s_mov_b32 m0, s70
	s_add_u32 s98, s8, s90
	s_addc_u32 s99, s9, s91
	global_load_lds_dwordx4 v129, s[98:99]
	s_mov_b32 m0, s71
	s_nop 0
	global_load_lds_dwordx4 v130, s[98:99]
	s_waitcnt lgkmcnt(8)
	s_barrier
	s_waitcnt lgkmcnt(0)
	s_setprio 1
	s_waitcnt lgkmcnt(0)
	v_mfma_f32_16x16x32_bf16 v[124:127], v[140:143], v[156:159], v[124:127]
	v_mfma_f32_16x16x32_bf16 v[120:123], v[148:151], v[156:159], v[120:123]
	v_mfma_f32_16x16x32_bf16 v[116:119], v[140:143], v[164:167], v[116:119]
	v_mfma_f32_16x16x32_bf16 v[112:115], v[148:151], v[164:167], v[112:115]
	v_mfma_f32_16x16x32_bf16 v[108:111], v[140:143], v[172:175], v[108:111]
	v_mfma_f32_16x16x32_bf16 v[104:107], v[148:151], v[172:175], v[104:107]
	v_mfma_f32_16x16x32_bf16 v[100:103], v[140:143], v[180:183], v[100:103]
	v_mfma_f32_16x16x32_bf16 v[96:99], v[148:151], v[180:183], v[96:99]
	v_mfma_f32_16x16x32_bf16 v[124:127], v[144:147], v[160:163], v[124:127]
	v_mfma_f32_16x16x32_bf16 v[120:123], v[152:155], v[160:163], v[120:123]
	v_mfma_f32_16x16x32_bf16 v[116:119], v[144:147], v[168:171], v[116:119]
	v_mfma_f32_16x16x32_bf16 v[112:115], v[152:155], v[168:171], v[112:115]
	v_mfma_f32_16x16x32_bf16 v[108:111], v[144:147], v[176:179], v[108:111]
	v_mfma_f32_16x16x32_bf16 v[104:107], v[152:155], v[176:179], v[104:107]
	v_mfma_f32_16x16x32_bf16 v[100:103], v[144:147], v[184:187], v[100:103]
	v_mfma_f32_16x16x32_bf16 v[96:99], v[152:155], v[184:187], v[96:99]
	s_setprio 0
	s_barrier
	v_mov_b32_e32 v196, v129
	v_mov_b32_e32 v210, v130
	ds_read_b128 v[188:191], v135
	ds_read_b128 v[192:195], v135 offset:1024
	ds_read_b128 v[202:205], v135 offset:2048
	ds_read_b128 v[206:209], v135 offset:3072
	v_mov_b32_e32 v211, v197
	s_mov_b32 m0, s28
	s_add_u32 s98, s10, s92
	s_addc_u32 s99, s11, s93
	global_load_lds_dwordx4 v129, s[98:99]
	s_mov_b32 m0, s29
	s_nop 0
	global_load_lds_dwordx4 v130, s[98:99]
	s_barrier
	s_waitcnt lgkmcnt(0)
	s_setprio 1
	s_waitcnt lgkmcnt(0)
	v_mfma_f32_16x16x32_bf16 v[92:95], v[188:191], v[156:159], v[92:95]
	v_mfma_f32_16x16x32_bf16 v[88:91], v[202:205], v[156:159], v[88:91]
	v_mfma_f32_16x16x32_bf16 v[84:87], v[188:191], v[164:167], v[84:87]
	v_mfma_f32_16x16x32_bf16 v[80:83], v[202:205], v[164:167], v[80:83]
	v_mfma_f32_16x16x32_bf16 v[76:79], v[188:191], v[172:175], v[76:79]
	v_mfma_f32_16x16x32_bf16 v[72:75], v[202:205], v[172:175], v[72:75]
	v_mfma_f32_16x16x32_bf16 v[68:71], v[188:191], v[180:183], v[68:71]
	v_mfma_f32_16x16x32_bf16 v[64:67], v[202:205], v[180:183], v[64:67]
	v_mfma_f32_16x16x32_bf16 v[92:95], v[192:195], v[160:163], v[92:95]
	v_mfma_f32_16x16x32_bf16 v[88:91], v[206:209], v[160:163], v[88:91]
	v_mfma_f32_16x16x32_bf16 v[84:87], v[192:195], v[168:171], v[84:87]
	v_mfma_f32_16x16x32_bf16 v[80:83], v[206:209], v[168:171], v[80:83]
	v_mfma_f32_16x16x32_bf16 v[76:79], v[192:195], v[176:179], v[76:79]
	v_mfma_f32_16x16x32_bf16 v[72:75], v[206:209], v[176:179], v[72:75]
	v_mfma_f32_16x16x32_bf16 v[68:71], v[192:195], v[184:187], v[68:71]
	v_mfma_f32_16x16x32_bf16 v[64:67], v[206:209], v[184:187], v[64:67]
	s_setprio 0
	v_mov_b32_e32 v196, v129
	v_mov_b32_e32 v210, v130
	s_barrier
	ds_read_b128 v[156:159], v134 offset:49152
	ds_read_b128 v[160:163], v134 offset:50176
	ds_read_b128 v[164:167], v133 offset:49152
	ds_read_b128 v[168:171], v133 offset:50176
	ds_read_b128 v[172:175], v132 offset:49152
	ds_read_b128 v[176:179], v132 offset:50176
	ds_read_b128 v[180:183], v131 offset:49152
	ds_read_b128 v[184:187], v131 offset:50176
	v_mov_b32_e32 v211, v197
	s_mov_b32 m0, s72
	s_add_u32 s98, s8, s96
	s_addc_u32 s99, s9, s97
	global_load_lds_dwordx4 v129, s[98:99]
	s_mov_b32 m0, s73
	s_nop 0
	global_load_lds_dwordx4 v130, s[98:99]
	s_barrier
	s_waitcnt lgkmcnt(0)
	s_setprio 1
	s_waitcnt lgkmcnt(0)
	v_mfma_f32_16x16x32_bf16 v[60:63], v[140:143], v[156:159], v[60:63]
	v_mfma_f32_16x16x32_bf16 v[56:59], v[148:151], v[156:159], v[56:59]
	v_mfma_f32_16x16x32_bf16 v[52:55], v[140:143], v[164:167], v[52:55]
	v_mfma_f32_16x16x32_bf16 v[48:51], v[148:151], v[164:167], v[48:51]
	v_mfma_f32_16x16x32_bf16 v[44:47], v[140:143], v[172:175], v[44:47]
	v_mfma_f32_16x16x32_bf16 v[40:43], v[148:151], v[172:175], v[40:43]
	v_mfma_f32_16x16x32_bf16 v[36:39], v[140:143], v[180:183], v[36:39]
	v_mfma_f32_16x16x32_bf16 v[32:35], v[148:151], v[180:183], v[32:35]
	v_mfma_f32_16x16x32_bf16 v[60:63], v[144:147], v[160:163], v[60:63]
	v_mfma_f32_16x16x32_bf16 v[56:59], v[152:155], v[160:163], v[56:59]
	v_mfma_f32_16x16x32_bf16 v[52:55], v[144:147], v[168:171], v[52:55]
	v_mfma_f32_16x16x32_bf16 v[48:51], v[152:155], v[168:171], v[48:51]
	v_mfma_f32_16x16x32_bf16 v[44:47], v[144:147], v[176:179], v[44:47]
	v_mfma_f32_16x16x32_bf16 v[40:43], v[152:155], v[176:179], v[40:43]
	v_mfma_f32_16x16x32_bf16 v[36:39], v[144:147], v[184:187], v[36:39]
	v_mfma_f32_16x16x32_bf16 v[32:35], v[152:155], v[184:187], v[32:35]
	s_setprio 0
	s_barrier
	v_mov_b32_e32 v196, v129
	v_mov_b32_e32 v140, v130
	v_mov_b32_e32 v141, v197
	s_mov_b32 m0, s33
	s_add_u32 s98, s10, vcc_lo
	s_addc_u32 s99, s11, vcc_hi
	global_load_lds_dwordx4 v129, s[98:99]
	s_mov_b32 m0, s74
	s_nop 0
	global_load_lds_dwordx4 v130, s[98:99]
	s_waitcnt vmcnt(6)
	s_barrier
	s_setprio 1
	v_mfma_f32_16x16x32_bf16 v[28:31], v[188:191], v[156:159], v[28:31]
	v_mfma_f32_16x16x32_bf16 v[24:27], v[202:205], v[156:159], v[24:27]
	v_mfma_f32_16x16x32_bf16 v[20:23], v[188:191], v[164:167], v[20:23]
	v_mfma_f32_16x16x32_bf16 v[16:19], v[202:205], v[164:167], v[16:19]
	v_mfma_f32_16x16x32_bf16 v[12:15], v[188:191], v[172:175], v[12:15]
	v_mfma_f32_16x16x32_bf16 v[8:11], v[202:205], v[172:175], v[8:11]
	v_mfma_f32_16x16x32_bf16 v[4:7], v[188:191], v[180:183], v[4:7]
	v_mfma_f32_16x16x32_bf16 v[0:3], v[202:205], v[180:183], v[0:3]
	v_mfma_f32_16x16x32_bf16 v[28:31], v[192:195], v[160:163], v[28:31]
	v_mfma_f32_16x16x32_bf16 v[24:27], v[206:209], v[160:163], v[24:27]
	v_mfma_f32_16x16x32_bf16 v[20:23], v[192:195], v[168:171], v[20:23]
	v_mfma_f32_16x16x32_bf16 v[16:19], v[206:209], v[168:171], v[16:19]
	v_mfma_f32_16x16x32_bf16 v[12:15], v[192:195], v[176:179], v[12:15]
	v_mfma_f32_16x16x32_bf16 v[8:11], v[206:209], v[176:179], v[8:11]
	v_mfma_f32_16x16x32_bf16 v[4:7], v[192:195], v[184:187], v[4:7]
	v_mfma_f32_16x16x32_bf16 v[0:3], v[206:209], v[184:187], v[0:3]
	s_setprio 0
	s_add_i32 s38, s38, 2
	s_add_u32 s6, s6, 0x100
	s_addc_u32 s7, s7, 0
	s_cmpk_lt_u32 s38, 0x54
	s_barrier
	s_cbranch_scc1 .LBB0_138
	s_add_u32 s4, s4, 0x2b80
	s_addc_u32 s5, s5, 0
	s_mov_b32 m0, s76
	ds_read_b128 v[140:143], v138
	ds_read_b128 v[144:147], v138 offset:1024
	ds_read_b128 v[148:151], v138 offset:2048
	ds_read_b128 v[152:155], v138 offset:3072
	ds_read_b128 v[156:159], v134
	ds_read_b128 v[160:163], v134 offset:1024
	ds_read_b128 v[164:167], v133
	ds_read_b128 v[168:171], v133 offset:1024
	ds_read_b128 v[172:175], v132
	ds_read_b128 v[176:179], v132 offset:1024
	ds_read_b128 v[180:183], v131
	ds_read_b128 v[184:187], v131 offset:1024
	s_nop 0
	global_load_lds_dwordx4 v129, s[4:5]
	s_mov_b32 m0, s75
	s_nop 0
	global_load_lds_dwordx4 v130, s[4:5]
	s_barrier
	s_waitcnt lgkmcnt(0)
	s_setprio 1
	s_waitcnt lgkmcnt(0)
	v_mfma_f32_16x16x32_bf16 v[124:127], v[140:143], v[156:159], v[124:127]
	v_mfma_f32_16x16x32_bf16 v[120:123], v[148:151], v[156:159], v[120:123]
	v_mfma_f32_16x16x32_bf16 v[116:119], v[140:143], v[164:167], v[116:119]
	v_mfma_f32_16x16x32_bf16 v[112:115], v[148:151], v[164:167], v[112:115]
	v_mfma_f32_16x16x32_bf16 v[108:111], v[140:143], v[172:175], v[108:111]
	v_mfma_f32_16x16x32_bf16 v[100:103], v[140:143], v[180:183], v[100:103]
	v_mfma_f32_16x16x32_bf16 v[96:99], v[148:151], v[180:183], v[96:99]
	v_mfma_f32_16x16x32_bf16 v[124:127], v[144:147], v[160:163], v[124:127]
	v_mfma_f32_16x16x32_bf16 v[120:123], v[152:155], v[160:163], v[120:123]
	v_mfma_f32_16x16x32_bf16 v[116:119], v[144:147], v[168:171], v[116:119]
	v_mfma_f32_16x16x32_bf16 v[112:115], v[152:155], v[168:171], v[112:115]
	v_mfma_f32_16x16x32_bf16 v[108:111], v[144:147], v[176:179], v[108:111]
	v_mfma_f32_16x16x32_bf16 v[104:107], v[148:151], v[172:175], v[104:107]
	v_mfma_f32_16x16x32_bf16 v[100:103], v[144:147], v[184:187], v[100:103]
	v_mfma_f32_16x16x32_bf16 v[96:99], v[152:155], v[184:187], v[96:99]
	v_mfma_f32_16x16x32_bf16 v[188:191], v[152:155], v[176:179], v[104:107]
	s_setprio 0
	s_barrier
	s_nop 2
	ds_read_b128 v[104:107], v137
	ds_read_b128 v[192:195], v137 offset:1024
	ds_read_b128 v[202:205], v137 offset:2048
	ds_read_b128 v[206:209], v137 offset:3072
	s_barrier
	s_waitcnt lgkmcnt(0)
	s_setprio 1
	s_waitcnt lgkmcnt(0)
	v_mfma_f32_16x16x32_bf16 v[92:95], v[104:107], v[156:159], v[92:95]
	v_mfma_f32_16x16x32_bf16 v[88:91], v[202:205], v[156:159], v[88:91]
	v_mfma_f32_16x16x32_bf16 v[80:83], v[202:205], v[164:167], v[80:83]
	v_mfma_f32_16x16x32_bf16 v[72:75], v[202:205], v[172:175], v[72:75]
	v_mfma_f32_16x16x32_bf16 v[64:67], v[202:205], v[180:183], v[64:67]
	v_mfma_f32_16x16x32_bf16 v[92:95], v[192:195], v[160:163], v[92:95]
	v_mfma_f32_16x16x32_bf16 v[88:91], v[206:209], v[160:163], v[88:91]
	v_mfma_f32_16x16x32_bf16 v[84:87], v[104:107], v[164:167], v[84:87]
	v_mfma_f32_16x16x32_bf16 v[80:83], v[206:209], v[168:171], v[80:83]
	v_mfma_f32_16x16x32_bf16 v[76:79], v[104:107], v[172:175], v[76:79]
	v_mfma_f32_16x16x32_bf16 v[72:75], v[206:209], v[176:179], v[72:75]
	v_mfma_f32_16x16x32_bf16 v[68:71], v[104:107], v[180:183], v[68:71]
	v_mfma_f32_16x16x32_bf16 v[64:67], v[206:209], v[184:187], v[64:67]
	v_mfma_f32_16x16x32_bf16 v[156:159], v[192:195], v[168:171], v[84:87]
	v_mfma_f32_16x16x32_bf16 v[160:163], v[192:195], v[176:179], v[76:79]
	v_mfma_f32_16x16x32_bf16 v[164:167], v[192:195], v[184:187], v[68:71]
	s_setprio 0
	s_barrier
	s_nop 1
	ds_read_b128 v[68:71], v134 offset:16384
	ds_read_b128 v[76:79], v134 offset:17408
	ds_read_b128 v[84:87], v133 offset:16384
	ds_read_b128 v[168:171], v133 offset:17408
	ds_read_b128 v[172:175], v132 offset:16384
	ds_read_b128 v[176:179], v132 offset:17408
	ds_read_b128 v[180:183], v131 offset:16384
	ds_read_b128 v[184:187], v131 offset:17408
	s_waitcnt vmcnt(4)
	s_barrier
	s_waitcnt lgkmcnt(0)
	s_setprio 1
	s_waitcnt lgkmcnt(0)
	v_mfma_f32_16x16x32_bf16 v[60:63], v[140:143], v[68:71], v[60:63]
	v_mfma_f32_16x16x32_bf16 v[56:59], v[148:151], v[68:71], v[56:59]
	v_mfma_f32_16x16x32_bf16 v[48:51], v[148:151], v[84:87], v[48:51]
	v_mfma_f32_16x16x32_bf16 v[32:35], v[148:151], v[180:183], v[32:35]
	v_mfma_f32_16x16x32_bf16 v[60:63], v[144:147], v[76:79], v[60:63]
	v_mfma_f32_16x16x32_bf16 v[56:59], v[152:155], v[76:79], v[56:59]
	v_mfma_f32_16x16x32_bf16 v[52:55], v[140:143], v[84:87], v[52:55]
	v_mfma_f32_16x16x32_bf16 v[48:51], v[152:155], v[168:171], v[48:51]
	v_mfma_f32_16x16x32_bf16 v[44:47], v[140:143], v[172:175], v[44:47]
	v_mfma_f32_16x16x32_bf16 v[40:43], v[148:151], v[172:175], v[40:43]
	v_mfma_f32_16x16x32_bf16 v[36:39], v[140:143], v[180:183], v[36:39]
	v_mfma_f32_16x16x32_bf16 v[32:35], v[152:155], v[184:187], v[32:35]
	v_mfma_f32_16x16x32_bf16 v[210:213], v[144:147], v[168:171], v[52:55]
	v_mfma_f32_16x16x32_bf16 v[214:217], v[144:147], v[176:179], v[44:47]
	v_mfma_f32_16x16x32_bf16 v[218:221], v[152:155], v[176:179], v[40:43]
	v_mfma_f32_16x16x32_bf16 v[138:141], v[144:147], v[184:187], v[36:39]
	s_setprio 0
	s_setprio 1
	v_mfma_f32_16x16x32_bf16 v[24:27], v[202:205], v[68:71], v[24:27]
	v_mfma_f32_16x16x32_bf16 v[20:23], v[104:107], v[84:87], v[20:23]
	v_mfma_f32_16x16x32_bf16 v[28:31], v[104:107], v[68:71], v[28:31]
	v_mfma_f32_16x16x32_bf16 v[24:27], v[206:209], v[76:79], v[24:27]
	v_mfma_f32_16x16x32_bf16 v[20:23], v[192:195], v[168:171], v[20:23]
	v_mfma_f32_16x16x32_bf16 v[16:19], v[202:205], v[84:87], v[16:19]
	v_mfma_f32_16x16x32_bf16 v[12:15], v[104:107], v[172:175], v[12:15]
	v_mfma_f32_16x16x32_bf16 v[8:11], v[202:205], v[172:175], v[8:11]
	v_mfma_f32_16x16x32_bf16 v[4:7], v[104:107], v[180:183], v[4:7]
	v_mfma_f32_16x16x32_bf16 v[0:3], v[202:205], v[180:183], v[0:3]
	v_mfma_f32_16x16x32_bf16 v[142:145], v[192:195], v[76:79], v[28:31]
	v_mfma_f32_16x16x32_bf16 v[146:149], v[206:209], v[168:171], v[16:19]
	v_mfma_f32_16x16x32_bf16 v[150:153], v[192:195], v[176:179], v[12:15]
	v_mfma_f32_16x16x32_bf16 v[168:171], v[206:209], v[176:179], v[8:11]
	v_mfma_f32_16x16x32_bf16 v[172:175], v[192:195], v[184:187], v[4:7]
	v_mfma_f32_16x16x32_bf16 v[176:179], v[206:209], v[184:187], v[0:3]
	s_setprio 0
	s_barrier
	ds_read_b128 v[16:19], v136
	ds_read_b128 v[180:183], v136 offset:1024
	ds_read_b128 v[184:187], v136 offset:2048
	ds_read_b128 v[192:195], v136 offset:3072
	ds_read_b128 v[0:3], v134 offset:32768
	ds_read_b128 v[4:7], v134 offset:33792
	ds_read_b128 v[8:11], v133 offset:32768
	ds_read_b128 v[12:15], v133 offset:33792
	ds_read_b128 v[44:47], v132 offset:32768
	ds_read_b128 v[202:205], v132 offset:33792
	ds_read_b128 v[206:209], v131 offset:32768
	ds_read_b128 v[222:225], v131 offset:33792
	s_waitcnt vmcnt(2)
	s_barrier
	s_waitcnt lgkmcnt(0)
	s_setprio 1
	s_waitcnt lgkmcnt(0)
	v_mfma_f32_16x16x32_bf16 v[28:31], v[16:19], v[0:3], v[124:127]
	v_mfma_f32_16x16x32_bf16 v[52:55], v[180:183], v[4:7], v[28:31]
	v_mfma_f32_16x16x32_bf16 v[28:31], v[184:187], v[0:3], v[120:123]
	v_mfma_f32_16x16x32_bf16 v[104:107], v[192:195], v[4:7], v[28:31]
	v_mfma_f32_16x16x32_bf16 v[28:31], v[16:19], v[8:11], v[116:119]
	v_mfma_f32_16x16x32_bf16 v[68:71], v[180:183], v[12:15], v[28:31]
	v_mfma_f32_16x16x32_bf16 v[28:31], v[184:187], v[8:11], v[112:115]
	v_mfma_f32_16x16x32_bf16 v[116:119], v[192:195], v[12:15], v[28:31]
	v_mfma_f32_16x16x32_bf16 v[28:31], v[16:19], v[44:47], v[108:111]
	v_mfma_f32_16x16x32_bf16 v[76:79], v[180:183], v[202:205], v[28:31]
	v_mfma_f32_16x16x32_bf16 v[28:31], v[184:187], v[44:47], v[188:191]
	v_mfma_f32_16x16x32_bf16 v[108:111], v[192:195], v[202:205], v[28:31]
	v_mfma_f32_16x16x32_bf16 v[28:31], v[16:19], v[206:209], v[100:103]
	v_mfma_f32_16x16x32_bf16 v[84:87], v[180:183], v[222:225], v[28:31]
	v_mfma_f32_16x16x32_bf16 v[28:31], v[184:187], v[206:209], v[96:99]
	v_mfma_f32_16x16x32_bf16 v[96:99], v[192:195], v[222:225], v[28:31]
	s_setprio 0
	s_barrier
	ds_read_b128 v[188:191], v135
	ds_read_b128 v[228:231], v135 offset:1024
	ds_read_b128 v[232:235], v135 offset:2048
	ds_read_b128 v[236:239], v135 offset:3072
	s_waitcnt vmcnt(0)
	s_barrier
	s_waitcnt lgkmcnt(0)
	s_setprio 1
	s_waitcnt lgkmcnt(0)
	v_mfma_f32_16x16x32_bf16 v[28:31], v[188:191], v[0:3], v[92:95]
	v_mfma_f32_16x16x32_bf16 v[0:3], v[232:235], v[0:3], v[88:91]
	v_mfma_f32_16x16x32_bf16 v[28:31], v[228:231], v[4:7], v[28:31]
	v_mfma_f32_16x16x32_bf16 v[0:3], v[236:239], v[4:7], v[0:3]
	v_mfma_f32_16x16x32_bf16 v[4:7], v[188:191], v[8:11], v[156:159]
	v_mfma_f32_16x16x32_bf16 v[36:39], v[228:231], v[12:15], v[4:7]
	v_mfma_f32_16x16x32_bf16 v[4:7], v[232:235], v[8:11], v[80:83]
	v_mfma_f32_16x16x32_bf16 v[4:7], v[236:239], v[12:15], v[4:7]
	v_mfma_f32_16x16x32_bf16 v[8:11], v[188:191], v[44:47], v[160:163]
	v_mfma_f32_16x16x32_bf16 v[12:15], v[188:191], v[206:209], v[164:167]
	v_mfma_f32_16x16x32_bf16 v[40:43], v[228:231], v[202:205], v[8:11]
	v_mfma_f32_16x16x32_bf16 v[8:11], v[232:235], v[44:47], v[72:75]
	v_mfma_f32_16x16x32_bf16 v[44:47], v[228:231], v[222:225], v[12:15]
	v_mfma_f32_16x16x32_bf16 v[12:15], v[232:235], v[206:209], v[64:67]
	v_mfma_f32_16x16x32_bf16 v[8:11], v[236:239], v[202:205], v[8:11]
	v_mfma_f32_16x16x32_bf16 v[12:15], v[236:239], v[222:225], v[12:15]
	s_setprio 0
	s_barrier
	ds_read_b128 v[64:67], v134 offset:49152
	ds_read_b128 v[134:137], v134 offset:50176
	ds_read_b128 v[154:157], v133 offset:49152
	ds_read_b128 v[158:161], v133 offset:50176
	ds_read_b128 v[162:165], v132 offset:49152
	ds_read_b128 v[202:205], v132 offset:50176
	ds_read_b128 v[206:209], v131 offset:49152
	ds_read_b128 v[130:133], v131 offset:50176
	s_barrier
	s_waitcnt lgkmcnt(0)
	s_setprio 1
	s_waitcnt lgkmcnt(0)
	v_mfma_f32_16x16x32_bf16 v[56:59], v[184:187], v[64:67], v[56:59]
	v_mfma_f32_16x16x32_bf16 v[48:51], v[184:187], v[154:157], v[48:51]
	v_mfma_f32_16x16x32_bf16 v[60:63], v[16:19], v[64:67], v[60:63]
	v_mfma_f32_16x16x32_bf16 v[92:95], v[192:195], v[134:137], v[56:59]
	v_mfma_f32_16x16x32_bf16 v[56:59], v[16:19], v[154:157], v[210:213]
	v_mfma_f32_16x16x32_bf16 v[88:91], v[192:195], v[158:161], v[48:51]
	v_mfma_f32_16x16x32_bf16 v[48:51], v[16:19], v[162:165], v[214:217]
	v_mfma_f32_16x16x32_bf16 v[16:19], v[16:19], v[206:209], v[138:141]
	v_mfma_f32_16x16x32_bf16 v[120:123], v[180:183], v[202:205], v[48:51]
	v_mfma_f32_16x16x32_bf16 v[48:51], v[184:187], v[162:165], v[218:221]
	v_mfma_f32_16x16x32_bf16 v[124:127], v[180:183], v[130:133], v[16:19]
	v_mfma_f32_16x16x32_bf16 v[16:19], v[184:187], v[206:209], v[32:35]
	v_mfma_f32_16x16x32_bf16 v[100:103], v[180:183], v[134:137], v[60:63]
	v_mfma_f32_16x16x32_bf16 v[112:115], v[180:183], v[158:161], v[56:59]
	v_mfma_f32_16x16x32_bf16 v[80:83], v[192:195], v[202:205], v[48:51]
	v_mfma_f32_16x16x32_bf16 v[72:75], v[192:195], v[130:133], v[16:19]
	s_setprio 0
	s_setprio 1
	v_mfma_f32_16x16x32_bf16 v[16:19], v[188:191], v[64:67], v[142:145]
	v_mfma_f32_16x16x32_bf16 v[48:51], v[228:231], v[134:137], v[16:19]
	v_mfma_f32_16x16x32_bf16 v[16:19], v[232:235], v[64:67], v[24:27]
	v_mfma_f32_16x16x32_bf16 v[20:23], v[188:191], v[154:157], v[20:23]
	v_mfma_f32_16x16x32_bf16 v[24:27], v[188:191], v[162:165], v[150:153]
	v_mfma_f32_16x16x32_bf16 v[32:35], v[188:191], v[206:209], v[172:175]
	v_mfma_f32_16x16x32_bf16 v[56:59], v[228:231], v[158:161], v[20:23]
	v_mfma_f32_16x16x32_bf16 v[20:23], v[232:235], v[154:157], v[146:149]
	v_mfma_f32_16x16x32_bf16 v[60:63], v[228:231], v[202:205], v[24:27]
	v_mfma_f32_16x16x32_bf16 v[24:27], v[232:235], v[162:165], v[168:171]
	v_mfma_f32_16x16x32_bf16 v[64:67], v[228:231], v[130:133], v[32:35]
	v_mfma_f32_16x16x32_bf16 v[32:35], v[232:235], v[206:209], v[176:179]
	v_mfma_f32_16x16x32_bf16 v[16:19], v[236:239], v[134:137], v[16:19]
	v_mfma_f32_16x16x32_bf16 v[20:23], v[236:239], v[158:161], v[20:23]
	v_mfma_f32_16x16x32_bf16 v[24:27], v[236:239], v[202:205], v[24:27]
	v_mfma_f32_16x16x32_bf16 v[32:35], v[236:239], v[130:133], v[32:35]
	s_setprio 0
	s_movk_i32 s4, 0x100
	v_cmp_gt_u32_e32 vcc, s4, v128
	s_barrier
	s_and_saveexec_b64 s[4:5], vcc
	s_cbranch_execz .LBB0_95
	s_barrier
	s_branch .LBB0_95

.Lhf_192:
	ds_read_b128 v[140:143], v129
	ds_read_b128 v[144:147], v129 offset:1024
	ds_read_b128 v[148:151], v129 offset:2048
	ds_read_b128 v[152:155], v129 offset:3072
	s_add_u32 s28, s56, s4
	v_mov_b32_e32 v196, v128
	v_mov_b32_e32 v188, v130
	s_addc_u32 s29, s57, s5
	ds_read_b128 v[156:159], v136
	ds_read_b128 v[160:163], v136 offset:1024
	ds_read_b128 v[164:167], v135
	ds_read_b128 v[168:171], v135 offset:1024
	ds_read_b128 v[172:175], v134
	ds_read_b128 v[176:179], v134 offset:1024
	ds_read_b128 v[180:183], v133
	ds_read_b128 v[184:187], v133 offset:1024
	s_add_i32 s40, s52, 0xc000
	v_mov_b32_e32 v189, v197
	s_mov_b32 m0, s40
	s_add_i32 s39, s52, 0xe000
	s_mov_b32 m0, s39
	s_nop 0
	s_waitcnt lgkmcnt(8)
	s_barrier
	s_waitcnt lgkmcnt(0)
	s_setprio 1
	s_waitcnt lgkmcnt(0)
	v_mfma_f32_16x16x32_bf16 v[124:127], v[140:143], v[156:159], v[124:127]
	v_mfma_f32_16x16x32_bf16 v[120:123], v[148:151], v[156:159], v[120:123]
	v_mfma_f32_16x16x32_bf16 v[116:119], v[140:143], v[164:167], v[116:119]
	v_mfma_f32_16x16x32_bf16 v[112:115], v[148:151], v[164:167], v[112:115]
	v_mfma_f32_16x16x32_bf16 v[108:111], v[140:143], v[172:175], v[108:111]
	v_mfma_f32_16x16x32_bf16 v[104:107], v[148:151], v[172:175], v[104:107]
	v_mfma_f32_16x16x32_bf16 v[100:103], v[140:143], v[180:183], v[100:103]
	v_mfma_f32_16x16x32_bf16 v[96:99], v[148:151], v[180:183], v[96:99]
	v_mfma_f32_16x16x32_bf16 v[124:127], v[144:147], v[160:163], v[124:127]
	v_mfma_f32_16x16x32_bf16 v[120:123], v[152:155], v[160:163], v[120:123]
	v_mfma_f32_16x16x32_bf16 v[116:119], v[144:147], v[168:171], v[116:119]
	v_mfma_f32_16x16x32_bf16 v[112:115], v[152:155], v[168:171], v[112:115]
	v_mfma_f32_16x16x32_bf16 v[108:111], v[144:147], v[176:179], v[108:111]
	v_mfma_f32_16x16x32_bf16 v[104:107], v[152:155], v[176:179], v[104:107]
	v_mfma_f32_16x16x32_bf16 v[100:103], v[144:147], v[184:187], v[100:103]
	v_mfma_f32_16x16x32_bf16 v[96:99], v[152:155], v[184:187], v[96:99]
	s_setprio 0
	s_barrier
	s_add_u32 s58, s56, s36
	v_mov_b32_e32 v196, v128
	v_mov_b32_e32 v210, v130
	s_addc_u32 s59, s57, s37
	ds_read_b128 v[188:191], v139
	ds_read_b128 v[192:195], v139 offset:1024
	ds_read_b128 v[202:205], v139 offset:2048
	ds_read_b128 v[206:209], v139 offset:3072
	v_mov_b32_e32 v211, v197
	s_add_i32 m0, s52, 0x10000
	s_add_u32 s98, s58, s46
	s_addc_u32 s99, s59, s47
	global_load_lds_dwordx4 v128, s[98:99]
	s_add_i32 m0, s52, 0x12000
	s_nop 0
	global_load_lds_dwordx4 v130, s[98:99]
	s_barrier
	s_waitcnt lgkmcnt(0)
	s_setprio 1
	s_waitcnt lgkmcnt(0)
	v_mfma_f32_16x16x32_bf16 v[92:95], v[188:191], v[156:159], v[92:95]
	v_mfma_f32_16x16x32_bf16 v[88:91], v[202:205], v[156:159], v[88:91]
	v_mfma_f32_16x16x32_bf16 v[84:87], v[188:191], v[164:167], v[84:87]
	v_mfma_f32_16x16x32_bf16 v[80:83], v[202:205], v[164:167], v[80:83]
	v_mfma_f32_16x16x32_bf16 v[76:79], v[188:191], v[172:175], v[76:79]
	v_mfma_f32_16x16x32_bf16 v[72:75], v[202:205], v[172:175], v[72:75]
	v_mfma_f32_16x16x32_bf16 v[68:71], v[188:191], v[180:183], v[68:71]
	v_mfma_f32_16x16x32_bf16 v[64:67], v[202:205], v[180:183], v[64:67]
	v_mfma_f32_16x16x32_bf16 v[92:95], v[192:195], v[160:163], v[92:95]
	v_mfma_f32_16x16x32_bf16 v[88:91], v[206:209], v[160:163], v[88:91]
	v_mfma_f32_16x16x32_bf16 v[84:87], v[192:195], v[168:171], v[84:87]
	v_mfma_f32_16x16x32_bf16 v[80:83], v[206:209], v[168:171], v[80:83]
	v_mfma_f32_16x16x32_bf16 v[76:79], v[192:195], v[176:179], v[76:79]
	v_mfma_f32_16x16x32_bf16 v[72:75], v[206:209], v[176:179], v[72:75]
	v_mfma_f32_16x16x32_bf16 v[68:71], v[192:195], v[184:187], v[68:71]
	v_mfma_f32_16x16x32_bf16 v[64:67], v[206:209], v[184:187], v[64:67]
	s_setprio 0
	v_mov_b32_e32 v196, v128
	v_mov_b32_e32 v210, v130
	s_barrier
	v_mov_b32_e32 v211, v197
	s_mov_b32 m0, s52
	s_add_u32 s98, s28, s48
	s_addc_u32 s99, s29, s49
	global_load_lds_dwordx4 v128, s[98:99]
	s_add_i32 m0, s52, 0x2000
	s_nop 0
	global_load_lds_dwordx4 v130, s[98:99]
	s_waitcnt vmcnt(4)
	s_barrier
	v_mov_b32_e32 v196, v128
	v_mov_b32_e32 v140, v130
	v_mov_b32_e32 v141, v197
	s_add_i32 m0, s52, 0x14000
	s_add_u32 s98, s58, s50
	s_addc_u32 s99, s59, s51
	global_load_lds_dwordx4 v128, s[98:99]
	s_add_i32 m0, s52, 0x16000
	s_nop 0
	global_load_lds_dwordx4 v130, s[98:99]
	s_barrier
	ds_read_b128 v[140:143], v138
	ds_read_b128 v[144:147], v138 offset:1024
	ds_read_b128 v[148:151], v138 offset:2048
	ds_read_b128 v[152:155], v138 offset:3072
	v_mov_b32_e32 v196, v128
	v_mov_b32_e32 v188, v130
	ds_read_b128 v[156:159], v136 offset:32768
	ds_read_b128 v[160:163], v136 offset:33792
	ds_read_b128 v[164:167], v135 offset:32768
	ds_read_b128 v[168:171], v135 offset:33792
	ds_read_b128 v[172:175], v134 offset:32768
	ds_read_b128 v[176:179], v134 offset:33792
	ds_read_b128 v[180:183], v133 offset:32768
	ds_read_b128 v[184:187], v133 offset:33792
	v_mov_b32_e32 v189, v197
	s_add_i32 m0, s52, 0x4000
	s_add_i32 m0, s52, 0x6000
	s_nop 0
	s_waitcnt lgkmcnt(8)
	s_barrier
	s_waitcnt lgkmcnt(0)
	s_setprio 1
	s_waitcnt lgkmcnt(0)
	v_mfma_f32_16x16x32_bf16 v[124:127], v[140:143], v[156:159], v[124:127]
	v_mfma_f32_16x16x32_bf16 v[120:123], v[148:151], v[156:159], v[120:123]
	v_mfma_f32_16x16x32_bf16 v[116:119], v[140:143], v[164:167], v[116:119]
	v_mfma_f32_16x16x32_bf16 v[112:115], v[148:151], v[164:167], v[112:115]
	v_mfma_f32_16x16x32_bf16 v[108:111], v[140:143], v[172:175], v[108:111]
	v_mfma_f32_16x16x32_bf16 v[104:107], v[148:151], v[172:175], v[104:107]
	v_mfma_f32_16x16x32_bf16 v[100:103], v[140:143], v[180:183], v[100:103]
	v_mfma_f32_16x16x32_bf16 v[96:99], v[148:151], v[180:183], v[96:99]
	v_mfma_f32_16x16x32_bf16 v[124:127], v[144:147], v[160:163], v[124:127]
	v_mfma_f32_16x16x32_bf16 v[120:123], v[152:155], v[160:163], v[120:123]
	v_mfma_f32_16x16x32_bf16 v[116:119], v[144:147], v[168:171], v[116:119]
	v_mfma_f32_16x16x32_bf16 v[112:115], v[152:155], v[168:171], v[112:115]
	v_mfma_f32_16x16x32_bf16 v[108:111], v[144:147], v[176:179], v[108:111]
	v_mfma_f32_16x16x32_bf16 v[104:107], v[152:155], v[176:179], v[104:107]
	v_mfma_f32_16x16x32_bf16 v[100:103], v[144:147], v[184:187], v[100:103]
	v_mfma_f32_16x16x32_bf16 v[96:99], v[152:155], v[184:187], v[96:99]
	s_setprio 0
	s_barrier
	v_mov_b32_e32 v196, v128
	v_mov_b32_e32 v210, v130
	ds_read_b128 v[188:191], v137
	ds_read_b128 v[192:195], v137 offset:1024
	ds_read_b128 v[202:205], v137 offset:2048
	ds_read_b128 v[206:209], v137 offset:3072
	v_mov_b32_e32 v211, v197
	s_mov_b32 m0, s7
	s_add_u32 s98, s58, s68
	s_addc_u32 s99, s59, s69
	global_load_lds_dwordx4 v128, s[98:99]
	s_mov_b32 m0, s53
	s_nop 0
	global_load_lds_dwordx4 v130, s[98:99]
	s_barrier
	s_waitcnt lgkmcnt(0)
	s_setprio 1
	s_waitcnt lgkmcnt(0)
	v_mfma_f32_16x16x32_bf16 v[92:95], v[188:191], v[156:159], v[92:95]
	v_mfma_f32_16x16x32_bf16 v[88:91], v[202:205], v[156:159], v[88:91]
	v_mfma_f32_16x16x32_bf16 v[84:87], v[188:191], v[164:167], v[84:87]
	v_mfma_f32_16x16x32_bf16 v[80:83], v[202:205], v[164:167], v[80:83]
	v_mfma_f32_16x16x32_bf16 v[76:79], v[188:191], v[172:175], v[76:79]
	v_mfma_f32_16x16x32_bf16 v[72:75], v[202:205], v[172:175], v[72:75]
	v_mfma_f32_16x16x32_bf16 v[68:71], v[188:191], v[180:183], v[68:71]
	v_mfma_f32_16x16x32_bf16 v[64:67], v[202:205], v[180:183], v[64:67]
	v_mfma_f32_16x16x32_bf16 v[92:95], v[192:195], v[160:163], v[92:95]
	v_mfma_f32_16x16x32_bf16 v[88:91], v[206:209], v[160:163], v[88:91]
	v_mfma_f32_16x16x32_bf16 v[84:87], v[192:195], v[168:171], v[84:87]
	v_mfma_f32_16x16x32_bf16 v[80:83], v[206:209], v[168:171], v[80:83]
	v_mfma_f32_16x16x32_bf16 v[76:79], v[192:195], v[176:179], v[76:79]
	v_mfma_f32_16x16x32_bf16 v[72:75], v[206:209], v[176:179], v[72:75]
	v_mfma_f32_16x16x32_bf16 v[68:71], v[192:195], v[184:187], v[68:71]
	v_mfma_f32_16x16x32_bf16 v[64:67], v[206:209], v[184:187], v[64:67]
	s_setprio 0
	v_mov_b32_e32 v196, v128
	v_mov_b32_e32 v210, v130
	s_barrier
	v_mov_b32_e32 v211, v197
	s_mov_b32 m0, s9
	s_add_u32 s98, s28, s70
	s_addc_u32 s99, s29, s71
	global_load_lds_dwordx4 v128, s[98:99]
	s_mov_b32 m0, s33
	s_nop 0
	global_load_lds_dwordx4 v130, s[98:99]
	s_waitcnt vmcnt(4)
	s_barrier
	v_mov_b32_e32 v196, v128
	v_mov_b32_e32 v140, v130
	v_mov_b32_e32 v141, v197
	s_mov_b32 m0, s65
	s_add_u32 s98, s58, s72
	s_addc_u32 s99, s59, s73
	global_load_lds_dwordx4 v128, s[98:99]
	s_mov_b32 m0, s66
	s_nop 0
	global_load_lds_dwordx4 v130, s[98:99]
	s_barrier
	s_add_i32 s38, s38, 2
	s_add_u32 s56, s56, 0x100
	s_addc_u32 s57, s57, 0
	s_cmp_lt_u32 s38, 28
	s_cbranch_scc1 .Lhf_192
	s_lshl_b64 s[4:5], s[10:11], 12
	v_readlane_b32 s10, v254, 12
	v_readlane_b32 s11, v254, 13
	s_add_u32 s4, s10, s4
	s_addc_u32 s5, s11, s5
	ds_read_b128 v[140:143], v129
	ds_read_b128 v[144:147], v129 offset:1024
	ds_read_b128 v[148:151], v129 offset:2048
	ds_read_b128 v[152:155], v129 offset:3072
	ds_read_b128 v[156:159], v136
	ds_read_b128 v[160:163], v136 offset:1024
	ds_read_b128 v[164:167], v135
	ds_read_b128 v[168:171], v135 offset:1024
	ds_read_b128 v[172:175], v134
	ds_read_b128 v[176:179], v134 offset:1024
	ds_read_b128 v[180:183], v133
	ds_read_b128 v[184:187], v133 offset:1024
	v_mov_b32_e32 v129, v197
	v_lshl_add_u64 v[128:129], s[4:5], 0, v[128:129]
	s_mov_b64 s[10:11], 0xf80
	s_mov_b32 m0, s40
	v_lshl_add_u64 v[128:129], v[128:129], 0, s[10:11]
	v_mov_b32_e32 v131, v197
	v_lshl_add_u64 v[128:129], s[4:5], 0, v[130:131]
	v_lshl_add_u64 v[128:129], v[128:129], 0, s[10:11]
	s_mov_b32 m0, s39
	s_nop 0
	s_barrier
	s_waitcnt lgkmcnt(0)
	s_setprio 1
	s_waitcnt lgkmcnt(0)
	v_mfma_f32_16x16x32_bf16 v[124:127], v[140:143], v[156:159], v[124:127]
	v_mfma_f32_16x16x32_bf16 v[116:119], v[140:143], v[164:167], v[116:119]
	v_mfma_f32_16x16x32_bf16 v[112:115], v[148:151], v[164:167], v[112:115]
	v_mfma_f32_16x16x32_bf16 v[108:111], v[140:143], v[172:175], v[108:111]
	v_mfma_f32_16x16x32_bf16 v[104:107], v[148:151], v[172:175], v[104:107]
	v_mfma_f32_16x16x32_bf16 v[100:103], v[140:143], v[180:183], v[100:103]
	v_mfma_f32_16x16x32_bf16 v[96:99], v[148:151], v[180:183], v[96:99]
	v_mfma_f32_16x16x32_bf16 v[124:127], v[144:147], v[160:163], v[124:127]
	v_mfma_f32_16x16x32_bf16 v[120:123], v[148:151], v[156:159], v[120:123]
	v_mfma_f32_16x16x32_bf16 v[116:119], v[144:147], v[168:171], v[116:119]
	v_mfma_f32_16x16x32_bf16 v[112:115], v[152:155], v[168:171], v[112:115]
	v_mfma_f32_16x16x32_bf16 v[108:111], v[144:147], v[176:179], v[108:111]
	v_mfma_f32_16x16x32_bf16 v[104:107], v[152:155], v[176:179], v[104:107]
	v_mfma_f32_16x16x32_bf16 v[100:103], v[144:147], v[184:187], v[100:103]
	v_mfma_f32_16x16x32_bf16 v[96:99], v[152:155], v[184:187], v[96:99]
	v_mfma_f32_16x16x32_bf16 v[128:131], v[152:155], v[160:163], v[120:123]
	s_setprio 0
	s_barrier
	s_nop 0
	ds_read_b128 v[120:123], v139
	ds_read_b128 v[188:191], v139 offset:1024
	ds_read_b128 v[192:195], v139 offset:2048
	ds_read_b128 v[202:205], v139 offset:3072
	s_barrier
	s_waitcnt lgkmcnt(0)
	s_setprio 1
	s_waitcnt lgkmcnt(0)
	v_mfma_f32_16x16x32_bf16 v[76:79], v[120:123], v[172:175], v[76:79]
	v_mfma_f32_16x16x32_bf16 v[68:71], v[120:123], v[180:183], v[68:71]
	v_mfma_f32_16x16x32_bf16 v[64:67], v[192:195], v[180:183], v[64:67]
	v_mfma_f32_16x16x32_bf16 v[92:95], v[120:123], v[156:159], v[92:95]
	v_mfma_f32_16x16x32_bf16 v[88:91], v[192:195], v[156:159], v[88:91]
	v_mfma_f32_16x16x32_bf16 v[84:87], v[120:123], v[164:167], v[84:87]
	v_mfma_f32_16x16x32_bf16 v[80:83], v[192:195], v[164:167], v[80:83]
	v_mfma_f32_16x16x32_bf16 v[76:79], v[188:191], v[176:179], v[76:79]
	v_mfma_f32_16x16x32_bf16 v[72:75], v[192:195], v[172:175], v[72:75]
	v_mfma_f32_16x16x32_bf16 v[68:71], v[188:191], v[184:187], v[68:71]
	v_mfma_f32_16x16x32_bf16 v[64:67], v[202:205], v[184:187], v[64:67]
	v_mfma_f32_16x16x32_bf16 v[206:209], v[188:191], v[160:163], v[92:95]
	v_mfma_f32_16x16x32_bf16 v[156:159], v[202:205], v[160:163], v[88:91]
	v_mfma_f32_16x16x32_bf16 v[160:163], v[188:191], v[168:171], v[84:87]
	v_mfma_f32_16x16x32_bf16 v[164:167], v[202:205], v[168:171], v[80:83]
	v_mfma_f32_16x16x32_bf16 v[168:171], v[202:205], v[176:179], v[72:75]
	s_setprio 0
	s_barrier
	s_nop 0
	s_waitcnt vmcnt(2)
	s_barrier
	s_waitcnt lgkmcnt(0)
	s_setprio 1
	s_waitcnt lgkmcnt(0)
	s_setprio 0
	s_setprio 1
	s_setprio 0
	s_barrier
	s_nop 0
	ds_read_b128 v[8:11], v138
	ds_read_b128 v[16:19], v138 offset:1024
	ds_read_b128 v[176:179], v138 offset:2048
	ds_read_b128 v[180:183], v138 offset:3072
	ds_read_b128 v[20:23], v136 offset:32768
	ds_read_b128 v[24:27], v136 offset:33792
	ds_read_b128 v[28:31], v135 offset:32768
	ds_read_b128 v[56:59], v135 offset:33792
	ds_read_b128 v[188:191], v134 offset:32768
	ds_read_b128 v[192:195], v134 offset:33792
	ds_read_b128 v[202:205], v133 offset:32768
	ds_read_b128 v[210:213], v133 offset:33792
	s_waitcnt vmcnt(0)
	s_barrier
	s_waitcnt lgkmcnt(0)
	s_setprio 1
	s_waitcnt lgkmcnt(0)
	v_mfma_f32_16x16x32_bf16 v[72:75], v[8:11], v[20:23], v[124:127]
	v_mfma_f32_16x16x32_bf16 v[120:123], v[16:19], v[24:27], v[72:75]
	v_mfma_f32_16x16x32_bf16 v[72:75], v[176:179], v[20:23], v[128:131]
	v_mfma_f32_16x16x32_bf16 v[124:127], v[180:183], v[24:27], v[72:75]
	v_mfma_f32_16x16x32_bf16 v[72:75], v[8:11], v[28:31], v[116:119]
	v_mfma_f32_16x16x32_bf16 v[116:119], v[16:19], v[56:59], v[72:75]
	v_mfma_f32_16x16x32_bf16 v[72:75], v[176:179], v[28:31], v[112:115]
	v_mfma_f32_16x16x32_bf16 v[112:115], v[180:183], v[56:59], v[72:75]
	v_mfma_f32_16x16x32_bf16 v[72:75], v[8:11], v[188:191], v[108:111]
	v_mfma_f32_16x16x32_bf16 v[88:91], v[16:19], v[192:195], v[72:75]
	v_mfma_f32_16x16x32_bf16 v[72:75], v[176:179], v[188:191], v[104:107]
	v_mfma_f32_16x16x32_bf16 v[92:95], v[180:183], v[192:195], v[72:75]
	v_mfma_f32_16x16x32_bf16 v[72:75], v[8:11], v[202:205], v[100:103]
	v_mfma_f32_16x16x32_bf16 v[84:87], v[16:19], v[210:213], v[72:75]
	v_mfma_f32_16x16x32_bf16 v[72:75], v[176:179], v[202:205], v[96:99]
	v_mfma_f32_16x16x32_bf16 v[80:83], v[180:183], v[210:213], v[72:75]
	s_setprio 0
	s_barrier
	ds_read_b128 v[128:131], v137
	ds_read_b128 v[214:217], v137 offset:1024
	ds_read_b128 v[218:221], v137 offset:2048
	ds_read_b128 v[222:225], v137 offset:3072
	s_waitcnt vmcnt(0)
	s_barrier
	s_waitcnt lgkmcnt(0)
	s_setprio 1
	s_waitcnt lgkmcnt(0)
	v_mfma_f32_16x16x32_bf16 v[72:75], v[128:131], v[20:23], v[206:209]
	v_mfma_f32_16x16x32_bf16 v[20:23], v[218:221], v[20:23], v[156:159]
	v_mfma_f32_16x16x32_bf16 v[108:111], v[222:225], v[24:27], v[20:23]
	v_mfma_f32_16x16x32_bf16 v[20:23], v[128:131], v[28:31], v[160:163]
	v_mfma_f32_16x16x32_bf16 v[100:103], v[214:217], v[56:59], v[20:23]
	v_mfma_f32_16x16x32_bf16 v[20:23], v[218:221], v[28:31], v[164:167]
	v_mfma_f32_16x16x32_bf16 v[96:99], v[222:225], v[56:59], v[20:23]
	v_mfma_f32_16x16x32_bf16 v[20:23], v[128:131], v[188:191], v[76:79]
	v_mfma_f32_16x16x32_bf16 v[104:107], v[214:217], v[24:27], v[72:75]
	v_mfma_f32_16x16x32_bf16 v[72:75], v[214:217], v[192:195], v[20:23]
	v_mfma_f32_16x16x32_bf16 v[20:23], v[218:221], v[188:191], v[168:171]
	v_mfma_f32_16x16x32_bf16 v[76:79], v[222:225], v[192:195], v[20:23]
	v_mfma_f32_16x16x32_bf16 v[20:23], v[128:131], v[202:205], v[68:71]
	v_mfma_f32_16x16x32_bf16 v[68:71], v[214:217], v[210:213], v[20:23]
	v_mfma_f32_16x16x32_bf16 v[20:23], v[218:221], v[202:205], v[64:67]
	v_mfma_f32_16x16x32_bf16 v[64:67], v[222:225], v[210:213], v[20:23]
	s_setprio 0
	s_barrier
	s_barrier
	s_waitcnt lgkmcnt(0)
	s_setprio 1
	s_waitcnt lgkmcnt(0)
	s_setprio 0
	s_setprio 1
	s_setprio 0
	s_movk_i32 s4, 0x100
	v_cmp_gt_u32_e32 vcc, s4, v132
	s_barrier
	s_and_saveexec_b64 s[4:5], vcc
	s_cbranch_execz .Lhf_195
	s_barrier

.LBB0_146:
	v_readlane_b32 s6, v254, 53
	s_add_i32 s64, s6, s61
	s_cmpk_lt_i32 s64, 0x840
	s_mov_b64 s[6:7], -1
	s_cbranch_scc1 .LBB0_182
	v_readlane_b32 s6, v255, 4
	v_readlane_b32 s7, v255, 5
	s_andn2_b64 vcc, exec, s[6:7]
	s_cbranch_vccnz .LBB0_181
	s_sub_i32 s6, 0x840, s61
	s_lshl_b32 s7, s6, 1
	s_cmp_ge_i32 s7, s42
	s_cbranch_scc1 .Lhf_noshare
	v_readlane_b32 s6, v254, 53
	s_cmp_lt_i32 s6, s7
	s_cbranch_scc1 .LBB0_181
	s_sub_i32 s6, s6, s7
	s_add_i32 s63, s6, 0x1578
	s_sub_i32 s62, s42, s7
.Lhf_noshare:
	s_mov_b32 s6, -1
	s_cmpk_gt_u32 s64, 0xe1b
	v_mbcnt_lo_u32_b32 v0, s6, 0
	v_mbcnt_hi_u32_b32 v0, s6, v0
	v_add_u32_e32 v0, s43, v0
	s_cbranch_scc1 .LBB0_181
	v_ashrrev_i32_e32 v6, 4, v0
	v_and_b32_e32 v2, 15, v0
	v_lshlrev_b32_e32 v3, 2, v6
	v_and_b32_e32 v1, 12, v3
	v_bfe_i32 v4, v6, 2, 1
	s_movk_i32 s6, 0x1600
	v_and_or_b32 v4, v4, s6, v1
	v_lshlrev_b32_e32 v5, 7, v6
	s_movk_i32 s6, 0x200
	v_and_or_b32 v5, v5, s6, v1
	v_lshlrev_b32_e32 v0, 4, v2
	v_lshlrev_b32_e32 v2, 3, v2
	s_mov_b32 s33, s63
	s_branch .LBB0_152

.LBB0_192:
	ds_read_b128 v[140:143], v129
	ds_read_b128 v[144:147], v129 offset:1024
	ds_read_b128 v[148:151], v129 offset:2048
	ds_read_b128 v[152:155], v129 offset:3072
	s_add_u32 s28, s56, s4
	v_mov_b32_e32 v196, v128
	v_mov_b32_e32 v188, v130
	s_addc_u32 s29, s57, s5
	ds_read_b128 v[156:159], v136
	ds_read_b128 v[160:163], v136 offset:1024
	ds_read_b128 v[164:167], v135
	ds_read_b128 v[168:171], v135 offset:1024
	ds_read_b128 v[172:175], v134
	ds_read_b128 v[176:179], v134 offset:1024
	ds_read_b128 v[180:183], v133
	ds_read_b128 v[184:187], v133 offset:1024
	s_add_i32 s40, s52, 0xc000
	v_mov_b32_e32 v189, v197
	s_mov_b32 m0, s40
	s_add_i32 s39, s52, 0xe000
	s_add_u32 s98, s28, s44
	s_addc_u32 s99, s29, s45
	global_load_lds_dwordx4 v128, s[98:99]
	s_mov_b32 m0, s39
	s_nop 0
	global_load_lds_dwordx4 v130, s[98:99]
	s_waitcnt lgkmcnt(8)
	s_barrier
	s_waitcnt lgkmcnt(0)
	s_setprio 1
	s_waitcnt lgkmcnt(0)
	v_mfma_f32_16x16x32_bf16 v[124:127], v[140:143], v[156:159], v[124:127]
	v_mfma_f32_16x16x32_bf16 v[120:123], v[148:151], v[156:159], v[120:123]
	v_mfma_f32_16x16x32_bf16 v[116:119], v[140:143], v[164:167], v[116:119]
	v_mfma_f32_16x16x32_bf16 v[112:115], v[148:151], v[164:167], v[112:115]
	v_mfma_f32_16x16x32_bf16 v[108:111], v[140:143], v[172:175], v[108:111]
	v_mfma_f32_16x16x32_bf16 v[104:107], v[148:151], v[172:175], v[104:107]
	v_mfma_f32_16x16x32_bf16 v[100:103], v[140:143], v[180:183], v[100:103]
	v_mfma_f32_16x16x32_bf16 v[96:99], v[148:151], v[180:183], v[96:99]
	v_mfma_f32_16x16x32_bf16 v[124:127], v[144:147], v[160:163], v[124:127]
	v_mfma_f32_16x16x32_bf16 v[120:123], v[152:155], v[160:163], v[120:123]
	v_mfma_f32_16x16x32_bf16 v[116:119], v[144:147], v[168:171], v[116:119]
	v_mfma_f32_16x16x32_bf16 v[112:115], v[152:155], v[168:171], v[112:115]
	v_mfma_f32_16x16x32_bf16 v[108:111], v[144:147], v[176:179], v[108:111]
	v_mfma_f32_16x16x32_bf16 v[104:107], v[152:155], v[176:179], v[104:107]
	v_mfma_f32_16x16x32_bf16 v[100:103], v[144:147], v[184:187], v[100:103]
	v_mfma_f32_16x16x32_bf16 v[96:99], v[152:155], v[184:187], v[96:99]
	s_setprio 0
	s_barrier
	s_add_u32 s58, s56, s36
	v_mov_b32_e32 v196, v128
	v_mov_b32_e32 v210, v130
	s_addc_u32 s59, s57, s37
	ds_read_b128 v[188:191], v139
	ds_read_b128 v[192:195], v139 offset:1024
	ds_read_b128 v[202:205], v139 offset:2048
	ds_read_b128 v[206:209], v139 offset:3072
	v_mov_b32_e32 v211, v197
	s_add_i32 m0, s52, 0x10000
	s_add_u32 s98, s58, s46
	s_addc_u32 s99, s59, s47
	global_load_lds_dwordx4 v128, s[98:99]
	s_add_i32 m0, s52, 0x12000
	s_nop 0
	global_load_lds_dwordx4 v130, s[98:99]
	s_barrier
	s_waitcnt lgkmcnt(0)
	s_setprio 1
	s_waitcnt lgkmcnt(0)
	v_mfma_f32_16x16x32_bf16 v[92:95], v[188:191], v[156:159], v[92:95]
	v_mfma_f32_16x16x32_bf16 v[88:91], v[202:205], v[156:159], v[88:91]
	v_mfma_f32_16x16x32_bf16 v[84:87], v[188:191], v[164:167], v[84:87]
	v_mfma_f32_16x16x32_bf16 v[80:83], v[202:205], v[164:167], v[80:83]
	v_mfma_f32_16x16x32_bf16 v[76:79], v[188:191], v[172:175], v[76:79]
	v_mfma_f32_16x16x32_bf16 v[72:75], v[202:205], v[172:175], v[72:75]
	v_mfma_f32_16x16x32_bf16 v[68:71], v[188:191], v[180:183], v[68:71]
	v_mfma_f32_16x16x32_bf16 v[64:67], v[202:205], v[180:183], v[64:67]
	v_mfma_f32_16x16x32_bf16 v[92:95], v[192:195], v[160:163], v[92:95]
	v_mfma_f32_16x16x32_bf16 v[88:91], v[206:209], v[160:163], v[88:91]
	v_mfma_f32_16x16x32_bf16 v[84:87], v[192:195], v[168:171], v[84:87]
	v_mfma_f32_16x16x32_bf16 v[80:83], v[206:209], v[168:171], v[80:83]
	v_mfma_f32_16x16x32_bf16 v[76:79], v[192:195], v[176:179], v[76:79]
	v_mfma_f32_16x16x32_bf16 v[72:75], v[206:209], v[176:179], v[72:75]
	v_mfma_f32_16x16x32_bf16 v[68:71], v[192:195], v[184:187], v[68:71]
	v_mfma_f32_16x16x32_bf16 v[64:67], v[206:209], v[184:187], v[64:67]
	s_setprio 0
	v_mov_b32_e32 v196, v128
	v_mov_b32_e32 v210, v130
	s_barrier
	ds_read_b128 v[156:159], v136 offset:16384
	ds_read_b128 v[160:163], v136 offset:17408
	ds_read_b128 v[164:167], v135 offset:16384
	ds_read_b128 v[168:171], v135 offset:17408
	ds_read_b128 v[172:175], v134 offset:16384
	ds_read_b128 v[176:179], v134 offset:17408
	ds_read_b128 v[180:183], v133 offset:16384
	ds_read_b128 v[184:187], v133 offset:17408
	v_mov_b32_e32 v211, v197
	s_mov_b32 m0, s52
	s_add_u32 s98, s28, s48
	s_addc_u32 s99, s29, s49
	global_load_lds_dwordx4 v128, s[98:99]
	s_add_i32 m0, s52, 0x2000
	s_nop 0
	global_load_lds_dwordx4 v130, s[98:99]
	s_barrier
	s_waitcnt lgkmcnt(0)
	s_setprio 1
	s_waitcnt lgkmcnt(0)
	v_mfma_f32_16x16x32_bf16 v[60:63], v[140:143], v[156:159], v[60:63]
	v_mfma_f32_16x16x32_bf16 v[56:59], v[148:151], v[156:159], v[56:59]
	v_mfma_f32_16x16x32_bf16 v[52:55], v[140:143], v[164:167], v[52:55]
	v_mfma_f32_16x16x32_bf16 v[48:51], v[148:151], v[164:167], v[48:51]
	v_mfma_f32_16x16x32_bf16 v[44:47], v[140:143], v[172:175], v[44:47]
	v_mfma_f32_16x16x32_bf16 v[40:43], v[148:151], v[172:175], v[40:43]
	v_mfma_f32_16x16x32_bf16 v[36:39], v[140:143], v[180:183], v[36:39]
	v_mfma_f32_16x16x32_bf16 v[32:35], v[148:151], v[180:183], v[32:35]
	v_mfma_f32_16x16x32_bf16 v[60:63], v[144:147], v[160:163], v[60:63]
	v_mfma_f32_16x16x32_bf16 v[56:59], v[152:155], v[160:163], v[56:59]
	v_mfma_f32_16x16x32_bf16 v[52:55], v[144:147], v[168:171], v[52:55]
	v_mfma_f32_16x16x32_bf16 v[48:51], v[152:155], v[168:171], v[48:51]
	v_mfma_f32_16x16x32_bf16 v[44:47], v[144:147], v[176:179], v[44:47]
	v_mfma_f32_16x16x32_bf16 v[40:43], v[152:155], v[176:179], v[40:43]
	v_mfma_f32_16x16x32_bf16 v[36:39], v[144:147], v[184:187], v[36:39]
	v_mfma_f32_16x16x32_bf16 v[32:35], v[152:155], v[184:187], v[32:35]
	s_setprio 0
	s_barrier
	v_mov_b32_e32 v196, v128
	v_mov_b32_e32 v140, v130
	v_mov_b32_e32 v141, v197
	s_add_i32 m0, s52, 0x14000
	s_add_u32 s98, s58, s50
	s_addc_u32 s99, s59, s51
	global_load_lds_dwordx4 v128, s[98:99]
	s_add_i32 m0, s52, 0x16000
	s_nop 0
	global_load_lds_dwordx4 v130, s[98:99]
	s_waitcnt vmcnt(6)
	s_barrier
	s_setprio 1
	v_mfma_f32_16x16x32_bf16 v[28:31], v[188:191], v[156:159], v[28:31]
	v_mfma_f32_16x16x32_bf16 v[24:27], v[202:205], v[156:159], v[24:27]
	v_mfma_f32_16x16x32_bf16 v[20:23], v[188:191], v[164:167], v[20:23]
	v_mfma_f32_16x16x32_bf16 v[16:19], v[202:205], v[164:167], v[16:19]
	v_mfma_f32_16x16x32_bf16 v[12:15], v[188:191], v[172:175], v[12:15]
	v_mfma_f32_16x16x32_bf16 v[8:11], v[202:205], v[172:175], v[8:11]
	v_mfma_f32_16x16x32_bf16 v[4:7], v[188:191], v[180:183], v[4:7]
	v_mfma_f32_16x16x32_bf16 v[0:3], v[202:205], v[180:183], v[0:3]
	v_mfma_f32_16x16x32_bf16 v[28:31], v[192:195], v[160:163], v[28:31]
	v_mfma_f32_16x16x32_bf16 v[24:27], v[206:209], v[160:163], v[24:27]
	v_mfma_f32_16x16x32_bf16 v[20:23], v[192:195], v[168:171], v[20:23]
	v_mfma_f32_16x16x32_bf16 v[16:19], v[206:209], v[168:171], v[16:19]
	v_mfma_f32_16x16x32_bf16 v[12:15], v[192:195], v[176:179], v[12:15]
	v_mfma_f32_16x16x32_bf16 v[8:11], v[206:209], v[176:179], v[8:11]
	v_mfma_f32_16x16x32_bf16 v[4:7], v[192:195], v[184:187], v[4:7]
	v_mfma_f32_16x16x32_bf16 v[0:3], v[206:209], v[184:187], v[0:3]
	s_setprio 0
	s_barrier
	ds_read_b128 v[140:143], v138
	ds_read_b128 v[144:147], v138 offset:1024
	ds_read_b128 v[148:151], v138 offset:2048
	ds_read_b128 v[152:155], v138 offset:3072
	v_mov_b32_e32 v196, v128
	v_mov_b32_e32 v188, v130
	ds_read_b128 v[156:159], v136 offset:32768
	ds_read_b128 v[160:163], v136 offset:33792
	ds_read_b128 v[164:167], v135 offset:32768
	ds_read_b128 v[168:171], v135 offset:33792
	ds_read_b128 v[172:175], v134 offset:32768
	ds_read_b128 v[176:179], v134 offset:33792
	ds_read_b128 v[180:183], v133 offset:32768
	ds_read_b128 v[184:187], v133 offset:33792
	v_mov_b32_e32 v189, v197
	s_add_i32 m0, s52, 0x4000
	s_add_u32 s98, s28, s54
	s_addc_u32 s99, s29, s55
	global_load_lds_dwordx4 v128, s[98:99]
	s_add_i32 m0, s52, 0x6000
	s_nop 0
	global_load_lds_dwordx4 v130, s[98:99]
	s_waitcnt lgkmcnt(8)
	s_barrier
	s_waitcnt lgkmcnt(0)
	s_setprio 1
	s_waitcnt lgkmcnt(0)
	v_mfma_f32_16x16x32_bf16 v[124:127], v[140:143], v[156:159], v[124:127]
	v_mfma_f32_16x16x32_bf16 v[120:123], v[148:151], v[156:159], v[120:123]
	v_mfma_f32_16x16x32_bf16 v[116:119], v[140:143], v[164:167], v[116:119]
	v_mfma_f32_16x16x32_bf16 v[112:115], v[148:151], v[164:167], v[112:115]
	v_mfma_f32_16x16x32_bf16 v[108:111], v[140:143], v[172:175], v[108:111]
	v_mfma_f32_16x16x32_bf16 v[104:107], v[148:151], v[172:175], v[104:107]
	v_mfma_f32_16x16x32_bf16 v[100:103], v[140:143], v[180:183], v[100:103]
	v_mfma_f32_16x16x32_bf16 v[96:99], v[148:151], v[180:183], v[96:99]
	v_mfma_f32_16x16x32_bf16 v[124:127], v[144:147], v[160:163], v[124:127]
	v_mfma_f32_16x16x32_bf16 v[120:123], v[152:155], v[160:163], v[120:123]
	v_mfma_f32_16x16x32_bf16 v[116:119], v[144:147], v[168:171], v[116:119]
	v_mfma_f32_16x16x32_bf16 v[112:115], v[152:155], v[168:171], v[112:115]
	v_mfma_f32_16x16x32_bf16 v[108:111], v[144:147], v[176:179], v[108:111]
	v_mfma_f32_16x16x32_bf16 v[104:107], v[152:155], v[176:179], v[104:107]
	v_mfma_f32_16x16x32_bf16 v[100:103], v[144:147], v[184:187], v[100:103]
	v_mfma_f32_16x16x32_bf16 v[96:99], v[152:155], v[184:187], v[96:99]
	s_setprio 0
	s_barrier
	v_mov_b32_e32 v196, v128
	v_mov_b32_e32 v210, v130
	ds_read_b128 v[188:191], v137
	ds_read_b128 v[192:195], v137 offset:1024
	ds_read_b128 v[202:205], v137 offset:2048
	ds_read_b128 v[206:209], v137 offset:3072
	v_mov_b32_e32 v211, v197
	s_mov_b32 m0, s7
	s_add_u32 s98, s58, s68
	s_addc_u32 s99, s59, s69
	global_load_lds_dwordx4 v128, s[98:99]
	s_mov_b32 m0, s53
	s_nop 0
	global_load_lds_dwordx4 v130, s[98:99]
	s_barrier
	s_waitcnt lgkmcnt(0)
	s_setprio 1
	s_waitcnt lgkmcnt(0)
	v_mfma_f32_16x16x32_bf16 v[92:95], v[188:191], v[156:159], v[92:95]
	v_mfma_f32_16x16x32_bf16 v[88:91], v[202:205], v[156:159], v[88:91]
	v_mfma_f32_16x16x32_bf16 v[84:87], v[188:191], v[164:167], v[84:87]
	v_mfma_f32_16x16x32_bf16 v[80:83], v[202:205], v[164:167], v[80:83]
	v_mfma_f32_16x16x32_bf16 v[76:79], v[188:191], v[172:175], v[76:79]
	v_mfma_f32_16x16x32_bf16 v[72:75], v[202:205], v[172:175], v[72:75]
	v_mfma_f32_16x16x32_bf16 v[68:71], v[188:191], v[180:183], v[68:71]
	v_mfma_f32_16x16x32_bf16 v[64:67], v[202:205], v[180:183], v[64:67]
	v_mfma_f32_16x16x32_bf16 v[92:95], v[192:195], v[160:163], v[92:95]
	v_mfma_f32_16x16x32_bf16 v[88:91], v[206:209], v[160:163], v[88:91]
	v_mfma_f32_16x16x32_bf16 v[84:87], v[192:195], v[168:171], v[84:87]
	v_mfma_f32_16x16x32_bf16 v[80:83], v[206:209], v[168:171], v[80:83]
	v_mfma_f32_16x16x32_bf16 v[76:79], v[192:195], v[176:179], v[76:79]
	v_mfma_f32_16x16x32_bf16 v[72:75], v[206:209], v[176:179], v[72:75]
	v_mfma_f32_16x16x32_bf16 v[68:71], v[192:195], v[184:187], v[68:71]
	v_mfma_f32_16x16x32_bf16 v[64:67], v[206:209], v[184:187], v[64:67]
	s_setprio 0
	v_mov_b32_e32 v196, v128
	v_mov_b32_e32 v210, v130
	s_barrier
	ds_read_b128 v[156:159], v136 offset:49152
	ds_read_b128 v[160:163], v136 offset:50176
	ds_read_b128 v[164:167], v135 offset:49152
	ds_read_b128 v[168:171], v135 offset:50176
	ds_read_b128 v[172:175], v134 offset:49152
	ds_read_b128 v[176:179], v134 offset:50176
	ds_read_b128 v[180:183], v133 offset:49152
	ds_read_b128 v[184:187], v133 offset:50176
	v_mov_b32_e32 v211, v197
	s_mov_b32 m0, s9
	s_add_u32 s98, s28, s70
	s_addc_u32 s99, s29, s71
	global_load_lds_dwordx4 v128, s[98:99]
	s_mov_b32 m0, s33
	s_nop 0
	global_load_lds_dwordx4 v130, s[98:99]
	s_barrier
	s_waitcnt lgkmcnt(0)
	s_setprio 1
	s_waitcnt lgkmcnt(0)
	v_mfma_f32_16x16x32_bf16 v[60:63], v[140:143], v[156:159], v[60:63]
	v_mfma_f32_16x16x32_bf16 v[56:59], v[148:151], v[156:159], v[56:59]
	v_mfma_f32_16x16x32_bf16 v[52:55], v[140:143], v[164:167], v[52:55]
	v_mfma_f32_16x16x32_bf16 v[48:51], v[148:151], v[164:167], v[48:51]
	v_mfma_f32_16x16x32_bf16 v[44:47], v[140:143], v[172:175], v[44:47]
	v_mfma_f32_16x16x32_bf16 v[40:43], v[148:151], v[172:175], v[40:43]
	v_mfma_f32_16x16x32_bf16 v[36:39], v[140:143], v[180:183], v[36:39]
	v_mfma_f32_16x16x32_bf16 v[32:35], v[148:151], v[180:183], v[32:35]
	v_mfma_f32_16x16x32_bf16 v[60:63], v[144:147], v[160:163], v[60:63]
	v_mfma_f32_16x16x32_bf16 v[56:59], v[152:155], v[160:163], v[56:59]
	v_mfma_f32_16x16x32_bf16 v[52:55], v[144:147], v[168:171], v[52:55]
	v_mfma_f32_16x16x32_bf16 v[48:51], v[152:155], v[168:171], v[48:51]
	v_mfma_f32_16x16x32_bf16 v[44:47], v[144:147], v[176:179], v[44:47]
	v_mfma_f32_16x16x32_bf16 v[40:43], v[152:155], v[176:179], v[40:43]
	v_mfma_f32_16x16x32_bf16 v[36:39], v[144:147], v[184:187], v[36:39]
	v_mfma_f32_16x16x32_bf16 v[32:35], v[152:155], v[184:187], v[32:35]
	s_setprio 0
	s_barrier
	v_mov_b32_e32 v196, v128
	v_mov_b32_e32 v140, v130
	v_mov_b32_e32 v141, v197
	s_mov_b32 m0, s65
	s_add_u32 s98, s58, s72
	s_addc_u32 s99, s59, s73
	global_load_lds_dwordx4 v128, s[98:99]
	s_mov_b32 m0, s66
	s_nop 0
	global_load_lds_dwordx4 v130, s[98:99]
	s_waitcnt vmcnt(6)
	s_barrier
	s_setprio 1
	v_mfma_f32_16x16x32_bf16 v[28:31], v[188:191], v[156:159], v[28:31]
	v_mfma_f32_16x16x32_bf16 v[24:27], v[202:205], v[156:159], v[24:27]
	v_mfma_f32_16x16x32_bf16 v[20:23], v[188:191], v[164:167], v[20:23]
	v_mfma_f32_16x16x32_bf16 v[16:19], v[202:205], v[164:167], v[16:19]
	v_mfma_f32_16x16x32_bf16 v[12:15], v[188:191], v[172:175], v[12:15]
	v_mfma_f32_16x16x32_bf16 v[8:11], v[202:205], v[172:175], v[8:11]
	v_mfma_f32_16x16x32_bf16 v[4:7], v[188:191], v[180:183], v[4:7]
	v_mfma_f32_16x16x32_bf16 v[0:3], v[202:205], v[180:183], v[0:3]
	v_mfma_f32_16x16x32_bf16 v[28:31], v[192:195], v[160:163], v[28:31]
	v_mfma_f32_16x16x32_bf16 v[24:27], v[206:209], v[160:163], v[24:27]
	v_mfma_f32_16x16x32_bf16 v[20:23], v[192:195], v[168:171], v[20:23]
	v_mfma_f32_16x16x32_bf16 v[16:19], v[206:209], v[168:171], v[16:19]
	v_mfma_f32_16x16x32_bf16 v[12:15], v[192:195], v[176:179], v[12:15]
	v_mfma_f32_16x16x32_bf16 v[8:11], v[206:209], v[176:179], v[8:11]
	v_mfma_f32_16x16x32_bf16 v[4:7], v[192:195], v[184:187], v[4:7]
	v_mfma_f32_16x16x32_bf16 v[0:3], v[206:209], v[184:187], v[0:3]
	s_setprio 0
	s_add_i32 s38, s38, 2
	s_add_u32 s56, s56, 0x100
	s_addc_u32 s57, s57, 0
	s_cmp_lt_u32 s38, 28
	s_barrier
	s_cbranch_scc1 .LBB0_192
	s_lshl_b64 s[4:5], s[10:11], 12
	v_readlane_b32 s10, v254, 12
	v_readlane_b32 s11, v254, 13
	s_add_u32 s4, s10, s4
	s_addc_u32 s5, s11, s5
	ds_read_b128 v[140:143], v129
	ds_read_b128 v[144:147], v129 offset:1024
	ds_read_b128 v[148:151], v129 offset:2048
	ds_read_b128 v[152:155], v129 offset:3072
	ds_read_b128 v[156:159], v136
	ds_read_b128 v[160:163], v136 offset:1024
	ds_read_b128 v[164:167], v135
	ds_read_b128 v[168:171], v135 offset:1024
	ds_read_b128 v[172:175], v134
	ds_read_b128 v[176:179], v134 offset:1024
	ds_read_b128 v[180:183], v133
	ds_read_b128 v[184:187], v133 offset:1024
	v_mov_b32_e32 v129, v197
	v_lshl_add_u64 v[128:129], s[4:5], 0, v[128:129]
	s_mov_b64 s[10:11], 0xf80
	s_mov_b32 m0, s40
	v_lshl_add_u64 v[128:129], v[128:129], 0, s[10:11]
	v_mov_b32_e32 v131, v197
	global_load_lds_dwordx4 v[128:129], off
	v_lshl_add_u64 v[128:129], s[4:5], 0, v[130:131]
	v_lshl_add_u64 v[128:129], v[128:129], 0, s[10:11]
	s_mov_b32 m0, s39
	s_nop 0
	global_load_lds_dwordx4 v[128:129], off
	s_barrier
	s_waitcnt lgkmcnt(0)
	s_setprio 1
	s_waitcnt lgkmcnt(0)
	v_mfma_f32_16x16x32_bf16 v[124:127], v[140:143], v[156:159], v[124:127]
	v_mfma_f32_16x16x32_bf16 v[116:119], v[140:143], v[164:167], v[116:119]
	v_mfma_f32_16x16x32_bf16 v[112:115], v[148:151], v[164:167], v[112:115]
	v_mfma_f32_16x16x32_bf16 v[108:111], v[140:143], v[172:175], v[108:111]
	v_mfma_f32_16x16x32_bf16 v[104:107], v[148:151], v[172:175], v[104:107]
	v_mfma_f32_16x16x32_bf16 v[100:103], v[140:143], v[180:183], v[100:103]
	v_mfma_f32_16x16x32_bf16 v[96:99], v[148:151], v[180:183], v[96:99]
	v_mfma_f32_16x16x32_bf16 v[124:127], v[144:147], v[160:163], v[124:127]
	v_mfma_f32_16x16x32_bf16 v[120:123], v[148:151], v[156:159], v[120:123]
	v_mfma_f32_16x16x32_bf16 v[116:119], v[144:147], v[168:171], v[116:119]
	v_mfma_f32_16x16x32_bf16 v[112:115], v[152:155], v[168:171], v[112:115]
	v_mfma_f32_16x16x32_bf16 v[108:111], v[144:147], v[176:179], v[108:111]
	v_mfma_f32_16x16x32_bf16 v[104:107], v[152:155], v[176:179], v[104:107]
	v_mfma_f32_16x16x32_bf16 v[100:103], v[144:147], v[184:187], v[100:103]
	v_mfma_f32_16x16x32_bf16 v[96:99], v[152:155], v[184:187], v[96:99]
	v_mfma_f32_16x16x32_bf16 v[128:131], v[152:155], v[160:163], v[120:123]
	s_setprio 0
	s_barrier
	s_nop 0
	ds_read_b128 v[120:123], v139
	ds_read_b128 v[188:191], v139 offset:1024
	ds_read_b128 v[192:195], v139 offset:2048
	ds_read_b128 v[202:205], v139 offset:3072
	s_barrier
	s_waitcnt lgkmcnt(0)
	s_setprio 1
	s_waitcnt lgkmcnt(0)
	v_mfma_f32_16x16x32_bf16 v[76:79], v[120:123], v[172:175], v[76:79]
	v_mfma_f32_16x16x32_bf16 v[68:71], v[120:123], v[180:183], v[68:71]
	v_mfma_f32_16x16x32_bf16 v[64:67], v[192:195], v[180:183], v[64:67]
	v_mfma_f32_16x16x32_bf16 v[92:95], v[120:123], v[156:159], v[92:95]
	v_mfma_f32_16x16x32_bf16 v[88:91], v[192:195], v[156:159], v[88:91]
	v_mfma_f32_16x16x32_bf16 v[84:87], v[120:123], v[164:167], v[84:87]
	v_mfma_f32_16x16x32_bf16 v[80:83], v[192:195], v[164:167], v[80:83]
	v_mfma_f32_16x16x32_bf16 v[76:79], v[188:191], v[176:179], v[76:79]
	v_mfma_f32_16x16x32_bf16 v[72:75], v[192:195], v[172:175], v[72:75]
	v_mfma_f32_16x16x32_bf16 v[68:71], v[188:191], v[184:187], v[68:71]
	v_mfma_f32_16x16x32_bf16 v[64:67], v[202:205], v[184:187], v[64:67]
	v_mfma_f32_16x16x32_bf16 v[206:209], v[188:191], v[160:163], v[92:95]
	v_mfma_f32_16x16x32_bf16 v[156:159], v[202:205], v[160:163], v[88:91]
	v_mfma_f32_16x16x32_bf16 v[160:163], v[188:191], v[168:171], v[84:87]
	v_mfma_f32_16x16x32_bf16 v[164:167], v[202:205], v[168:171], v[80:83]
	v_mfma_f32_16x16x32_bf16 v[168:171], v[202:205], v[176:179], v[72:75]
	s_setprio 0
	s_barrier
	s_nop 0
	ds_read_b128 v[72:75], v136 offset:16384
	ds_read_b128 v[80:83], v136 offset:17408
	ds_read_b128 v[84:87], v135 offset:16384
	ds_read_b128 v[88:91], v135 offset:17408
	ds_read_b128 v[92:95], v134 offset:16384
	ds_read_b128 v[172:175], v134 offset:17408
	ds_read_b128 v[176:179], v133 offset:16384
	ds_read_b128 v[180:183], v133 offset:17408
	s_waitcnt vmcnt(4)
	s_barrier
	s_waitcnt lgkmcnt(0)
	s_setprio 1
	s_waitcnt lgkmcnt(0)
	v_mfma_f32_16x16x32_bf16 v[60:63], v[140:143], v[72:75], v[60:63]
	v_mfma_f32_16x16x32_bf16 v[52:55], v[140:143], v[84:87], v[52:55]
	v_mfma_f32_16x16x32_bf16 v[48:51], v[148:151], v[84:87], v[48:51]
	v_mfma_f32_16x16x32_bf16 v[44:47], v[140:143], v[92:95], v[44:47]
	v_mfma_f32_16x16x32_bf16 v[40:43], v[148:151], v[92:95], v[40:43]
	v_mfma_f32_16x16x32_bf16 v[36:39], v[140:143], v[176:179], v[36:39]
	v_mfma_f32_16x16x32_bf16 v[32:35], v[148:151], v[176:179], v[32:35]
	v_mfma_f32_16x16x32_bf16 v[60:63], v[144:147], v[80:83], v[60:63]
	v_mfma_f32_16x16x32_bf16 v[56:59], v[148:151], v[72:75], v[56:59]
	v_mfma_f32_16x16x32_bf16 v[52:55], v[144:147], v[88:91], v[52:55]
	v_mfma_f32_16x16x32_bf16 v[48:51], v[152:155], v[88:91], v[48:51]
	v_mfma_f32_16x16x32_bf16 v[44:47], v[144:147], v[172:175], v[44:47]
	v_mfma_f32_16x16x32_bf16 v[40:43], v[152:155], v[172:175], v[40:43]
	v_mfma_f32_16x16x32_bf16 v[36:39], v[144:147], v[180:183], v[36:39]
	v_mfma_f32_16x16x32_bf16 v[32:35], v[152:155], v[180:183], v[32:35]
	v_mfma_f32_16x16x32_bf16 v[184:187], v[152:155], v[80:83], v[56:59]
	s_setprio 0
	s_setprio 1
	v_mfma_f32_16x16x32_bf16 v[12:15], v[120:123], v[92:95], v[12:15]
	v_mfma_f32_16x16x32_bf16 v[4:7], v[120:123], v[176:179], v[4:7]
	v_mfma_f32_16x16x32_bf16 v[0:3], v[192:195], v[176:179], v[0:3]
	v_mfma_f32_16x16x32_bf16 v[28:31], v[120:123], v[72:75], v[28:31]
	v_mfma_f32_16x16x32_bf16 v[24:27], v[192:195], v[72:75], v[24:27]
	v_mfma_f32_16x16x32_bf16 v[20:23], v[120:123], v[84:87], v[20:23]
	v_mfma_f32_16x16x32_bf16 v[16:19], v[192:195], v[84:87], v[16:19]
	v_mfma_f32_16x16x32_bf16 v[12:15], v[188:191], v[172:175], v[12:15]
	v_mfma_f32_16x16x32_bf16 v[8:11], v[192:195], v[92:95], v[8:11]
	v_mfma_f32_16x16x32_bf16 v[4:7], v[188:191], v[180:183], v[4:7]
	v_mfma_f32_16x16x32_bf16 v[0:3], v[202:205], v[180:183], v[0:3]
	v_mfma_f32_16x16x32_bf16 v[140:143], v[188:191], v[80:83], v[28:31]
	v_mfma_f32_16x16x32_bf16 v[144:147], v[202:205], v[80:83], v[24:27]
	v_mfma_f32_16x16x32_bf16 v[148:151], v[188:191], v[88:91], v[20:23]
	v_mfma_f32_16x16x32_bf16 v[152:155], v[202:205], v[88:91], v[16:19]
	v_mfma_f32_16x16x32_bf16 v[172:175], v[202:205], v[172:175], v[8:11]
	s_setprio 0
	s_barrier
	s_nop 0
	ds_read_b128 v[8:11], v138
	ds_read_b128 v[16:19], v138 offset:1024
	ds_read_b128 v[176:179], v138 offset:2048
	ds_read_b128 v[180:183], v138 offset:3072
	ds_read_b128 v[20:23], v136 offset:32768
	ds_read_b128 v[24:27], v136 offset:33792
	ds_read_b128 v[28:31], v135 offset:32768
	ds_read_b128 v[56:59], v135 offset:33792
	ds_read_b128 v[188:191], v134 offset:32768
	ds_read_b128 v[192:195], v134 offset:33792
	ds_read_b128 v[202:205], v133 offset:32768
	ds_read_b128 v[210:213], v133 offset:33792
	s_waitcnt vmcnt(2)
	s_barrier
	s_waitcnt lgkmcnt(0)
	s_setprio 1
	s_waitcnt lgkmcnt(0)
	v_mfma_f32_16x16x32_bf16 v[72:75], v[8:11], v[20:23], v[124:127]
	v_mfma_f32_16x16x32_bf16 v[120:123], v[16:19], v[24:27], v[72:75]
	v_mfma_f32_16x16x32_bf16 v[72:75], v[176:179], v[20:23], v[128:131]
	v_mfma_f32_16x16x32_bf16 v[124:127], v[180:183], v[24:27], v[72:75]
	v_mfma_f32_16x16x32_bf16 v[72:75], v[8:11], v[28:31], v[116:119]
	v_mfma_f32_16x16x32_bf16 v[116:119], v[16:19], v[56:59], v[72:75]
	v_mfma_f32_16x16x32_bf16 v[72:75], v[176:179], v[28:31], v[112:115]
	v_mfma_f32_16x16x32_bf16 v[112:115], v[180:183], v[56:59], v[72:75]
	v_mfma_f32_16x16x32_bf16 v[72:75], v[8:11], v[188:191], v[108:111]
	v_mfma_f32_16x16x32_bf16 v[88:91], v[16:19], v[192:195], v[72:75]
	v_mfma_f32_16x16x32_bf16 v[72:75], v[176:179], v[188:191], v[104:107]
	v_mfma_f32_16x16x32_bf16 v[92:95], v[180:183], v[192:195], v[72:75]
	v_mfma_f32_16x16x32_bf16 v[72:75], v[8:11], v[202:205], v[100:103]
	v_mfma_f32_16x16x32_bf16 v[84:87], v[16:19], v[210:213], v[72:75]
	v_mfma_f32_16x16x32_bf16 v[72:75], v[176:179], v[202:205], v[96:99]
	v_mfma_f32_16x16x32_bf16 v[80:83], v[180:183], v[210:213], v[72:75]
	s_setprio 0
	s_barrier
	ds_read_b128 v[128:131], v137
	ds_read_b128 v[214:217], v137 offset:1024
	ds_read_b128 v[218:221], v137 offset:2048
	ds_read_b128 v[222:225], v137 offset:3072
	s_waitcnt vmcnt(0)
	s_barrier
	s_waitcnt lgkmcnt(0)
	s_setprio 1
	s_waitcnt lgkmcnt(0)
	v_mfma_f32_16x16x32_bf16 v[72:75], v[128:131], v[20:23], v[206:209]
	v_mfma_f32_16x16x32_bf16 v[20:23], v[218:221], v[20:23], v[156:159]
	v_mfma_f32_16x16x32_bf16 v[108:111], v[222:225], v[24:27], v[20:23]
	v_mfma_f32_16x16x32_bf16 v[20:23], v[128:131], v[28:31], v[160:163]
	v_mfma_f32_16x16x32_bf16 v[100:103], v[214:217], v[56:59], v[20:23]
	v_mfma_f32_16x16x32_bf16 v[20:23], v[218:221], v[28:31], v[164:167]
	v_mfma_f32_16x16x32_bf16 v[96:99], v[222:225], v[56:59], v[20:23]
	v_mfma_f32_16x16x32_bf16 v[20:23], v[128:131], v[188:191], v[76:79]
	v_mfma_f32_16x16x32_bf16 v[104:107], v[214:217], v[24:27], v[72:75]
	v_mfma_f32_16x16x32_bf16 v[72:75], v[214:217], v[192:195], v[20:23]
	v_mfma_f32_16x16x32_bf16 v[20:23], v[218:221], v[188:191], v[168:171]
	v_mfma_f32_16x16x32_bf16 v[76:79], v[222:225], v[192:195], v[20:23]
	v_mfma_f32_16x16x32_bf16 v[20:23], v[128:131], v[202:205], v[68:71]
	v_mfma_f32_16x16x32_bf16 v[68:71], v[214:217], v[210:213], v[20:23]
	v_mfma_f32_16x16x32_bf16 v[20:23], v[218:221], v[202:205], v[64:67]
	v_mfma_f32_16x16x32_bf16 v[64:67], v[222:225], v[210:213], v[20:23]
	s_setprio 0
	s_barrier
	ds_read_b128 v[156:159], v136 offset:49152
	ds_read_b128 v[136:139], v136 offset:50176
	ds_read_b128 v[160:163], v135 offset:49152
	ds_read_b128 v[164:167], v135 offset:50176
	ds_read_b128 v[168:171], v134 offset:49152
	ds_read_b128 v[188:191], v134 offset:50176
	ds_read_b128 v[192:195], v133 offset:49152
	ds_read_b128 v[202:205], v133 offset:50176
	s_barrier
	s_waitcnt lgkmcnt(0)
	s_setprio 1
	s_waitcnt lgkmcnt(0)
	v_mfma_f32_16x16x32_bf16 v[20:23], v[8:11], v[156:159], v[60:63]
	v_mfma_f32_16x16x32_bf16 v[56:59], v[16:19], v[136:139], v[20:23]
	v_mfma_f32_16x16x32_bf16 v[20:23], v[176:179], v[156:159], v[184:187]
	v_mfma_f32_16x16x32_bf16 v[60:63], v[180:183], v[136:139], v[20:23]
	v_mfma_f32_16x16x32_bf16 v[20:23], v[8:11], v[160:163], v[52:55]
	v_mfma_f32_16x16x32_bf16 v[52:55], v[16:19], v[164:167], v[20:23]
	v_mfma_f32_16x16x32_bf16 v[20:23], v[176:179], v[160:163], v[48:51]
	v_mfma_f32_16x16x32_bf16 v[48:51], v[180:183], v[164:167], v[20:23]
	v_mfma_f32_16x16x32_bf16 v[20:23], v[8:11], v[168:171], v[44:47]
	v_mfma_f32_16x16x32_bf16 v[24:27], v[16:19], v[188:191], v[20:23]
	v_mfma_f32_16x16x32_bf16 v[20:23], v[176:179], v[168:171], v[40:43]
	v_mfma_f32_16x16x32_bf16 v[8:11], v[8:11], v[192:195], v[36:39]
	v_mfma_f32_16x16x32_bf16 v[28:31], v[180:183], v[188:191], v[20:23]
	v_mfma_f32_16x16x32_bf16 v[20:23], v[16:19], v[202:205], v[8:11]
	v_mfma_f32_16x16x32_bf16 v[8:11], v[176:179], v[192:195], v[32:35]
	v_mfma_f32_16x16x32_bf16 v[16:19], v[180:183], v[202:205], v[8:11]
	s_setprio 0
	s_setprio 1
	v_mfma_f32_16x16x32_bf16 v[8:11], v[128:131], v[156:159], v[140:143]
	v_mfma_f32_16x16x32_bf16 v[40:43], v[214:217], v[136:139], v[8:11]
	v_mfma_f32_16x16x32_bf16 v[8:11], v[218:221], v[156:159], v[144:147]
	v_mfma_f32_16x16x32_bf16 v[44:47], v[222:225], v[136:139], v[8:11]
	v_mfma_f32_16x16x32_bf16 v[8:11], v[128:131], v[160:163], v[148:151]
	v_mfma_f32_16x16x32_bf16 v[36:39], v[214:217], v[164:167], v[8:11]
	v_mfma_f32_16x16x32_bf16 v[8:11], v[218:221], v[160:163], v[152:155]
	v_mfma_f32_16x16x32_bf16 v[32:35], v[222:225], v[164:167], v[8:11]
	v_mfma_f32_16x16x32_bf16 v[8:11], v[128:131], v[168:171], v[12:15]
	v_mfma_f32_16x16x32_bf16 v[12:15], v[218:221], v[168:171], v[172:175]
	v_mfma_f32_16x16x32_bf16 v[4:7], v[128:131], v[192:195], v[4:7]
	v_mfma_f32_16x16x32_bf16 v[0:3], v[218:221], v[192:195], v[0:3]
	v_mfma_f32_16x16x32_bf16 v[8:11], v[214:217], v[188:191], v[8:11]
	v_mfma_f32_16x16x32_bf16 v[12:15], v[222:225], v[188:191], v[12:15]
	v_mfma_f32_16x16x32_bf16 v[4:7], v[214:217], v[202:205], v[4:7]
	v_mfma_f32_16x16x32_bf16 v[0:3], v[222:225], v[202:205], v[0:3]
	s_setprio 0
	s_movk_i32 s4, 0x100
	v_cmp_gt_u32_e32 vcc, s4, v132
	s_barrier
	s_and_saveexec_b64 s[4:5], vcc
	s_cbranch_execz .LBB0_195
	s_barrier

.Lh1_loop:
	ds_read_b128 v[140:143], v129
	ds_read_b128 v[144:147], v129 offset:1024
	ds_read_b128 v[148:151], v129 offset:2048
	ds_read_b128 v[152:155], v129 offset:3072
	s_add_u32 s28, s60, s56
	v_mov_b32_e32 v196, v128
	v_mov_b32_e32 v188, v130
	s_addc_u32 s29, s61, s57
	ds_read_b128 v[156:159], v136
	ds_read_b128 v[160:163], v136 offset:1024
	ds_read_b128 v[164:167], v135
	ds_read_b128 v[168:171], v135 offset:1024
	ds_read_b128 v[172:175], v134
	ds_read_b128 v[176:179], v134 offset:1024
	ds_read_b128 v[180:183], v133
	ds_read_b128 v[184:187], v133 offset:1024
	s_add_i32 s40, s53, 0xc000
	v_mov_b32_e32 v189, v197
	s_mov_b32 m0, s40
	s_add_i32 s39, s53, 0xe000
	s_mov_b32 m0, s39
	s_nop 0
	s_waitcnt lgkmcnt(8)
	s_barrier
	s_waitcnt lgkmcnt(0)
	s_setprio 1
	s_waitcnt lgkmcnt(0)
	v_mfma_f32_16x16x32_bf16 v[124:127], v[140:143], v[156:159], v[124:127]
	v_mfma_f32_16x16x32_bf16 v[120:123], v[148:151], v[156:159], v[120:123]
	v_mfma_f32_16x16x32_bf16 v[116:119], v[140:143], v[164:167], v[116:119]
	v_mfma_f32_16x16x32_bf16 v[112:115], v[148:151], v[164:167], v[112:115]
	v_mfma_f32_16x16x32_bf16 v[108:111], v[140:143], v[172:175], v[108:111]
	v_mfma_f32_16x16x32_bf16 v[104:107], v[148:151], v[172:175], v[104:107]
	v_mfma_f32_16x16x32_bf16 v[100:103], v[140:143], v[180:183], v[100:103]
	v_mfma_f32_16x16x32_bf16 v[96:99], v[148:151], v[180:183], v[96:99]
	v_mfma_f32_16x16x32_bf16 v[124:127], v[144:147], v[160:163], v[124:127]
	v_mfma_f32_16x16x32_bf16 v[120:123], v[152:155], v[160:163], v[120:123]
	v_mfma_f32_16x16x32_bf16 v[116:119], v[144:147], v[168:171], v[116:119]
	v_mfma_f32_16x16x32_bf16 v[112:115], v[152:155], v[168:171], v[112:115]
	v_mfma_f32_16x16x32_bf16 v[108:111], v[144:147], v[176:179], v[108:111]
	v_mfma_f32_16x16x32_bf16 v[104:107], v[152:155], v[176:179], v[104:107]
	v_mfma_f32_16x16x32_bf16 v[100:103], v[144:147], v[184:187], v[100:103]
	v_mfma_f32_16x16x32_bf16 v[96:99], v[152:155], v[184:187], v[96:99]
	s_setprio 0
	s_barrier
	s_add_u32 s62, s60, s36
	v_mov_b32_e32 v196, v128
	v_mov_b32_e32 v210, v130
	s_addc_u32 s63, s61, s37
	ds_read_b128 v[188:191], v139
	ds_read_b128 v[192:195], v139 offset:1024
	ds_read_b128 v[202:205], v139 offset:2048
	ds_read_b128 v[206:209], v139 offset:3072
	v_mov_b32_e32 v211, v197
	s_mov_b32 m0, s68
	s_add_u32 s98, s62, s46
	s_addc_u32 s99, s63, s47
	global_load_lds_dwordx4 v128, s[98:99]
	s_mov_b32 m0, s69
	s_nop 0
	global_load_lds_dwordx4 v130, s[98:99]
	s_barrier
	s_waitcnt lgkmcnt(0)
	s_setprio 1
	s_waitcnt lgkmcnt(0)
	v_mfma_f32_16x16x32_bf16 v[92:95], v[188:191], v[156:159], v[92:95]
	v_mfma_f32_16x16x32_bf16 v[88:91], v[202:205], v[156:159], v[88:91]
	v_mfma_f32_16x16x32_bf16 v[84:87], v[188:191], v[164:167], v[84:87]
	v_mfma_f32_16x16x32_bf16 v[80:83], v[202:205], v[164:167], v[80:83]
	v_mfma_f32_16x16x32_bf16 v[76:79], v[188:191], v[172:175], v[76:79]
	v_mfma_f32_16x16x32_bf16 v[72:75], v[202:205], v[172:175], v[72:75]
	v_mfma_f32_16x16x32_bf16 v[68:71], v[188:191], v[180:183], v[68:71]
	v_mfma_f32_16x16x32_bf16 v[64:67], v[202:205], v[180:183], v[64:67]
	v_mfma_f32_16x16x32_bf16 v[92:95], v[192:195], v[160:163], v[92:95]
	v_mfma_f32_16x16x32_bf16 v[88:91], v[206:209], v[160:163], v[88:91]
	v_mfma_f32_16x16x32_bf16 v[84:87], v[192:195], v[168:171], v[84:87]
	v_mfma_f32_16x16x32_bf16 v[80:83], v[206:209], v[168:171], v[80:83]
	v_mfma_f32_16x16x32_bf16 v[76:79], v[192:195], v[176:179], v[76:79]
	v_mfma_f32_16x16x32_bf16 v[72:75], v[206:209], v[176:179], v[72:75]
	v_mfma_f32_16x16x32_bf16 v[68:71], v[192:195], v[184:187], v[68:71]
	v_mfma_f32_16x16x32_bf16 v[64:67], v[206:209], v[184:187], v[64:67]
	s_setprio 0
	v_mov_b32_e32 v196, v128
	v_mov_b32_e32 v210, v130
	s_barrier
	v_mov_b32_e32 v211, v197
	s_mov_b32 m0, s53
	s_add_u32 s98, s28, s48
	s_addc_u32 s99, s29, s49
	global_load_lds_dwordx4 v128, s[98:99]
	s_mov_b32 m0, s11
	s_nop 0
	global_load_lds_dwordx4 v130, s[98:99]
	s_waitcnt vmcnt(4)
	s_barrier
	v_mov_b32_e32 v196, v128
	v_mov_b32_e32 v140, v130
	v_mov_b32_e32 v141, v197
	s_mov_b32 m0, s9
	s_add_u32 s98, s62, s50
	s_addc_u32 s99, s63, s51
	global_load_lds_dwordx4 v128, s[98:99]
	s_mov_b32 m0, s70
	s_nop 0
	global_load_lds_dwordx4 v130, s[98:99]
	s_barrier
	ds_read_b128 v[140:143], v138
	ds_read_b128 v[144:147], v138 offset:1024
	ds_read_b128 v[148:151], v138 offset:2048
	ds_read_b128 v[152:155], v138 offset:3072
	v_mov_b32_e32 v196, v128
	v_mov_b32_e32 v188, v130
	ds_read_b128 v[156:159], v136 offset:32768
	ds_read_b128 v[160:163], v136 offset:33792
	ds_read_b128 v[164:167], v135 offset:32768
	ds_read_b128 v[168:171], v135 offset:33792
	ds_read_b128 v[172:175], v134 offset:32768
	ds_read_b128 v[176:179], v134 offset:33792
	ds_read_b128 v[180:183], v133 offset:32768
	ds_read_b128 v[184:187], v133 offset:33792
	v_mov_b32_e32 v189, v197
	s_mov_b32 m0, s71
	s_mov_b32 m0, s72
	s_nop 0
	s_waitcnt lgkmcnt(8)
	s_barrier
	s_waitcnt lgkmcnt(0)
	s_setprio 1
	s_waitcnt lgkmcnt(0)
	v_mfma_f32_16x16x32_bf16 v[124:127], v[140:143], v[156:159], v[124:127]
	v_mfma_f32_16x16x32_bf16 v[120:123], v[148:151], v[156:159], v[120:123]
	v_mfma_f32_16x16x32_bf16 v[116:119], v[140:143], v[164:167], v[116:119]
	v_mfma_f32_16x16x32_bf16 v[112:115], v[148:151], v[164:167], v[112:115]
	v_mfma_f32_16x16x32_bf16 v[108:111], v[140:143], v[172:175], v[108:111]
	v_mfma_f32_16x16x32_bf16 v[104:107], v[148:151], v[172:175], v[104:107]
	v_mfma_f32_16x16x32_bf16 v[100:103], v[140:143], v[180:183], v[100:103]
	v_mfma_f32_16x16x32_bf16 v[96:99], v[148:151], v[180:183], v[96:99]
	v_mfma_f32_16x16x32_bf16 v[124:127], v[144:147], v[160:163], v[124:127]
	v_mfma_f32_16x16x32_bf16 v[120:123], v[152:155], v[160:163], v[120:123]
	v_mfma_f32_16x16x32_bf16 v[116:119], v[144:147], v[168:171], v[116:119]
	v_mfma_f32_16x16x32_bf16 v[112:115], v[152:155], v[168:171], v[112:115]
	v_mfma_f32_16x16x32_bf16 v[108:111], v[144:147], v[176:179], v[108:111]
	v_mfma_f32_16x16x32_bf16 v[104:107], v[152:155], v[176:179], v[104:107]
	v_mfma_f32_16x16x32_bf16 v[100:103], v[144:147], v[184:187], v[100:103]
	v_mfma_f32_16x16x32_bf16 v[96:99], v[152:155], v[184:187], v[96:99]
	s_setprio 0
	s_barrier
	v_mov_b32_e32 v196, v128
	v_mov_b32_e32 v210, v130
	ds_read_b128 v[188:191], v137
	ds_read_b128 v[192:195], v137 offset:1024
	ds_read_b128 v[202:205], v137 offset:2048
	ds_read_b128 v[206:209], v137 offset:3072
	v_mov_b32_e32 v211, v197
	s_mov_b32 m0, s66
	s_add_u32 s98, s62, s90
	s_addc_u32 s99, s63, s91
	global_load_lds_dwordx4 v128, s[98:99]
	s_mov_b32 m0, s64
	s_nop 0
	global_load_lds_dwordx4 v130, s[98:99]
	s_barrier
	s_waitcnt lgkmcnt(0)
	s_setprio 1
	s_waitcnt lgkmcnt(0)
	v_mfma_f32_16x16x32_bf16 v[92:95], v[188:191], v[156:159], v[92:95]
	v_mfma_f32_16x16x32_bf16 v[88:91], v[202:205], v[156:159], v[88:91]
	v_mfma_f32_16x16x32_bf16 v[84:87], v[188:191], v[164:167], v[84:87]
	v_mfma_f32_16x16x32_bf16 v[80:83], v[202:205], v[164:167], v[80:83]
	v_mfma_f32_16x16x32_bf16 v[76:79], v[188:191], v[172:175], v[76:79]
	v_mfma_f32_16x16x32_bf16 v[72:75], v[202:205], v[172:175], v[72:75]
	v_mfma_f32_16x16x32_bf16 v[68:71], v[188:191], v[180:183], v[68:71]
	v_mfma_f32_16x16x32_bf16 v[64:67], v[202:205], v[180:183], v[64:67]
	v_mfma_f32_16x16x32_bf16 v[92:95], v[192:195], v[160:163], v[92:95]
	v_mfma_f32_16x16x32_bf16 v[88:91], v[206:209], v[160:163], v[88:91]
	v_mfma_f32_16x16x32_bf16 v[84:87], v[192:195], v[168:171], v[84:87]
	v_mfma_f32_16x16x32_bf16 v[80:83], v[206:209], v[168:171], v[80:83]
	v_mfma_f32_16x16x32_bf16 v[76:79], v[192:195], v[176:179], v[76:79]
	v_mfma_f32_16x16x32_bf16 v[72:75], v[206:209], v[176:179], v[72:75]
	v_mfma_f32_16x16x32_bf16 v[68:71], v[192:195], v[184:187], v[68:71]
	v_mfma_f32_16x16x32_bf16 v[64:67], v[206:209], v[184:187], v[64:67]
	s_setprio 0
	v_mov_b32_e32 v196, v128
	v_mov_b32_e32 v210, v130
	s_barrier
	v_mov_b32_e32 v211, v197
	s_mov_b32 m0, s65
	s_add_u32 s98, s28, s92
	s_addc_u32 s99, s29, s93
	global_load_lds_dwordx4 v128, s[98:99]
	s_mov_b32 m0, s67
	s_nop 0
	global_load_lds_dwordx4 v130, s[98:99]
	s_waitcnt vmcnt(4)
	s_barrier
	v_mov_b32_e32 v196, v128
	v_mov_b32_e32 v140, v130
	v_mov_b32_e32 v141, v197
	s_mov_b32 m0, s33
	s_add_u32 s98, s62, s96
	s_addc_u32 s99, s63, s97
	global_load_lds_dwordx4 v128, s[98:99]
	s_mov_b32 m0, s73
	s_nop 0
	global_load_lds_dwordx4 v130, s[98:99]
	s_barrier
	s_add_i32 s38, s38, 2
	s_add_u32 s60, s60, 0x100
	s_addc_u32 s61, s61, 0
	s_cmp_lt_u32 s38, 28
	s_cbranch_scc1 .Lh1_loop
	ds_read_b128 v[140:143], v129
	ds_read_b128 v[144:147], v129 offset:1024
	ds_read_b128 v[148:151], v129 offset:2048
	ds_read_b128 v[152:155], v129 offset:3072
	ds_read_b128 v[156:159], v136
	ds_read_b128 v[160:163], v136 offset:1024
	ds_read_b128 v[164:167], v135
	ds_read_b128 v[168:171], v135 offset:1024
	ds_read_b128 v[172:175], v134
	ds_read_b128 v[176:179], v134 offset:1024
	ds_read_b128 v[180:183], v133
	ds_read_b128 v[184:187], v133 offset:1024
	v_mov_b32_e32 v129, v197
	v_lshl_add_u64 v[128:129], s[58:59], 0, v[128:129]
	s_mov_b64 s[28:29], 0xf80
	s_mov_b32 m0, s40
	v_lshl_add_u64 v[128:129], v[128:129], 0, s[28:29]
	v_mov_b32_e32 v131, v197
	v_lshl_add_u64 v[128:129], s[58:59], 0, v[130:131]
	v_lshl_add_u64 v[128:129], v[128:129], 0, s[28:29]
	s_mov_b32 m0, s39
	s_nop 0
	s_barrier
	s_waitcnt lgkmcnt(0)
	s_setprio 1
	s_waitcnt lgkmcnt(0)
	v_mfma_f32_16x16x32_bf16 v[124:127], v[140:143], v[156:159], v[124:127]
	v_mfma_f32_16x16x32_bf16 v[120:123], v[148:151], v[156:159], v[120:123]
	v_mfma_f32_16x16x32_bf16 v[116:119], v[140:143], v[164:167], v[116:119]
	v_mfma_f32_16x16x32_bf16 v[112:115], v[148:151], v[164:167], v[112:115]
	v_mfma_f32_16x16x32_bf16 v[108:111], v[140:143], v[172:175], v[108:111]
	v_mfma_f32_16x16x32_bf16 v[100:103], v[140:143], v[180:183], v[100:103]
	v_mfma_f32_16x16x32_bf16 v[96:99], v[148:151], v[180:183], v[96:99]
	v_mfma_f32_16x16x32_bf16 v[124:127], v[144:147], v[160:163], v[124:127]
	v_mfma_f32_16x16x32_bf16 v[120:123], v[152:155], v[160:163], v[120:123]
	v_mfma_f32_16x16x32_bf16 v[116:119], v[144:147], v[168:171], v[116:119]
	v_mfma_f32_16x16x32_bf16 v[112:115], v[152:155], v[168:171], v[112:115]
	v_mfma_f32_16x16x32_bf16 v[108:111], v[144:147], v[176:179], v[108:111]
	v_mfma_f32_16x16x32_bf16 v[104:107], v[148:151], v[172:175], v[104:107]
	v_mfma_f32_16x16x32_bf16 v[100:103], v[144:147], v[184:187], v[100:103]
	v_mfma_f32_16x16x32_bf16 v[96:99], v[152:155], v[184:187], v[96:99]
	v_mfma_f32_16x16x32_bf16 v[128:131], v[152:155], v[176:179], v[104:107]
	s_setprio 0
	s_barrier
	s_nop 2
	ds_read_b128 v[104:107], v139
	ds_read_b128 v[188:191], v139 offset:1024
	ds_read_b128 v[192:195], v139 offset:2048
	ds_read_b128 v[202:205], v139 offset:3072
	s_barrier
	s_waitcnt lgkmcnt(0)
	s_setprio 1
	s_waitcnt lgkmcnt(0)
	v_mfma_f32_16x16x32_bf16 v[92:95], v[104:107], v[156:159], v[92:95]
	v_mfma_f32_16x16x32_bf16 v[84:87], v[104:107], v[164:167], v[84:87]
	v_mfma_f32_16x16x32_bf16 v[76:79], v[104:107], v[172:175], v[76:79]
	v_mfma_f32_16x16x32_bf16 v[68:71], v[104:107], v[180:183], v[68:71]
	v_mfma_f32_16x16x32_bf16 v[64:67], v[192:195], v[180:183], v[64:67]
	v_mfma_f32_16x16x32_bf16 v[92:95], v[188:191], v[160:163], v[92:95]
	v_mfma_f32_16x16x32_bf16 v[88:91], v[192:195], v[156:159], v[88:91]
	v_mfma_f32_16x16x32_bf16 v[84:87], v[188:191], v[168:171], v[84:87]
	v_mfma_f32_16x16x32_bf16 v[80:83], v[192:195], v[164:167], v[80:83]
	v_mfma_f32_16x16x32_bf16 v[76:79], v[188:191], v[176:179], v[76:79]
	v_mfma_f32_16x16x32_bf16 v[72:75], v[192:195], v[172:175], v[72:75]
	v_mfma_f32_16x16x32_bf16 v[68:71], v[188:191], v[184:187], v[68:71]
	v_mfma_f32_16x16x32_bf16 v[64:67], v[202:205], v[184:187], v[64:67]
	v_mfma_f32_16x16x32_bf16 v[156:159], v[202:205], v[160:163], v[88:91]
	v_mfma_f32_16x16x32_bf16 v[160:163], v[202:205], v[168:171], v[80:83]
	v_mfma_f32_16x16x32_bf16 v[164:167], v[202:205], v[176:179], v[72:75]
	s_setprio 0
	s_barrier
	s_nop 0
	s_waitcnt vmcnt(2)
	s_barrier
	s_waitcnt lgkmcnt(0)
	s_setprio 1
	s_waitcnt lgkmcnt(0)
	s_setprio 0
	s_setprio 1
	s_setprio 0
	s_barrier
	ds_read_b128 v[16:19], v138
	ds_read_b128 v[180:183], v138 offset:1024
	ds_read_b128 v[184:187], v138 offset:2048
	ds_read_b128 v[188:191], v138 offset:3072
	ds_read_b128 v[0:3], v136 offset:32768
	ds_read_b128 v[4:7], v136 offset:33792
	ds_read_b128 v[8:11], v135 offset:32768
	ds_read_b128 v[12:15], v135 offset:33792
	ds_read_b128 v[44:47], v134 offset:32768
	ds_read_b128 v[192:195], v134 offset:33792
	ds_read_b128 v[202:205], v133 offset:32768
	ds_read_b128 v[218:221], v133 offset:33792
	s_waitcnt vmcnt(0)
	s_barrier
	s_waitcnt lgkmcnt(0)
	s_setprio 1
	s_waitcnt lgkmcnt(0)
	v_mfma_f32_16x16x32_bf16 v[28:31], v[16:19], v[0:3], v[124:127]
	v_mfma_f32_16x16x32_bf16 v[52:55], v[180:183], v[4:7], v[28:31]
	v_mfma_f32_16x16x32_bf16 v[28:31], v[184:187], v[0:3], v[120:123]
	v_mfma_f32_16x16x32_bf16 v[104:107], v[188:191], v[4:7], v[28:31]
	v_mfma_f32_16x16x32_bf16 v[28:31], v[16:19], v[8:11], v[116:119]
	v_mfma_f32_16x16x32_bf16 v[72:75], v[180:183], v[12:15], v[28:31]
	v_mfma_f32_16x16x32_bf16 v[28:31], v[184:187], v[8:11], v[112:115]
	v_mfma_f32_16x16x32_bf16 v[116:119], v[188:191], v[12:15], v[28:31]
	v_mfma_f32_16x16x32_bf16 v[28:31], v[16:19], v[44:47], v[108:111]
	v_mfma_f32_16x16x32_bf16 v[80:83], v[180:183], v[192:195], v[28:31]
	v_mfma_f32_16x16x32_bf16 v[28:31], v[184:187], v[44:47], v[128:131]
	v_mfma_f32_16x16x32_bf16 v[108:111], v[188:191], v[192:195], v[28:31]
	v_mfma_f32_16x16x32_bf16 v[28:31], v[16:19], v[202:205], v[100:103]
	v_mfma_f32_16x16x32_bf16 v[88:91], v[180:183], v[218:221], v[28:31]
	v_mfma_f32_16x16x32_bf16 v[28:31], v[184:187], v[202:205], v[96:99]
	v_mfma_f32_16x16x32_bf16 v[96:99], v[188:191], v[218:221], v[28:31]
	s_setprio 0
	s_barrier
	ds_read_b128 v[128:131], v137
	ds_read_b128 v[222:225], v137 offset:1024
	ds_read_b128 v[228:231], v137 offset:2048
	ds_read_b128 v[232:235], v137 offset:3072
	s_waitcnt vmcnt(0)
	s_barrier
	s_waitcnt lgkmcnt(0)
	s_setprio 1
	s_waitcnt lgkmcnt(0)
	v_mfma_f32_16x16x32_bf16 v[28:31], v[128:131], v[0:3], v[92:95]
	v_mfma_f32_16x16x32_bf16 v[0:3], v[228:231], v[0:3], v[156:159]
	v_mfma_f32_16x16x32_bf16 v[28:31], v[222:225], v[4:7], v[28:31]
	v_mfma_f32_16x16x32_bf16 v[0:3], v[232:235], v[4:7], v[0:3]
	v_mfma_f32_16x16x32_bf16 v[4:7], v[128:131], v[8:11], v[84:87]
	v_mfma_f32_16x16x32_bf16 v[36:39], v[222:225], v[12:15], v[4:7]
	v_mfma_f32_16x16x32_bf16 v[4:7], v[228:231], v[8:11], v[160:163]
	v_mfma_f32_16x16x32_bf16 v[4:7], v[232:235], v[12:15], v[4:7]
	v_mfma_f32_16x16x32_bf16 v[8:11], v[128:131], v[44:47], v[76:79]
	v_mfma_f32_16x16x32_bf16 v[12:15], v[128:131], v[202:205], v[68:71]
	v_mfma_f32_16x16x32_bf16 v[40:43], v[222:225], v[192:195], v[8:11]
	v_mfma_f32_16x16x32_bf16 v[8:11], v[228:231], v[44:47], v[164:167]
	v_mfma_f32_16x16x32_bf16 v[44:47], v[222:225], v[218:221], v[12:15]
	v_mfma_f32_16x16x32_bf16 v[12:15], v[228:231], v[202:205], v[64:67]
	v_mfma_f32_16x16x32_bf16 v[8:11], v[232:235], v[192:195], v[8:11]
	v_mfma_f32_16x16x32_bf16 v[12:15], v[232:235], v[218:221], v[12:15]
	s_setprio 0
	s_barrier
	s_barrier
	s_waitcnt lgkmcnt(0)
	s_setprio 1
	s_waitcnt lgkmcnt(0)
	s_setprio 0
	s_setprio 1
	s_setprio 0
	s_movk_i32 s9, 0x100
	v_cmp_gt_u32_e32 vcc, s9, v132
	s_barrier
	s_and_saveexec_b64 s[28:29], vcc
	s_cbranch_execz .Lh1_epi
	s_barrier

.LBB0_255:
	ds_read_b128 v[140:143], v129
	ds_read_b128 v[144:147], v129 offset:1024
	ds_read_b128 v[148:151], v129 offset:2048
	ds_read_b128 v[152:155], v129 offset:3072
	s_add_u32 s28, s60, s56
	v_mov_b32_e32 v196, v128
	v_mov_b32_e32 v188, v130
	s_addc_u32 s29, s61, s57
	ds_read_b128 v[156:159], v136
	ds_read_b128 v[160:163], v136 offset:1024
	ds_read_b128 v[164:167], v135
	ds_read_b128 v[168:171], v135 offset:1024
	ds_read_b128 v[172:175], v134
	ds_read_b128 v[176:179], v134 offset:1024
	ds_read_b128 v[180:183], v133
	ds_read_b128 v[184:187], v133 offset:1024
	s_add_i32 s40, s53, 0xc000
	v_mov_b32_e32 v189, v197
	s_mov_b32 m0, s40
	s_add_i32 s39, s53, 0xe000
	s_add_u32 s98, s28, s44
	s_addc_u32 s99, s29, s45
	global_load_lds_dwordx4 v128, s[98:99]
	s_mov_b32 m0, s39
	s_nop 0
	global_load_lds_dwordx4 v130, s[98:99]
	s_waitcnt lgkmcnt(8)
	s_barrier
	s_waitcnt lgkmcnt(0)
	s_setprio 1
	s_waitcnt lgkmcnt(0)
	v_mfma_f32_16x16x32_bf16 v[124:127], v[140:143], v[156:159], v[124:127]
	v_mfma_f32_16x16x32_bf16 v[120:123], v[148:151], v[156:159], v[120:123]
	v_mfma_f32_16x16x32_bf16 v[116:119], v[140:143], v[164:167], v[116:119]
	v_mfma_f32_16x16x32_bf16 v[112:115], v[148:151], v[164:167], v[112:115]
	v_mfma_f32_16x16x32_bf16 v[108:111], v[140:143], v[172:175], v[108:111]
	v_mfma_f32_16x16x32_bf16 v[104:107], v[148:151], v[172:175], v[104:107]
	v_mfma_f32_16x16x32_bf16 v[100:103], v[140:143], v[180:183], v[100:103]
	v_mfma_f32_16x16x32_bf16 v[96:99], v[148:151], v[180:183], v[96:99]
	v_mfma_f32_16x16x32_bf16 v[124:127], v[144:147], v[160:163], v[124:127]
	v_mfma_f32_16x16x32_bf16 v[120:123], v[152:155], v[160:163], v[120:123]
	v_mfma_f32_16x16x32_bf16 v[116:119], v[144:147], v[168:171], v[116:119]
	v_mfma_f32_16x16x32_bf16 v[112:115], v[152:155], v[168:171], v[112:115]
	v_mfma_f32_16x16x32_bf16 v[108:111], v[144:147], v[176:179], v[108:111]
	v_mfma_f32_16x16x32_bf16 v[104:107], v[152:155], v[176:179], v[104:107]
	v_mfma_f32_16x16x32_bf16 v[100:103], v[144:147], v[184:187], v[100:103]
	v_mfma_f32_16x16x32_bf16 v[96:99], v[152:155], v[184:187], v[96:99]
	s_setprio 0
	s_barrier
	s_add_u32 s62, s60, s36
	v_mov_b32_e32 v196, v128
	v_mov_b32_e32 v210, v130
	s_addc_u32 s63, s61, s37
	ds_read_b128 v[188:191], v139
	ds_read_b128 v[192:195], v139 offset:1024
	ds_read_b128 v[202:205], v139 offset:2048
	ds_read_b128 v[206:209], v139 offset:3072
	v_mov_b32_e32 v211, v197
	s_mov_b32 m0, s68
	s_add_u32 s98, s62, s46
	s_addc_u32 s99, s63, s47
	global_load_lds_dwordx4 v128, s[98:99]
	s_mov_b32 m0, s69
	s_nop 0
	global_load_lds_dwordx4 v130, s[98:99]
	s_barrier
	s_waitcnt lgkmcnt(0)
	s_setprio 1
	s_waitcnt lgkmcnt(0)
	v_mfma_f32_16x16x32_bf16 v[92:95], v[188:191], v[156:159], v[92:95]
	v_mfma_f32_16x16x32_bf16 v[88:91], v[202:205], v[156:159], v[88:91]
	v_mfma_f32_16x16x32_bf16 v[84:87], v[188:191], v[164:167], v[84:87]
	v_mfma_f32_16x16x32_bf16 v[80:83], v[202:205], v[164:167], v[80:83]
	v_mfma_f32_16x16x32_bf16 v[76:79], v[188:191], v[172:175], v[76:79]
	v_mfma_f32_16x16x32_bf16 v[72:75], v[202:205], v[172:175], v[72:75]
	v_mfma_f32_16x16x32_bf16 v[68:71], v[188:191], v[180:183], v[68:71]
	v_mfma_f32_16x16x32_bf16 v[64:67], v[202:205], v[180:183], v[64:67]
	v_mfma_f32_16x16x32_bf16 v[92:95], v[192:195], v[160:163], v[92:95]
	v_mfma_f32_16x16x32_bf16 v[88:91], v[206:209], v[160:163], v[88:91]
	v_mfma_f32_16x16x32_bf16 v[84:87], v[192:195], v[168:171], v[84:87]
	v_mfma_f32_16x16x32_bf16 v[80:83], v[206:209], v[168:171], v[80:83]
	v_mfma_f32_16x16x32_bf16 v[76:79], v[192:195], v[176:179], v[76:79]
	v_mfma_f32_16x16x32_bf16 v[72:75], v[206:209], v[176:179], v[72:75]
	v_mfma_f32_16x16x32_bf16 v[68:71], v[192:195], v[184:187], v[68:71]
	v_mfma_f32_16x16x32_bf16 v[64:67], v[206:209], v[184:187], v[64:67]
	s_setprio 0
	v_mov_b32_e32 v196, v128
	v_mov_b32_e32 v210, v130
	s_barrier
	ds_read_b128 v[156:159], v136 offset:16384
	ds_read_b128 v[160:163], v136 offset:17408
	ds_read_b128 v[164:167], v135 offset:16384
	ds_read_b128 v[168:171], v135 offset:17408
	ds_read_b128 v[172:175], v134 offset:16384
	ds_read_b128 v[176:179], v134 offset:17408
	ds_read_b128 v[180:183], v133 offset:16384
	ds_read_b128 v[184:187], v133 offset:17408
	v_mov_b32_e32 v211, v197
	s_mov_b32 m0, s53
	s_add_u32 s98, s28, s48
	s_addc_u32 s99, s29, s49
	global_load_lds_dwordx4 v128, s[98:99]
	s_mov_b32 m0, s11
	s_nop 0
	global_load_lds_dwordx4 v130, s[98:99]
	s_barrier
	s_waitcnt lgkmcnt(0)
	s_setprio 1
	s_waitcnt lgkmcnt(0)
	v_mfma_f32_16x16x32_bf16 v[60:63], v[140:143], v[156:159], v[60:63]
	v_mfma_f32_16x16x32_bf16 v[56:59], v[148:151], v[156:159], v[56:59]
	v_mfma_f32_16x16x32_bf16 v[52:55], v[140:143], v[164:167], v[52:55]
	v_mfma_f32_16x16x32_bf16 v[48:51], v[148:151], v[164:167], v[48:51]
	v_mfma_f32_16x16x32_bf16 v[44:47], v[140:143], v[172:175], v[44:47]
	v_mfma_f32_16x16x32_bf16 v[40:43], v[148:151], v[172:175], v[40:43]
	v_mfma_f32_16x16x32_bf16 v[36:39], v[140:143], v[180:183], v[36:39]
	v_mfma_f32_16x16x32_bf16 v[32:35], v[148:151], v[180:183], v[32:35]
	v_mfma_f32_16x16x32_bf16 v[60:63], v[144:147], v[160:163], v[60:63]
	v_mfma_f32_16x16x32_bf16 v[56:59], v[152:155], v[160:163], v[56:59]
	v_mfma_f32_16x16x32_bf16 v[52:55], v[144:147], v[168:171], v[52:55]
	v_mfma_f32_16x16x32_bf16 v[48:51], v[152:155], v[168:171], v[48:51]
	v_mfma_f32_16x16x32_bf16 v[44:47], v[144:147], v[176:179], v[44:47]
	v_mfma_f32_16x16x32_bf16 v[40:43], v[152:155], v[176:179], v[40:43]
	v_mfma_f32_16x16x32_bf16 v[36:39], v[144:147], v[184:187], v[36:39]
	v_mfma_f32_16x16x32_bf16 v[32:35], v[152:155], v[184:187], v[32:35]
	s_setprio 0
	s_barrier
	v_mov_b32_e32 v196, v128
	v_mov_b32_e32 v140, v130
	v_mov_b32_e32 v141, v197
	s_mov_b32 m0, s9
	s_add_u32 s98, s62, s50
	s_addc_u32 s99, s63, s51
	global_load_lds_dwordx4 v128, s[98:99]
	s_mov_b32 m0, s70
	s_nop 0
	global_load_lds_dwordx4 v130, s[98:99]
	s_waitcnt vmcnt(6)
	s_barrier
	s_setprio 1
	v_mfma_f32_16x16x32_bf16 v[28:31], v[188:191], v[156:159], v[28:31]
	v_mfma_f32_16x16x32_bf16 v[24:27], v[202:205], v[156:159], v[24:27]
	v_mfma_f32_16x16x32_bf16 v[20:23], v[188:191], v[164:167], v[20:23]
	v_mfma_f32_16x16x32_bf16 v[16:19], v[202:205], v[164:167], v[16:19]
	v_mfma_f32_16x16x32_bf16 v[12:15], v[188:191], v[172:175], v[12:15]
	v_mfma_f32_16x16x32_bf16 v[8:11], v[202:205], v[172:175], v[8:11]
	v_mfma_f32_16x16x32_bf16 v[4:7], v[188:191], v[180:183], v[4:7]
	v_mfma_f32_16x16x32_bf16 v[0:3], v[202:205], v[180:183], v[0:3]
	v_mfma_f32_16x16x32_bf16 v[28:31], v[192:195], v[160:163], v[28:31]
	v_mfma_f32_16x16x32_bf16 v[24:27], v[206:209], v[160:163], v[24:27]
	v_mfma_f32_16x16x32_bf16 v[20:23], v[192:195], v[168:171], v[20:23]
	v_mfma_f32_16x16x32_bf16 v[16:19], v[206:209], v[168:171], v[16:19]
	v_mfma_f32_16x16x32_bf16 v[12:15], v[192:195], v[176:179], v[12:15]
	v_mfma_f32_16x16x32_bf16 v[8:11], v[206:209], v[176:179], v[8:11]
	v_mfma_f32_16x16x32_bf16 v[4:7], v[192:195], v[184:187], v[4:7]
	v_mfma_f32_16x16x32_bf16 v[0:3], v[206:209], v[184:187], v[0:3]
	s_setprio 0
	s_barrier
	ds_read_b128 v[140:143], v138
	ds_read_b128 v[144:147], v138 offset:1024
	ds_read_b128 v[148:151], v138 offset:2048
	ds_read_b128 v[152:155], v138 offset:3072
	v_mov_b32_e32 v196, v128
	v_mov_b32_e32 v188, v130
	ds_read_b128 v[156:159], v136 offset:32768
	ds_read_b128 v[160:163], v136 offset:33792
	ds_read_b128 v[164:167], v135 offset:32768
	ds_read_b128 v[168:171], v135 offset:33792
	ds_read_b128 v[172:175], v134 offset:32768
	ds_read_b128 v[176:179], v134 offset:33792
	ds_read_b128 v[180:183], v133 offset:32768
	ds_read_b128 v[184:187], v133 offset:33792
	v_mov_b32_e32 v189, v197
	s_mov_b32 m0, s71
	s_add_u32 s98, s28, s74
	s_addc_u32 s99, s29, s75
	global_load_lds_dwordx4 v128, s[98:99]
	s_mov_b32 m0, s72
	s_nop 0
	global_load_lds_dwordx4 v130, s[98:99]
	s_waitcnt lgkmcnt(8)
	s_barrier
	s_waitcnt lgkmcnt(0)
	s_setprio 1
	s_waitcnt lgkmcnt(0)
	v_mfma_f32_16x16x32_bf16 v[124:127], v[140:143], v[156:159], v[124:127]
	v_mfma_f32_16x16x32_bf16 v[120:123], v[148:151], v[156:159], v[120:123]
	v_mfma_f32_16x16x32_bf16 v[116:119], v[140:143], v[164:167], v[116:119]
	v_mfma_f32_16x16x32_bf16 v[112:115], v[148:151], v[164:167], v[112:115]
	v_mfma_f32_16x16x32_bf16 v[108:111], v[140:143], v[172:175], v[108:111]
	v_mfma_f32_16x16x32_bf16 v[104:107], v[148:151], v[172:175], v[104:107]
	v_mfma_f32_16x16x32_bf16 v[100:103], v[140:143], v[180:183], v[100:103]
	v_mfma_f32_16x16x32_bf16 v[96:99], v[148:151], v[180:183], v[96:99]
	v_mfma_f32_16x16x32_bf16 v[124:127], v[144:147], v[160:163], v[124:127]
	v_mfma_f32_16x16x32_bf16 v[120:123], v[152:155], v[160:163], v[120:123]
	v_mfma_f32_16x16x32_bf16 v[116:119], v[144:147], v[168:171], v[116:119]
	v_mfma_f32_16x16x32_bf16 v[112:115], v[152:155], v[168:171], v[112:115]
	v_mfma_f32_16x16x32_bf16 v[108:111], v[144:147], v[176:179], v[108:111]
	v_mfma_f32_16x16x32_bf16 v[104:107], v[152:155], v[176:179], v[104:107]
	v_mfma_f32_16x16x32_bf16 v[100:103], v[144:147], v[184:187], v[100:103]
	v_mfma_f32_16x16x32_bf16 v[96:99], v[152:155], v[184:187], v[96:99]
	s_setprio 0
	s_barrier
	v_mov_b32_e32 v196, v128
	v_mov_b32_e32 v210, v130
	ds_read_b128 v[188:191], v137
	ds_read_b128 v[192:195], v137 offset:1024
	ds_read_b128 v[202:205], v137 offset:2048
	ds_read_b128 v[206:209], v137 offset:3072
	v_mov_b32_e32 v211, v197
	s_mov_b32 m0, s66
	s_add_u32 s98, s62, s90
	s_addc_u32 s99, s63, s91
	global_load_lds_dwordx4 v128, s[98:99]
	s_mov_b32 m0, s64
	s_nop 0
	global_load_lds_dwordx4 v130, s[98:99]
	s_barrier
	s_waitcnt lgkmcnt(0)
	s_setprio 1
	s_waitcnt lgkmcnt(0)
	v_mfma_f32_16x16x32_bf16 v[92:95], v[188:191], v[156:159], v[92:95]
	v_mfma_f32_16x16x32_bf16 v[88:91], v[202:205], v[156:159], v[88:91]
	v_mfma_f32_16x16x32_bf16 v[84:87], v[188:191], v[164:167], v[84:87]
	v_mfma_f32_16x16x32_bf16 v[80:83], v[202:205], v[164:167], v[80:83]
	v_mfma_f32_16x16x32_bf16 v[76:79], v[188:191], v[172:175], v[76:79]
	v_mfma_f32_16x16x32_bf16 v[72:75], v[202:205], v[172:175], v[72:75]
	v_mfma_f32_16x16x32_bf16 v[68:71], v[188:191], v[180:183], v[68:71]
	v_mfma_f32_16x16x32_bf16 v[64:67], v[202:205], v[180:183], v[64:67]
	v_mfma_f32_16x16x32_bf16 v[92:95], v[192:195], v[160:163], v[92:95]
	v_mfma_f32_16x16x32_bf16 v[88:91], v[206:209], v[160:163], v[88:91]
	v_mfma_f32_16x16x32_bf16 v[84:87], v[192:195], v[168:171], v[84:87]
	v_mfma_f32_16x16x32_bf16 v[80:83], v[206:209], v[168:171], v[80:83]
	v_mfma_f32_16x16x32_bf16 v[76:79], v[192:195], v[176:179], v[76:79]
	v_mfma_f32_16x16x32_bf16 v[72:75], v[206:209], v[176:179], v[72:75]
	v_mfma_f32_16x16x32_bf16 v[68:71], v[192:195], v[184:187], v[68:71]
	v_mfma_f32_16x16x32_bf16 v[64:67], v[206:209], v[184:187], v[64:67]
	s_setprio 0
	v_mov_b32_e32 v196, v128
	v_mov_b32_e32 v210, v130
	s_barrier
	ds_read_b128 v[156:159], v136 offset:49152
	ds_read_b128 v[160:163], v136 offset:50176
	ds_read_b128 v[164:167], v135 offset:49152
	ds_read_b128 v[168:171], v135 offset:50176
	ds_read_b128 v[172:175], v134 offset:49152
	ds_read_b128 v[176:179], v134 offset:50176
	ds_read_b128 v[180:183], v133 offset:49152
	ds_read_b128 v[184:187], v133 offset:50176
	v_mov_b32_e32 v211, v197
	s_mov_b32 m0, s65
	s_add_u32 s98, s28, s92
	s_addc_u32 s99, s29, s93
	global_load_lds_dwordx4 v128, s[98:99]
	s_mov_b32 m0, s67
	s_nop 0
	global_load_lds_dwordx4 v130, s[98:99]
	s_barrier
	s_waitcnt lgkmcnt(0)
	s_setprio 1
	s_waitcnt lgkmcnt(0)
	v_mfma_f32_16x16x32_bf16 v[60:63], v[140:143], v[156:159], v[60:63]
	v_mfma_f32_16x16x32_bf16 v[56:59], v[148:151], v[156:159], v[56:59]
	v_mfma_f32_16x16x32_bf16 v[52:55], v[140:143], v[164:167], v[52:55]
	v_mfma_f32_16x16x32_bf16 v[48:51], v[148:151], v[164:167], v[48:51]
	v_mfma_f32_16x16x32_bf16 v[44:47], v[140:143], v[172:175], v[44:47]
	v_mfma_f32_16x16x32_bf16 v[40:43], v[148:151], v[172:175], v[40:43]
	v_mfma_f32_16x16x32_bf16 v[36:39], v[140:143], v[180:183], v[36:39]
	v_mfma_f32_16x16x32_bf16 v[32:35], v[148:151], v[180:183], v[32:35]
	v_mfma_f32_16x16x32_bf16 v[60:63], v[144:147], v[160:163], v[60:63]
	v_mfma_f32_16x16x32_bf16 v[56:59], v[152:155], v[160:163], v[56:59]
	v_mfma_f32_16x16x32_bf16 v[52:55], v[144:147], v[168:171], v[52:55]
	v_mfma_f32_16x16x32_bf16 v[48:51], v[152:155], v[168:171], v[48:51]
	v_mfma_f32_16x16x32_bf16 v[44:47], v[144:147], v[176:179], v[44:47]
	v_mfma_f32_16x16x32_bf16 v[40:43], v[152:155], v[176:179], v[40:43]
	v_mfma_f32_16x16x32_bf16 v[36:39], v[144:147], v[184:187], v[36:39]
	v_mfma_f32_16x16x32_bf16 v[32:35], v[152:155], v[184:187], v[32:35]
	s_setprio 0
	s_barrier
	v_mov_b32_e32 v196, v128
	v_mov_b32_e32 v140, v130
	v_mov_b32_e32 v141, v197
	s_mov_b32 m0, s33
	s_add_u32 s98, s62, s96
	s_addc_u32 s99, s63, s97
	global_load_lds_dwordx4 v128, s[98:99]
	s_mov_b32 m0, s73
	s_nop 0
	global_load_lds_dwordx4 v130, s[98:99]
	s_waitcnt vmcnt(6)
	s_barrier
	s_setprio 1
	v_mfma_f32_16x16x32_bf16 v[28:31], v[188:191], v[156:159], v[28:31]
	v_mfma_f32_16x16x32_bf16 v[24:27], v[202:205], v[156:159], v[24:27]
	v_mfma_f32_16x16x32_bf16 v[20:23], v[188:191], v[164:167], v[20:23]
	v_mfma_f32_16x16x32_bf16 v[16:19], v[202:205], v[164:167], v[16:19]
	v_mfma_f32_16x16x32_bf16 v[12:15], v[188:191], v[172:175], v[12:15]
	v_mfma_f32_16x16x32_bf16 v[8:11], v[202:205], v[172:175], v[8:11]
	v_mfma_f32_16x16x32_bf16 v[4:7], v[188:191], v[180:183], v[4:7]
	v_mfma_f32_16x16x32_bf16 v[0:3], v[202:205], v[180:183], v[0:3]
	v_mfma_f32_16x16x32_bf16 v[28:31], v[192:195], v[160:163], v[28:31]
	v_mfma_f32_16x16x32_bf16 v[24:27], v[206:209], v[160:163], v[24:27]
	v_mfma_f32_16x16x32_bf16 v[20:23], v[192:195], v[168:171], v[20:23]
	v_mfma_f32_16x16x32_bf16 v[16:19], v[206:209], v[168:171], v[16:19]
	v_mfma_f32_16x16x32_bf16 v[12:15], v[192:195], v[176:179], v[12:15]
	v_mfma_f32_16x16x32_bf16 v[8:11], v[206:209], v[176:179], v[8:11]
	v_mfma_f32_16x16x32_bf16 v[4:7], v[192:195], v[184:187], v[4:7]
	v_mfma_f32_16x16x32_bf16 v[0:3], v[206:209], v[184:187], v[0:3]
	s_setprio 0
	s_add_i32 s38, s38, 2
	s_add_u32 s60, s60, 0x100
	s_addc_u32 s61, s61, 0
	s_cmp_lt_u32 s38, 28
	s_barrier
	s_cbranch_scc1 .LBB0_255
	ds_read_b128 v[140:143], v129
	ds_read_b128 v[144:147], v129 offset:1024
	ds_read_b128 v[148:151], v129 offset:2048
	ds_read_b128 v[152:155], v129 offset:3072
	ds_read_b128 v[156:159], v136
	ds_read_b128 v[160:163], v136 offset:1024
	ds_read_b128 v[164:167], v135
	ds_read_b128 v[168:171], v135 offset:1024
	ds_read_b128 v[172:175], v134
	ds_read_b128 v[176:179], v134 offset:1024
	ds_read_b128 v[180:183], v133
	ds_read_b128 v[184:187], v133 offset:1024
	v_mov_b32_e32 v129, v197
	v_lshl_add_u64 v[128:129], s[58:59], 0, v[128:129]
	s_mov_b64 s[28:29], 0xf80
	s_mov_b32 m0, s40
	v_lshl_add_u64 v[128:129], v[128:129], 0, s[28:29]
	v_mov_b32_e32 v131, v197
	global_load_lds_dwordx4 v[128:129], off
	v_lshl_add_u64 v[128:129], s[58:59], 0, v[130:131]
	v_lshl_add_u64 v[128:129], v[128:129], 0, s[28:29]
	s_mov_b32 m0, s39
	s_nop 0
	global_load_lds_dwordx4 v[128:129], off
	s_barrier
	s_waitcnt lgkmcnt(0)
	s_setprio 1
	s_waitcnt lgkmcnt(0)
	v_mfma_f32_16x16x32_bf16 v[124:127], v[140:143], v[156:159], v[124:127]
	v_mfma_f32_16x16x32_bf16 v[120:123], v[148:151], v[156:159], v[120:123]
	v_mfma_f32_16x16x32_bf16 v[116:119], v[140:143], v[164:167], v[116:119]
	v_mfma_f32_16x16x32_bf16 v[112:115], v[148:151], v[164:167], v[112:115]
	v_mfma_f32_16x16x32_bf16 v[108:111], v[140:143], v[172:175], v[108:111]
	v_mfma_f32_16x16x32_bf16 v[100:103], v[140:143], v[180:183], v[100:103]
	v_mfma_f32_16x16x32_bf16 v[96:99], v[148:151], v[180:183], v[96:99]
	v_mfma_f32_16x16x32_bf16 v[124:127], v[144:147], v[160:163], v[124:127]
	v_mfma_f32_16x16x32_bf16 v[120:123], v[152:155], v[160:163], v[120:123]
	v_mfma_f32_16x16x32_bf16 v[116:119], v[144:147], v[168:171], v[116:119]
	v_mfma_f32_16x16x32_bf16 v[112:115], v[152:155], v[168:171], v[112:115]
	v_mfma_f32_16x16x32_bf16 v[108:111], v[144:147], v[176:179], v[108:111]
	v_mfma_f32_16x16x32_bf16 v[104:107], v[148:151], v[172:175], v[104:107]
	v_mfma_f32_16x16x32_bf16 v[100:103], v[144:147], v[184:187], v[100:103]
	v_mfma_f32_16x16x32_bf16 v[96:99], v[152:155], v[184:187], v[96:99]
	v_mfma_f32_16x16x32_bf16 v[128:131], v[152:155], v[176:179], v[104:107]
	s_setprio 0
	s_barrier
	s_nop 2
	ds_read_b128 v[104:107], v139
	ds_read_b128 v[188:191], v139 offset:1024
	ds_read_b128 v[192:195], v139 offset:2048
	ds_read_b128 v[202:205], v139 offset:3072
	s_barrier
	s_waitcnt lgkmcnt(0)
	s_setprio 1
	s_waitcnt lgkmcnt(0)
	v_mfma_f32_16x16x32_bf16 v[92:95], v[104:107], v[156:159], v[92:95]
	v_mfma_f32_16x16x32_bf16 v[84:87], v[104:107], v[164:167], v[84:87]
	v_mfma_f32_16x16x32_bf16 v[76:79], v[104:107], v[172:175], v[76:79]
	v_mfma_f32_16x16x32_bf16 v[68:71], v[104:107], v[180:183], v[68:71]
	v_mfma_f32_16x16x32_bf16 v[64:67], v[192:195], v[180:183], v[64:67]
	v_mfma_f32_16x16x32_bf16 v[92:95], v[188:191], v[160:163], v[92:95]
	v_mfma_f32_16x16x32_bf16 v[88:91], v[192:195], v[156:159], v[88:91]
	v_mfma_f32_16x16x32_bf16 v[84:87], v[188:191], v[168:171], v[84:87]
	v_mfma_f32_16x16x32_bf16 v[80:83], v[192:195], v[164:167], v[80:83]
	v_mfma_f32_16x16x32_bf16 v[76:79], v[188:191], v[176:179], v[76:79]
	v_mfma_f32_16x16x32_bf16 v[72:75], v[192:195], v[172:175], v[72:75]
	v_mfma_f32_16x16x32_bf16 v[68:71], v[188:191], v[184:187], v[68:71]
	v_mfma_f32_16x16x32_bf16 v[64:67], v[202:205], v[184:187], v[64:67]
	v_mfma_f32_16x16x32_bf16 v[156:159], v[202:205], v[160:163], v[88:91]
	v_mfma_f32_16x16x32_bf16 v[160:163], v[202:205], v[168:171], v[80:83]
	v_mfma_f32_16x16x32_bf16 v[164:167], v[202:205], v[176:179], v[72:75]
	s_setprio 0
	s_barrier
	s_nop 0
	ds_read_b128 v[72:75], v136 offset:16384
	ds_read_b128 v[80:83], v136 offset:17408
	ds_read_b128 v[88:91], v135 offset:16384
	ds_read_b128 v[168:171], v135 offset:17408
	ds_read_b128 v[172:175], v134 offset:16384
	ds_read_b128 v[176:179], v134 offset:17408
	ds_read_b128 v[180:183], v133 offset:16384
	ds_read_b128 v[184:187], v133 offset:17408
	s_waitcnt vmcnt(4)
	s_barrier
	s_waitcnt lgkmcnt(0)
	s_setprio 1
	s_waitcnt lgkmcnt(0)
	v_mfma_f32_16x16x32_bf16 v[60:63], v[140:143], v[72:75], v[60:63]
	v_mfma_f32_16x16x32_bf16 v[56:59], v[148:151], v[72:75], v[56:59]
	v_mfma_f32_16x16x32_bf16 v[48:51], v[148:151], v[88:91], v[48:51]
	v_mfma_f32_16x16x32_bf16 v[32:35], v[148:151], v[180:183], v[32:35]
	v_mfma_f32_16x16x32_bf16 v[60:63], v[144:147], v[80:83], v[60:63]
	v_mfma_f32_16x16x32_bf16 v[56:59], v[152:155], v[80:83], v[56:59]
	v_mfma_f32_16x16x32_bf16 v[52:55], v[140:143], v[88:91], v[52:55]
	v_mfma_f32_16x16x32_bf16 v[48:51], v[152:155], v[168:171], v[48:51]
	v_mfma_f32_16x16x32_bf16 v[44:47], v[140:143], v[172:175], v[44:47]
	v_mfma_f32_16x16x32_bf16 v[40:43], v[148:151], v[172:175], v[40:43]
	v_mfma_f32_16x16x32_bf16 v[36:39], v[140:143], v[180:183], v[36:39]
	v_mfma_f32_16x16x32_bf16 v[32:35], v[152:155], v[184:187], v[32:35]
	v_mfma_f32_16x16x32_bf16 v[206:209], v[144:147], v[168:171], v[52:55]
	v_mfma_f32_16x16x32_bf16 v[210:213], v[144:147], v[176:179], v[44:47]
	v_mfma_f32_16x16x32_bf16 v[214:217], v[152:155], v[176:179], v[40:43]
	v_mfma_f32_16x16x32_bf16 v[140:143], v[144:147], v[184:187], v[36:39]
	s_setprio 0
	s_setprio 1
	v_mfma_f32_16x16x32_bf16 v[24:27], v[192:195], v[72:75], v[24:27]
	v_mfma_f32_16x16x32_bf16 v[20:23], v[104:107], v[88:91], v[20:23]
	v_mfma_f32_16x16x32_bf16 v[28:31], v[104:107], v[72:75], v[28:31]
	v_mfma_f32_16x16x32_bf16 v[24:27], v[202:205], v[80:83], v[24:27]
	v_mfma_f32_16x16x32_bf16 v[20:23], v[188:191], v[168:171], v[20:23]
	v_mfma_f32_16x16x32_bf16 v[16:19], v[192:195], v[88:91], v[16:19]
	v_mfma_f32_16x16x32_bf16 v[12:15], v[104:107], v[172:175], v[12:15]
	v_mfma_f32_16x16x32_bf16 v[8:11], v[192:195], v[172:175], v[8:11]
	v_mfma_f32_16x16x32_bf16 v[4:7], v[104:107], v[180:183], v[4:7]
	v_mfma_f32_16x16x32_bf16 v[0:3], v[192:195], v[180:183], v[0:3]
	v_mfma_f32_16x16x32_bf16 v[144:147], v[188:191], v[80:83], v[28:31]
	v_mfma_f32_16x16x32_bf16 v[148:151], v[202:205], v[168:171], v[16:19]
	v_mfma_f32_16x16x32_bf16 v[152:155], v[188:191], v[176:179], v[12:15]
	v_mfma_f32_16x16x32_bf16 v[168:171], v[202:205], v[176:179], v[8:11]
	v_mfma_f32_16x16x32_bf16 v[172:175], v[188:191], v[184:187], v[4:7]
	v_mfma_f32_16x16x32_bf16 v[176:179], v[202:205], v[184:187], v[0:3]
	s_setprio 0
	s_barrier
	ds_read_b128 v[16:19], v138
	ds_read_b128 v[180:183], v138 offset:1024
	ds_read_b128 v[184:187], v138 offset:2048
	ds_read_b128 v[188:191], v138 offset:3072
	ds_read_b128 v[0:3], v136 offset:32768
	ds_read_b128 v[4:7], v136 offset:33792
	ds_read_b128 v[8:11], v135 offset:32768
	ds_read_b128 v[12:15], v135 offset:33792
	ds_read_b128 v[44:47], v134 offset:32768
	ds_read_b128 v[192:195], v134 offset:33792
	ds_read_b128 v[202:205], v133 offset:32768
	ds_read_b128 v[218:221], v133 offset:33792
	s_waitcnt vmcnt(2)
	s_barrier
	s_waitcnt lgkmcnt(0)
	s_setprio 1
	s_waitcnt lgkmcnt(0)
	v_mfma_f32_16x16x32_bf16 v[28:31], v[16:19], v[0:3], v[124:127]
	v_mfma_f32_16x16x32_bf16 v[52:55], v[180:183], v[4:7], v[28:31]
	v_mfma_f32_16x16x32_bf16 v[28:31], v[184:187], v[0:3], v[120:123]
	v_mfma_f32_16x16x32_bf16 v[104:107], v[188:191], v[4:7], v[28:31]
	v_mfma_f32_16x16x32_bf16 v[28:31], v[16:19], v[8:11], v[116:119]
	v_mfma_f32_16x16x32_bf16 v[72:75], v[180:183], v[12:15], v[28:31]
	v_mfma_f32_16x16x32_bf16 v[28:31], v[184:187], v[8:11], v[112:115]
	v_mfma_f32_16x16x32_bf16 v[116:119], v[188:191], v[12:15], v[28:31]
	v_mfma_f32_16x16x32_bf16 v[28:31], v[16:19], v[44:47], v[108:111]
	v_mfma_f32_16x16x32_bf16 v[80:83], v[180:183], v[192:195], v[28:31]
	v_mfma_f32_16x16x32_bf16 v[28:31], v[184:187], v[44:47], v[128:131]
	v_mfma_f32_16x16x32_bf16 v[108:111], v[188:191], v[192:195], v[28:31]
	v_mfma_f32_16x16x32_bf16 v[28:31], v[16:19], v[202:205], v[100:103]
	v_mfma_f32_16x16x32_bf16 v[88:91], v[180:183], v[218:221], v[28:31]
	v_mfma_f32_16x16x32_bf16 v[28:31], v[184:187], v[202:205], v[96:99]
	v_mfma_f32_16x16x32_bf16 v[96:99], v[188:191], v[218:221], v[28:31]
	s_setprio 0
	s_barrier
	ds_read_b128 v[128:131], v137
	ds_read_b128 v[222:225], v137 offset:1024
	ds_read_b128 v[228:231], v137 offset:2048
	ds_read_b128 v[232:235], v137 offset:3072
	s_waitcnt vmcnt(0)
	s_barrier
	s_waitcnt lgkmcnt(0)
	s_setprio 1
	s_waitcnt lgkmcnt(0)
	v_mfma_f32_16x16x32_bf16 v[28:31], v[128:131], v[0:3], v[92:95]
	v_mfma_f32_16x16x32_bf16 v[0:3], v[228:231], v[0:3], v[156:159]
	v_mfma_f32_16x16x32_bf16 v[28:31], v[222:225], v[4:7], v[28:31]
	v_mfma_f32_16x16x32_bf16 v[0:3], v[232:235], v[4:7], v[0:3]
	v_mfma_f32_16x16x32_bf16 v[4:7], v[128:131], v[8:11], v[84:87]
	v_mfma_f32_16x16x32_bf16 v[36:39], v[222:225], v[12:15], v[4:7]
	v_mfma_f32_16x16x32_bf16 v[4:7], v[228:231], v[8:11], v[160:163]
	v_mfma_f32_16x16x32_bf16 v[4:7], v[232:235], v[12:15], v[4:7]
	v_mfma_f32_16x16x32_bf16 v[8:11], v[128:131], v[44:47], v[76:79]
	v_mfma_f32_16x16x32_bf16 v[12:15], v[128:131], v[202:205], v[68:71]
	v_mfma_f32_16x16x32_bf16 v[40:43], v[222:225], v[192:195], v[8:11]
	v_mfma_f32_16x16x32_bf16 v[8:11], v[228:231], v[44:47], v[164:167]
	v_mfma_f32_16x16x32_bf16 v[44:47], v[222:225], v[218:221], v[12:15]
	v_mfma_f32_16x16x32_bf16 v[12:15], v[228:231], v[202:205], v[64:67]
	v_mfma_f32_16x16x32_bf16 v[8:11], v[232:235], v[192:195], v[8:11]
	v_mfma_f32_16x16x32_bf16 v[12:15], v[232:235], v[218:221], v[12:15]
	s_setprio 0
	s_barrier
	ds_read_b128 v[64:67], v136 offset:49152
	ds_read_b128 v[136:139], v136 offset:50176
	ds_read_b128 v[156:159], v135 offset:49152
	ds_read_b128 v[160:163], v135 offset:50176
	ds_read_b128 v[164:167], v134 offset:49152
	ds_read_b128 v[192:195], v134 offset:50176
	ds_read_b128 v[202:205], v133 offset:49152
	ds_read_b128 v[218:221], v133 offset:50176
	s_barrier
	s_waitcnt lgkmcnt(0)
	s_setprio 1
	s_waitcnt lgkmcnt(0)
	v_mfma_f32_16x16x32_bf16 v[56:59], v[184:187], v[64:67], v[56:59]
	v_mfma_f32_16x16x32_bf16 v[48:51], v[184:187], v[156:159], v[48:51]
	v_mfma_f32_16x16x32_bf16 v[60:63], v[16:19], v[64:67], v[60:63]
	v_mfma_f32_16x16x32_bf16 v[92:95], v[188:191], v[136:139], v[56:59]
	v_mfma_f32_16x16x32_bf16 v[56:59], v[16:19], v[156:159], v[206:209]
	v_mfma_f32_16x16x32_bf16 v[84:87], v[188:191], v[160:163], v[48:51]
	v_mfma_f32_16x16x32_bf16 v[48:51], v[16:19], v[164:167], v[210:213]
	v_mfma_f32_16x16x32_bf16 v[16:19], v[16:19], v[202:205], v[140:143]
	v_mfma_f32_16x16x32_bf16 v[120:123], v[180:183], v[192:195], v[48:51]
	v_mfma_f32_16x16x32_bf16 v[48:51], v[184:187], v[164:167], v[214:217]
	v_mfma_f32_16x16x32_bf16 v[124:127], v[180:183], v[218:221], v[16:19]
	v_mfma_f32_16x16x32_bf16 v[16:19], v[184:187], v[202:205], v[32:35]
	v_mfma_f32_16x16x32_bf16 v[100:103], v[180:183], v[136:139], v[60:63]
	v_mfma_f32_16x16x32_bf16 v[112:115], v[180:183], v[160:163], v[56:59]
	v_mfma_f32_16x16x32_bf16 v[76:79], v[188:191], v[192:195], v[48:51]
	v_mfma_f32_16x16x32_bf16 v[68:71], v[188:191], v[218:221], v[16:19]
	s_setprio 0
	s_setprio 1
	v_mfma_f32_16x16x32_bf16 v[16:19], v[128:131], v[64:67], v[144:147]
	v_mfma_f32_16x16x32_bf16 v[48:51], v[222:225], v[136:139], v[16:19]
	v_mfma_f32_16x16x32_bf16 v[16:19], v[228:231], v[64:67], v[24:27]
	v_mfma_f32_16x16x32_bf16 v[20:23], v[128:131], v[156:159], v[20:23]
	v_mfma_f32_16x16x32_bf16 v[24:27], v[128:131], v[164:167], v[152:155]
	v_mfma_f32_16x16x32_bf16 v[32:35], v[128:131], v[202:205], v[172:175]
	v_mfma_f32_16x16x32_bf16 v[56:59], v[222:225], v[160:163], v[20:23]
	v_mfma_f32_16x16x32_bf16 v[20:23], v[228:231], v[156:159], v[148:151]
	v_mfma_f32_16x16x32_bf16 v[60:63], v[222:225], v[192:195], v[24:27]
	v_mfma_f32_16x16x32_bf16 v[24:27], v[228:231], v[164:167], v[168:171]
	v_mfma_f32_16x16x32_bf16 v[64:67], v[222:225], v[218:221], v[32:35]
	v_mfma_f32_16x16x32_bf16 v[32:35], v[228:231], v[202:205], v[176:179]
	v_mfma_f32_16x16x32_bf16 v[16:19], v[232:235], v[136:139], v[16:19]
	v_mfma_f32_16x16x32_bf16 v[20:23], v[232:235], v[160:163], v[20:23]
	v_mfma_f32_16x16x32_bf16 v[24:27], v[232:235], v[192:195], v[24:27]
	v_mfma_f32_16x16x32_bf16 v[32:35], v[232:235], v[218:221], v[32:35]
	s_setprio 0
	s_movk_i32 s9, 0x100
	v_cmp_gt_u32_e32 vcc, s9, v132
	s_barrier
	s_and_saveexec_b64 s[28:29], vcc
	s_cbranch_execz .LBB0_212
	s_barrier
	s_branch .LBB0_212

.LBB0_314:
	ds_read_b128 v[172:175], v170
	ds_read_b128 v[176:179], v170 offset:1024
	ds_read_b128 v[180:183], v170 offset:2048
	ds_read_b128 v[184:187], v170 offset:3072
	s_add_u32 s8, s37, vcc_lo
	v_mov_b32_e32 v222, v161
	v_mov_b32_e32 v196, v160
	s_addc_u32 s9, s38, vcc_hi
	ds_read_b128 v[188:191], v166
	ds_read_b128 v[192:195], v166 offset:1024
	ds_read_b128 v[202:205], v165
	ds_read_b128 v[206:209], v165 offset:1024
	ds_read_b128 v[210:213], v163
	ds_read_b128 v[214:217], v163 offset:1024
	ds_read_b128 v[218:221], v162
	ds_read_b128 v[236:239], v162 offset:1024
	s_add_i32 s40, s34, 0xc000
	v_mov_b32_e32 v223, v197
	s_mov_b32 m0, s40
	s_add_i32 s41, s34, 0xe000
	s_add_u32 s98, s8, s94
	s_addc_u32 s99, s9, s95
	global_load_lds_dwordx4 v160, s[98:99]
	s_mov_b32 m0, s41
	s_nop 0
	global_load_lds_dwordx4 v161, s[98:99]
	s_waitcnt lgkmcnt(8)
	s_barrier
	s_waitcnt lgkmcnt(0)
	s_setprio 1
	s_waitcnt lgkmcnt(0)
	v_mfma_f32_16x16x32_bf16 v[44:47], v[172:175], v[188:191], v[44:47]
	v_mfma_f32_16x16x32_bf16 v[40:43], v[180:183], v[188:191], v[40:43]
	v_mfma_f32_16x16x32_bf16 v[60:63], v[172:175], v[202:205], v[60:63]
	v_mfma_f32_16x16x32_bf16 v[56:59], v[180:183], v[202:205], v[56:59]
	v_mfma_f32_16x16x32_bf16 v[76:79], v[172:175], v[210:213], v[76:79]
	v_mfma_f32_16x16x32_bf16 v[72:75], v[180:183], v[210:213], v[72:75]
	v_mfma_f32_16x16x32_bf16 v[92:95], v[172:175], v[218:221], v[92:95]
	v_mfma_f32_16x16x32_bf16 v[88:91], v[180:183], v[218:221], v[88:91]
	v_mfma_f32_16x16x32_bf16 v[44:47], v[176:179], v[192:195], v[44:47]
	v_mfma_f32_16x16x32_bf16 v[40:43], v[184:187], v[192:195], v[40:43]
	v_mfma_f32_16x16x32_bf16 v[60:63], v[176:179], v[206:209], v[60:63]
	v_mfma_f32_16x16x32_bf16 v[56:59], v[184:187], v[206:209], v[56:59]
	v_mfma_f32_16x16x32_bf16 v[76:79], v[176:179], v[214:217], v[76:79]
	v_mfma_f32_16x16x32_bf16 v[72:75], v[184:187], v[214:217], v[72:75]
	v_mfma_f32_16x16x32_bf16 v[92:95], v[176:179], v[236:239], v[92:95]
	v_mfma_f32_16x16x32_bf16 v[88:91], v[184:187], v[236:239], v[88:91]
	s_setprio 0
	s_barrier
	s_add_i32 s39, s39, 2
	s_add_u32 s28, s6, vcc_lo
	v_mov_b32_e32 v222, v161
	v_mov_b32_e32 v196, v160
	s_addc_u32 s29, s7, vcc_hi
	ds_read_b128 v[240:243], v169
	ds_read_b128 v[244:247], v169 offset:1024
	ds_read_b128 v[248:251], v169 offset:2048
	ds_read_b128 v[228:231], v169 offset:3072
	v_mov_b32_e32 v223, v197
	s_mov_b32 m0, s59
	s_add_u32 s98, s28, s0
	s_addc_u32 s99, s29, s1
	global_load_lds_dwordx4 v160, s[98:99]
	s_mov_b32 m0, s61
	s_nop 0
	global_load_lds_dwordx4 v161, s[98:99]
	s_barrier
	s_waitcnt lgkmcnt(0)
	s_setprio 1
	s_waitcnt lgkmcnt(0)
	v_mfma_f32_16x16x32_bf16 v[32:35], v[240:243], v[188:191], v[32:35]
	v_mfma_f32_16x16x32_bf16 v[36:39], v[248:251], v[188:191], v[36:39]
	v_mfma_f32_16x16x32_bf16 v[48:51], v[240:243], v[202:205], v[48:51]
	v_mfma_f32_16x16x32_bf16 v[52:55], v[248:251], v[202:205], v[52:55]
	v_mfma_f32_16x16x32_bf16 v[64:67], v[240:243], v[210:213], v[64:67]
	v_mfma_f32_16x16x32_bf16 v[68:71], v[248:251], v[210:213], v[68:71]
	v_mfma_f32_16x16x32_bf16 v[80:83], v[240:243], v[218:221], v[80:83]
	v_mfma_f32_16x16x32_bf16 v[84:87], v[248:251], v[218:221], v[84:87]
	v_mfma_f32_16x16x32_bf16 v[32:35], v[244:247], v[192:195], v[32:35]
	v_mfma_f32_16x16x32_bf16 v[36:39], v[228:231], v[192:195], v[36:39]
	v_mfma_f32_16x16x32_bf16 v[48:51], v[244:247], v[206:209], v[48:51]
	v_mfma_f32_16x16x32_bf16 v[52:55], v[228:231], v[206:209], v[52:55]
	v_mfma_f32_16x16x32_bf16 v[64:67], v[244:247], v[214:217], v[64:67]
	v_mfma_f32_16x16x32_bf16 v[68:71], v[228:231], v[214:217], v[68:71]
	v_mfma_f32_16x16x32_bf16 v[80:83], v[244:247], v[236:239], v[80:83]
	v_mfma_f32_16x16x32_bf16 v[84:87], v[228:231], v[236:239], v[84:87]
	s_setprio 0
	s_add_u32 s92, s90, vcc_lo
	v_mov_b32_e32 v222, v161
	v_mov_b32_e32 v196, v160
	s_addc_u32 s93, s91, vcc_hi
	s_barrier
	ds_read_b128 v[188:191], v166 offset:16384
	ds_read_b128 v[192:195], v166 offset:17408
	ds_read_b128 v[202:205], v165 offset:16384
	ds_read_b128 v[206:209], v165 offset:17408
	ds_read_b128 v[210:213], v163 offset:16384
	ds_read_b128 v[214:217], v163 offset:17408
	ds_read_b128 v[218:221], v162 offset:16384
	ds_read_b128 v[236:239], v162 offset:17408
	v_mov_b32_e32 v223, v197
	s_mov_b32 m0, s34
	s_add_u32 s98, s92, s0
	s_addc_u32 s99, s93, s1
	global_load_lds_dwordx4 v160, s[98:99]
	s_mov_b32 m0, s79
	s_nop 0
	global_load_lds_dwordx4 v161, s[98:99]
	s_barrier
	s_waitcnt lgkmcnt(0)
	s_setprio 1
	s_waitcnt lgkmcnt(0)
	v_mfma_f32_16x16x32_bf16 v[108:111], v[172:175], v[188:191], v[108:111]
	v_mfma_f32_16x16x32_bf16 v[104:107], v[180:183], v[188:191], v[104:107]
	v_mfma_f32_16x16x32_bf16 v[124:127], v[172:175], v[202:205], v[124:127]
	v_mfma_f32_16x16x32_bf16 v[120:123], v[180:183], v[202:205], v[120:123]
	v_mfma_f32_16x16x32_bf16 v[140:143], v[172:175], v[210:213], v[140:143]
	v_mfma_f32_16x16x32_bf16 v[136:139], v[180:183], v[210:213], v[136:139]
	v_mfma_f32_16x16x32_bf16 v[156:159], v[172:175], v[218:221], v[156:159]
	v_mfma_f32_16x16x32_bf16 v[152:155], v[180:183], v[218:221], v[152:155]
	v_mfma_f32_16x16x32_bf16 v[108:111], v[176:179], v[192:195], v[108:111]
	v_mfma_f32_16x16x32_bf16 v[104:107], v[184:187], v[192:195], v[104:107]
	v_mfma_f32_16x16x32_bf16 v[124:127], v[176:179], v[206:209], v[124:127]
	v_mfma_f32_16x16x32_bf16 v[120:123], v[184:187], v[206:209], v[120:123]
	v_mfma_f32_16x16x32_bf16 v[140:143], v[176:179], v[214:217], v[140:143]
	v_mfma_f32_16x16x32_bf16 v[136:139], v[184:187], v[214:217], v[136:139]
	v_mfma_f32_16x16x32_bf16 v[156:159], v[176:179], v[236:239], v[156:159]
	v_mfma_f32_16x16x32_bf16 v[152:155], v[184:187], v[236:239], v[152:155]
	s_setprio 0
	s_barrier
	s_add_u32 s96, s82, vcc_lo
	v_mov_b32_e32 v172, v161
	v_mov_b32_e32 v196, v160
	s_addc_u32 s97, s36, vcc_hi
	v_mov_b32_e32 v173, v197
	s_mov_b32 m0, s52
	s_add_u32 s98, s96, s0
	s_addc_u32 s99, s97, s1
	global_load_lds_dwordx4 v160, s[98:99]
	s_mov_b32 m0, s53
	s_nop 0
	global_load_lds_dwordx4 v161, s[98:99]
	s_waitcnt vmcnt(6)
	s_barrier
	s_setprio 1
	v_mfma_f32_16x16x32_bf16 v[96:99], v[240:243], v[188:191], v[96:99]
	v_mfma_f32_16x16x32_bf16 v[100:103], v[248:251], v[188:191], v[100:103]
	v_mfma_f32_16x16x32_bf16 v[112:115], v[240:243], v[202:205], v[112:115]
	v_mfma_f32_16x16x32_bf16 v[116:119], v[248:251], v[202:205], v[116:119]
	v_mfma_f32_16x16x32_bf16 v[128:131], v[240:243], v[210:213], v[128:131]
	v_mfma_f32_16x16x32_bf16 v[132:135], v[248:251], v[210:213], v[132:135]
	v_mfma_f32_16x16x32_bf16 v[144:147], v[240:243], v[218:221], v[144:147]
	v_mfma_f32_16x16x32_bf16 v[148:151], v[248:251], v[218:221], v[148:151]
	v_mfma_f32_16x16x32_bf16 v[96:99], v[244:247], v[192:195], v[96:99]
	v_mfma_f32_16x16x32_bf16 v[100:103], v[228:231], v[192:195], v[100:103]
	v_mfma_f32_16x16x32_bf16 v[112:115], v[244:247], v[206:209], v[112:115]
	v_mfma_f32_16x16x32_bf16 v[116:119], v[228:231], v[206:209], v[116:119]
	v_mfma_f32_16x16x32_bf16 v[128:131], v[244:247], v[214:217], v[128:131]
	v_mfma_f32_16x16x32_bf16 v[132:135], v[228:231], v[214:217], v[132:135]
	v_mfma_f32_16x16x32_bf16 v[144:147], v[244:247], v[236:239], v[144:147]
	v_mfma_f32_16x16x32_bf16 v[148:151], v[228:231], v[236:239], v[148:151]
	s_setprio 0
	s_barrier
	ds_read_b128 v[172:175], v168
	ds_read_b128 v[176:179], v168 offset:1024
	ds_read_b128 v[180:183], v168 offset:2048
	ds_read_b128 v[184:187], v168 offset:3072
	v_mov_b32_e32 v222, v161
	v_mov_b32_e32 v196, v160
	ds_read_b128 v[188:191], v166 offset:32768
	ds_read_b128 v[192:195], v166 offset:33792
	ds_read_b128 v[202:205], v165 offset:32768
	ds_read_b128 v[206:209], v165 offset:33792
	ds_read_b128 v[210:213], v163 offset:32768
	ds_read_b128 v[214:217], v163 offset:33792
	ds_read_b128 v[218:221], v162 offset:32768
	ds_read_b128 v[228:231], v162 offset:33792
	v_mov_b32_e32 v223, v197
	s_mov_b32 m0, s68
	s_add_u32 s98, s8, s0
	s_addc_u32 s99, s9, s1
	global_load_lds_dwordx4 v160, s[98:99]
	s_mov_b32 m0, s69
	s_nop 0
	global_load_lds_dwordx4 v161, s[98:99]
	s_waitcnt lgkmcnt(8)
	s_barrier
	s_waitcnt lgkmcnt(0)
	s_setprio 1
	s_waitcnt lgkmcnt(0)
	v_mfma_f32_16x16x32_bf16 v[44:47], v[172:175], v[188:191], v[44:47]
	v_mfma_f32_16x16x32_bf16 v[40:43], v[180:183], v[188:191], v[40:43]
	v_mfma_f32_16x16x32_bf16 v[60:63], v[172:175], v[202:205], v[60:63]
	v_mfma_f32_16x16x32_bf16 v[56:59], v[180:183], v[202:205], v[56:59]
	v_mfma_f32_16x16x32_bf16 v[76:79], v[172:175], v[210:213], v[76:79]
	v_mfma_f32_16x16x32_bf16 v[72:75], v[180:183], v[210:213], v[72:75]
	v_mfma_f32_16x16x32_bf16 v[92:95], v[172:175], v[218:221], v[92:95]
	v_mfma_f32_16x16x32_bf16 v[88:91], v[180:183], v[218:221], v[88:91]
	v_mfma_f32_16x16x32_bf16 v[44:47], v[176:179], v[192:195], v[44:47]
	v_mfma_f32_16x16x32_bf16 v[40:43], v[184:187], v[192:195], v[40:43]
	v_mfma_f32_16x16x32_bf16 v[60:63], v[176:179], v[206:209], v[60:63]
	v_mfma_f32_16x16x32_bf16 v[56:59], v[184:187], v[206:209], v[56:59]
	v_mfma_f32_16x16x32_bf16 v[76:79], v[176:179], v[214:217], v[76:79]
	v_mfma_f32_16x16x32_bf16 v[72:75], v[184:187], v[214:217], v[72:75]
	v_mfma_f32_16x16x32_bf16 v[92:95], v[176:179], v[228:231], v[92:95]
	v_mfma_f32_16x16x32_bf16 v[88:91], v[184:187], v[228:231], v[88:91]
	s_setprio 0
	s_barrier
	v_mov_b32_e32 v222, v161
	v_mov_b32_e32 v196, v160
	ds_read_b128 v[236:239], v167
	ds_read_b128 v[240:243], v167 offset:1024
	ds_read_b128 v[244:247], v167 offset:2048
	ds_read_b128 v[248:251], v167 offset:3072
	v_mov_b32_e32 v223, v197
	s_mov_b32 m0, s70
	s_add_u32 s98, s28, s30
	s_addc_u32 s99, s29, s31
	global_load_lds_dwordx4 v160, s[98:99]
	s_mov_b32 m0, s71
	s_nop 0
	global_load_lds_dwordx4 v161, s[98:99]
	s_barrier
	s_waitcnt lgkmcnt(0)
	s_setprio 1
	s_waitcnt lgkmcnt(0)
	v_mfma_f32_16x16x32_bf16 v[32:35], v[236:239], v[188:191], v[32:35]
	v_mfma_f32_16x16x32_bf16 v[36:39], v[244:247], v[188:191], v[36:39]
	v_mfma_f32_16x16x32_bf16 v[48:51], v[236:239], v[202:205], v[48:51]
	v_mfma_f32_16x16x32_bf16 v[52:55], v[244:247], v[202:205], v[52:55]
	v_mfma_f32_16x16x32_bf16 v[64:67], v[236:239], v[210:213], v[64:67]
	v_mfma_f32_16x16x32_bf16 v[68:71], v[244:247], v[210:213], v[68:71]
	v_mfma_f32_16x16x32_bf16 v[80:83], v[236:239], v[218:221], v[80:83]
	v_mfma_f32_16x16x32_bf16 v[84:87], v[244:247], v[218:221], v[84:87]
	v_mfma_f32_16x16x32_bf16 v[32:35], v[240:243], v[192:195], v[32:35]
	v_mfma_f32_16x16x32_bf16 v[36:39], v[248:251], v[192:195], v[36:39]
	v_mfma_f32_16x16x32_bf16 v[48:51], v[240:243], v[206:209], v[48:51]
	v_mfma_f32_16x16x32_bf16 v[52:55], v[248:251], v[206:209], v[52:55]
	v_mfma_f32_16x16x32_bf16 v[64:67], v[240:243], v[214:217], v[64:67]
	v_mfma_f32_16x16x32_bf16 v[68:71], v[248:251], v[214:217], v[68:71]
	v_mfma_f32_16x16x32_bf16 v[80:83], v[240:243], v[228:231], v[80:83]
	v_mfma_f32_16x16x32_bf16 v[84:87], v[248:251], v[228:231], v[84:87]
	s_setprio 0
	v_mov_b32_e32 v222, v161
	v_mov_b32_e32 v196, v160
	s_barrier
	ds_read_b128 v[188:191], v166 offset:49152
	ds_read_b128 v[192:195], v166 offset:50176
	ds_read_b128 v[202:205], v165 offset:49152
	ds_read_b128 v[206:209], v165 offset:50176
	ds_read_b128 v[210:213], v163 offset:49152
	ds_read_b128 v[214:217], v163 offset:50176
	ds_read_b128 v[218:221], v162 offset:49152
	ds_read_b128 v[228:231], v162 offset:50176
	v_mov_b32_e32 v223, v197
	s_mov_b32 m0, s72
	s_add_u32 s98, s92, s30
	s_addc_u32 s99, s93, s31
	global_load_lds_dwordx4 v160, s[98:99]
	s_mov_b32 m0, s73
	s_nop 0
	global_load_lds_dwordx4 v161, s[98:99]
	s_barrier
	s_waitcnt lgkmcnt(0)
	s_setprio 1
	s_waitcnt lgkmcnt(0)
	v_mfma_f32_16x16x32_bf16 v[108:111], v[172:175], v[188:191], v[108:111]
	v_mfma_f32_16x16x32_bf16 v[104:107], v[180:183], v[188:191], v[104:107]
	v_mfma_f32_16x16x32_bf16 v[124:127], v[172:175], v[202:205], v[124:127]
	v_mfma_f32_16x16x32_bf16 v[120:123], v[180:183], v[202:205], v[120:123]
	v_mfma_f32_16x16x32_bf16 v[140:143], v[172:175], v[210:213], v[140:143]
	v_mfma_f32_16x16x32_bf16 v[136:139], v[180:183], v[210:213], v[136:139]
	v_mfma_f32_16x16x32_bf16 v[156:159], v[172:175], v[218:221], v[156:159]
	v_mfma_f32_16x16x32_bf16 v[152:155], v[180:183], v[218:221], v[152:155]
	v_mfma_f32_16x16x32_bf16 v[108:111], v[176:179], v[192:195], v[108:111]
	v_mfma_f32_16x16x32_bf16 v[104:107], v[184:187], v[192:195], v[104:107]
	v_mfma_f32_16x16x32_bf16 v[124:127], v[176:179], v[206:209], v[124:127]
	v_mfma_f32_16x16x32_bf16 v[120:123], v[184:187], v[206:209], v[120:123]
	v_mfma_f32_16x16x32_bf16 v[140:143], v[176:179], v[214:217], v[140:143]
	v_mfma_f32_16x16x32_bf16 v[136:139], v[184:187], v[214:217], v[136:139]
	v_mfma_f32_16x16x32_bf16 v[156:159], v[176:179], v[228:231], v[156:159]
	v_mfma_f32_16x16x32_bf16 v[152:155], v[184:187], v[228:231], v[152:155]
	s_setprio 0
	s_barrier
	v_mov_b32_e32 v172, v161
	v_mov_b32_e32 v196, v160
	v_mov_b32_e32 v173, v197
	s_mov_b32 m0, s75
	s_add_u32 s98, s96, s30
	s_addc_u32 s99, s97, s31
	global_load_lds_dwordx4 v160, s[98:99]
	s_mov_b32 m0, s89
	s_nop 0
	global_load_lds_dwordx4 v161, s[98:99]
	s_waitcnt vmcnt(6)
	s_barrier
	s_setprio 1
	v_mfma_f32_16x16x32_bf16 v[96:99], v[236:239], v[188:191], v[96:99]
	v_mfma_f32_16x16x32_bf16 v[100:103], v[244:247], v[188:191], v[100:103]
	v_mfma_f32_16x16x32_bf16 v[112:115], v[236:239], v[202:205], v[112:115]
	v_mfma_f32_16x16x32_bf16 v[116:119], v[244:247], v[202:205], v[116:119]
	v_mfma_f32_16x16x32_bf16 v[128:131], v[236:239], v[210:213], v[128:131]
	v_mfma_f32_16x16x32_bf16 v[132:135], v[244:247], v[210:213], v[132:135]
	v_mfma_f32_16x16x32_bf16 v[144:147], v[236:239], v[218:221], v[144:147]
	v_mfma_f32_16x16x32_bf16 v[148:151], v[244:247], v[218:221], v[148:151]
	v_mfma_f32_16x16x32_bf16 v[96:99], v[240:243], v[192:195], v[96:99]
	v_mfma_f32_16x16x32_bf16 v[100:103], v[248:251], v[192:195], v[100:103]
	v_mfma_f32_16x16x32_bf16 v[112:115], v[240:243], v[206:209], v[112:115]
	v_mfma_f32_16x16x32_bf16 v[116:119], v[248:251], v[206:209], v[116:119]
	v_mfma_f32_16x16x32_bf16 v[128:131], v[240:243], v[214:217], v[128:131]
	v_mfma_f32_16x16x32_bf16 v[132:135], v[248:251], v[214:217], v[132:135]
	v_mfma_f32_16x16x32_bf16 v[144:147], v[240:243], v[228:231], v[144:147]
	v_mfma_f32_16x16x32_bf16 v[148:151], v[248:251], v[228:231], v[148:151]
	s_setprio 0
	s_add_u32 vcc_lo, vcc_lo, 0x100
	s_addc_u32 vcc_hi, vcc_hi, 0
	s_cmp_lt_u32 s39, s74
	s_barrier
	s_cbranch_scc1 .LBB0_314
	s_add_i32 s34, s33, -1
	s_lshl_b64 s[6:7], s[34:35], 7
	s_add_u32 s6, s84, s6
	s_addc_u32 s7, s85, s7
	s_mov_b32 m0, s40
	ds_read_b128 v[172:175], v170
	ds_read_b128 v[176:179], v170 offset:1024
	ds_read_b128 v[180:183], v170 offset:2048
	ds_read_b128 v[184:187], v170 offset:3072
	ds_read_b128 v[188:191], v166
	ds_read_b128 v[192:195], v166 offset:1024
	ds_read_b128 v[202:205], v165
	ds_read_b128 v[206:209], v165 offset:1024
	ds_read_b128 v[210:213], v163
	ds_read_b128 v[214:217], v163 offset:1024
	ds_read_b128 v[218:221], v162
	ds_read_b128 v[228:231], v162 offset:1024
	s_nop 0
	global_load_lds_dwordx4 v160, s[6:7]
	s_mov_b32 m0, s41
	s_nop 0
	global_load_lds_dwordx4 v161, s[6:7]
	s_barrier
	s_waitcnt lgkmcnt(0)
	s_setprio 1
	s_waitcnt lgkmcnt(0)
	v_mfma_f32_16x16x32_bf16 v[40:43], v[180:183], v[188:191], v[40:43]
	v_mfma_f32_16x16x32_bf16 v[56:59], v[180:183], v[202:205], v[56:59]
	v_mfma_f32_16x16x32_bf16 v[72:75], v[180:183], v[210:213], v[72:75]
	v_mfma_f32_16x16x32_bf16 v[92:95], v[172:175], v[218:221], v[92:95]
	v_mfma_f32_16x16x32_bf16 v[88:91], v[180:183], v[218:221], v[88:91]
	v_mfma_f32_16x16x32_bf16 v[44:47], v[172:175], v[188:191], v[44:47]
	v_mfma_f32_16x16x32_bf16 v[40:43], v[184:187], v[192:195], v[40:43]
	v_mfma_f32_16x16x32_bf16 v[60:63], v[172:175], v[202:205], v[60:63]
	v_mfma_f32_16x16x32_bf16 v[56:59], v[184:187], v[206:209], v[56:59]
	v_mfma_f32_16x16x32_bf16 v[76:79], v[172:175], v[210:213], v[76:79]
	v_mfma_f32_16x16x32_bf16 v[72:75], v[184:187], v[214:217], v[72:75]
	v_mfma_f32_16x16x32_bf16 v[92:95], v[176:179], v[228:231], v[92:95]
	v_mfma_f32_16x16x32_bf16 v[88:91], v[184:187], v[228:231], v[88:91]
	v_mfma_f32_16x16x32_bf16 v[44:47], v[176:179], v[192:195], v[44:47]
	v_mfma_f32_16x16x32_bf16 v[60:63], v[176:179], v[206:209], v[60:63]
	v_mfma_f32_16x16x32_bf16 v[76:79], v[176:179], v[214:217], v[76:79]
	s_setprio 0
	s_barrier
	ds_read_b128 v[236:239], v169
	ds_read_b128 v[240:243], v169 offset:1024
	ds_read_b128 v[244:247], v169 offset:2048
	ds_read_b128 v[248:251], v169 offset:3072
	s_barrier
	s_waitcnt lgkmcnt(0)
	s_setprio 1
	s_waitcnt lgkmcnt(0)
	v_mfma_f32_16x16x32_bf16 v[36:39], v[244:247], v[188:191], v[36:39]
	v_mfma_f32_16x16x32_bf16 v[32:35], v[236:239], v[188:191], v[32:35]
	v_mfma_f32_16x16x32_bf16 v[188:191], v[248:251], v[192:195], v[36:39]
	v_mfma_f32_16x16x32_bf16 v[36:39], v[236:239], v[202:205], v[48:51]
	v_mfma_f32_16x16x32_bf16 v[48:51], v[240:243], v[206:209], v[36:39]
	v_mfma_f32_16x16x32_bf16 v[36:39], v[244:247], v[202:205], v[52:55]
	v_mfma_f32_16x16x32_bf16 v[32:35], v[240:243], v[192:195], v[32:35]
	v_mfma_f32_16x16x32_bf16 v[192:195], v[248:251], v[206:209], v[36:39]
	v_mfma_f32_16x16x32_bf16 v[36:39], v[236:239], v[210:213], v[64:67]
	v_mfma_f32_16x16x32_bf16 v[64:67], v[240:243], v[214:217], v[36:39]
	v_mfma_f32_16x16x32_bf16 v[36:39], v[244:247], v[210:213], v[68:71]
	v_mfma_f32_16x16x32_bf16 v[202:205], v[248:251], v[214:217], v[36:39]
	v_mfma_f32_16x16x32_bf16 v[36:39], v[236:239], v[218:221], v[80:83]
	v_mfma_f32_16x16x32_bf16 v[80:83], v[240:243], v[228:231], v[36:39]
	v_mfma_f32_16x16x32_bf16 v[36:39], v[244:247], v[218:221], v[84:87]
	v_mfma_f32_16x16x32_bf16 v[206:209], v[248:251], v[228:231], v[36:39]
	s_setprio 0
	s_barrier
	s_nop 4
	ds_read_b128 v[36:39], v166 offset:16384
	ds_read_b128 v[52:55], v166 offset:17408
	ds_read_b128 v[68:71], v165 offset:16384
	ds_read_b128 v[84:87], v165 offset:17408
	ds_read_b128 v[210:213], v163 offset:16384
	ds_read_b128 v[214:217], v163 offset:17408
	ds_read_b128 v[218:221], v162 offset:16384
	ds_read_b128 v[228:231], v162 offset:17408
	s_waitcnt vmcnt(4)
	s_barrier
	s_waitcnt lgkmcnt(0)
	s_setprio 1
	s_waitcnt lgkmcnt(0)
	v_mfma_f32_16x16x32_bf16 v[108:111], v[172:175], v[36:39], v[108:111]
	v_mfma_f32_16x16x32_bf16 v[222:225], v[176:179], v[52:55], v[108:111]
	v_mfma_f32_16x16x32_bf16 v[108:111], v[172:175], v[68:71], v[124:127]
	v_mfma_f32_16x16x32_bf16 v[124:127], v[176:179], v[84:87], v[108:111]
	v_mfma_f32_16x16x32_bf16 v[108:111], v[180:183], v[68:71], v[120:123]
	v_mfma_f32_16x16x32_bf16 v[120:123], v[184:187], v[84:87], v[108:111]
	v_mfma_f32_16x16x32_bf16 v[108:111], v[172:175], v[210:213], v[140:143]
	v_mfma_f32_16x16x32_bf16 v[140:143], v[176:179], v[214:217], v[108:111]
	v_mfma_f32_16x16x32_bf16 v[108:111], v[180:183], v[210:213], v[136:139]
	v_mfma_f32_16x16x32_bf16 v[136:139], v[184:187], v[214:217], v[108:111]
	v_mfma_f32_16x16x32_bf16 v[108:111], v[172:175], v[218:221], v[156:159]
	v_mfma_f32_16x16x32_bf16 v[104:107], v[180:183], v[36:39], v[104:107]
	v_mfma_f32_16x16x32_bf16 v[156:159], v[176:179], v[228:231], v[108:111]
	v_mfma_f32_16x16x32_bf16 v[108:111], v[180:183], v[218:221], v[152:155]
	v_mfma_f32_16x16x32_bf16 v[104:107], v[184:187], v[52:55], v[104:107]
	v_mfma_f32_16x16x32_bf16 v[152:155], v[184:187], v[228:231], v[108:111]
	s_setprio 0
	s_setprio 1
	v_mfma_f32_16x16x32_bf16 v[96:99], v[236:239], v[36:39], v[96:99]
	v_mfma_f32_16x16x32_bf16 v[36:39], v[244:247], v[36:39], v[100:103]
	v_mfma_f32_16x16x32_bf16 v[172:175], v[248:251], v[52:55], v[36:39]
	v_mfma_f32_16x16x32_bf16 v[36:39], v[236:239], v[68:71], v[112:115]
	v_mfma_f32_16x16x32_bf16 v[112:115], v[240:243], v[84:87], v[36:39]
	v_mfma_f32_16x16x32_bf16 v[36:39], v[244:247], v[68:71], v[116:119]
	v_mfma_f32_16x16x32_bf16 v[180:183], v[248:251], v[84:87], v[36:39]
	v_mfma_f32_16x16x32_bf16 v[36:39], v[236:239], v[210:213], v[128:131]
	v_mfma_f32_16x16x32_bf16 v[128:131], v[240:243], v[214:217], v[36:39]
	v_mfma_f32_16x16x32_bf16 v[36:39], v[244:247], v[210:213], v[132:135]
	v_mfma_f32_16x16x32_bf16 v[184:187], v[248:251], v[214:217], v[36:39]
	v_mfma_f32_16x16x32_bf16 v[36:39], v[236:239], v[218:221], v[144:147]
	v_mfma_f32_16x16x32_bf16 v[96:99], v[240:243], v[52:55], v[96:99]
	v_mfma_f32_16x16x32_bf16 v[144:147], v[240:243], v[228:231], v[36:39]
	v_mfma_f32_16x16x32_bf16 v[36:39], v[244:247], v[218:221], v[148:151]
	v_mfma_f32_16x16x32_bf16 v[210:213], v[248:251], v[228:231], v[36:39]
	s_setprio 0
	s_barrier
	ds_read_b128 v[148:151], v168
	ds_read_b128 v[214:217], v168 offset:1024
	ds_read_b128 v[218:221], v168 offset:2048
	ds_read_b128 v[228:231], v168 offset:3072
	ds_read_b128 v[100:103], v166 offset:32768
	ds_read_b128 v[108:111], v166 offset:33792
	ds_read_b128 v[116:119], v165 offset:32768
	ds_read_b128 v[132:135], v165 offset:33792
	ds_read_b128 v[236:239], v163 offset:32768
	ds_read_b128 v[240:243], v163 offset:33792
	ds_read_b128 v[244:247], v162 offset:32768
	ds_read_b128 v[248:251], v162 offset:33792
	s_waitcnt vmcnt(2)
	s_barrier
	s_waitcnt lgkmcnt(0)
	s_setprio 1
	s_waitcnt lgkmcnt(0)
	v_mfma_f32_16x16x32_bf16 v[36:39], v[148:151], v[100:103], v[44:47]
	v_mfma_f32_16x16x32_bf16 v[44:47], v[148:151], v[116:119], v[60:63]
	v_mfma_f32_16x16x32_bf16 v[52:55], v[214:217], v[132:135], v[44:47]
	v_mfma_f32_16x16x32_bf16 v[44:47], v[218:221], v[116:119], v[56:59]
	v_mfma_f32_16x16x32_bf16 v[56:59], v[228:231], v[132:135], v[44:47]
	v_mfma_f32_16x16x32_bf16 v[44:47], v[148:151], v[236:239], v[76:79]
	v_mfma_f32_16x16x32_bf16 v[68:71], v[214:217], v[240:243], v[44:47]
	v_mfma_f32_16x16x32_bf16 v[44:47], v[218:221], v[236:239], v[72:75]
	v_mfma_f32_16x16x32_bf16 v[72:75], v[228:231], v[240:243], v[44:47]
	v_mfma_f32_16x16x32_bf16 v[44:47], v[148:151], v[244:247], v[92:95]
	v_mfma_f32_16x16x32_bf16 v[40:43], v[218:221], v[100:103], v[40:43]
	v_mfma_f32_16x16x32_bf16 v[84:87], v[214:217], v[248:251], v[44:47]
	v_mfma_f32_16x16x32_bf16 v[44:47], v[218:221], v[244:247], v[88:91]
	v_mfma_f32_16x16x32_bf16 v[36:39], v[214:217], v[108:111], v[36:39]
	v_mfma_f32_16x16x32_bf16 v[40:43], v[228:231], v[108:111], v[40:43]
	v_mfma_f32_16x16x32_bf16 v[88:91], v[228:231], v[248:251], v[44:47]
	s_setprio 0
	s_barrier
	s_nop 2
	ds_read_b128 v[44:47], v167
	ds_read_b128 v[60:63], v167 offset:1024
	ds_read_b128 v[76:79], v167 offset:2048
	ds_read_b128 v[232:235], v167 offset:3072
	s_waitcnt vmcnt(0)
	s_barrier
	s_waitcnt lgkmcnt(0)
	s_setprio 1
	s_waitcnt lgkmcnt(0)
	v_mfma_f32_16x16x32_bf16 v[92:95], v[76:79], v[100:103], v[188:191]
	v_mfma_f32_16x16x32_bf16 v[176:179], v[232:235], v[108:111], v[92:95]
	v_mfma_f32_16x16x32_bf16 v[92:95], v[76:79], v[116:119], v[192:195]
	v_mfma_f32_16x16x32_bf16 v[32:35], v[44:47], v[100:103], v[32:35]
	v_mfma_f32_16x16x32_bf16 v[48:51], v[44:47], v[116:119], v[48:51]
	v_mfma_f32_16x16x32_bf16 v[168:171], v[232:235], v[132:135], v[92:95]
	v_mfma_f32_16x16x32_bf16 v[64:67], v[44:47], v[236:239], v[64:67]
	v_mfma_f32_16x16x32_bf16 v[92:95], v[76:79], v[236:239], v[202:205]
	v_mfma_f32_16x16x32_bf16 v[80:83], v[44:47], v[244:247], v[80:83]
	v_mfma_f32_16x16x32_bf16 v[100:103], v[76:79], v[244:247], v[206:209]
	v_mfma_f32_16x16x32_bf16 v[32:35], v[60:63], v[108:111], v[32:35]
	v_mfma_f32_16x16x32_bf16 v[48:51], v[60:63], v[132:135], v[48:51]
	v_mfma_f32_16x16x32_bf16 v[64:67], v[60:63], v[240:243], v[64:67]
	v_mfma_f32_16x16x32_bf16 v[92:95], v[232:235], v[240:243], v[92:95]
	v_mfma_f32_16x16x32_bf16 v[80:83], v[60:63], v[248:251], v[80:83]
	v_mfma_f32_16x16x32_bf16 v[108:111], v[232:235], v[248:251], v[100:103]
	s_setprio 0
	s_barrier
	ds_read_b128 v[188:191], v166 offset:49152
	ds_read_b128 v[192:195], v166 offset:50176
	ds_read_b128 v[202:205], v165 offset:49152
	ds_read_b128 v[206:209], v165 offset:50176
	ds_read_b128 v[236:239], v163 offset:49152
	ds_read_b128 v[240:243], v163 offset:50176
	ds_read_b128 v[244:247], v162 offset:49152
	ds_read_b128 v[160:163], v162 offset:50176
	s_barrier
	s_waitcnt lgkmcnt(0)
	s_setprio 1
	s_waitcnt lgkmcnt(0)
	v_mfma_f32_16x16x32_bf16 v[116:119], v[148:151], v[202:205], v[124:127]
	v_mfma_f32_16x16x32_bf16 v[124:127], v[148:151], v[236:239], v[140:143]
	v_mfma_f32_16x16x32_bf16 v[132:135], v[214:217], v[240:243], v[124:127]
	v_mfma_f32_16x16x32_bf16 v[124:127], v[218:221], v[236:239], v[136:139]
	v_mfma_f32_16x16x32_bf16 v[136:139], v[228:231], v[240:243], v[124:127]
	v_mfma_f32_16x16x32_bf16 v[124:127], v[148:151], v[244:247], v[156:159]
	v_mfma_f32_16x16x32_bf16 v[100:103], v[148:151], v[188:191], v[222:225]
	v_mfma_f32_16x16x32_bf16 v[104:107], v[218:221], v[188:191], v[104:107]
	v_mfma_f32_16x16x32_bf16 v[120:123], v[218:221], v[202:205], v[120:123]
	v_mfma_f32_16x16x32_bf16 v[148:151], v[214:217], v[160:163], v[124:127]
	v_mfma_f32_16x16x32_bf16 v[124:127], v[218:221], v[244:247], v[152:155]
	v_mfma_f32_16x16x32_bf16 v[100:103], v[214:217], v[192:195], v[100:103]
	v_mfma_f32_16x16x32_bf16 v[104:107], v[228:231], v[192:195], v[104:107]
	v_mfma_f32_16x16x32_bf16 v[116:119], v[214:217], v[206:209], v[116:119]
	v_mfma_f32_16x16x32_bf16 v[120:123], v[228:231], v[206:209], v[120:123]
	v_mfma_f32_16x16x32_bf16 v[152:155], v[228:231], v[160:163], v[124:127]
	s_setprio 0
	s_setprio 1
	v_mfma_f32_16x16x32_bf16 v[96:99], v[44:47], v[188:191], v[96:99]
	v_mfma_f32_16x16x32_bf16 v[112:115], v[44:47], v[202:205], v[112:115]
	v_mfma_f32_16x16x32_bf16 v[128:131], v[44:47], v[236:239], v[128:131]
	v_mfma_f32_16x16x32_bf16 v[44:47], v[44:47], v[244:247], v[144:147]
	v_mfma_f32_16x16x32_bf16 v[124:127], v[76:79], v[188:191], v[172:175]
	v_mfma_f32_16x16x32_bf16 v[140:143], v[76:79], v[202:205], v[180:183]
	v_mfma_f32_16x16x32_bf16 v[156:159], v[76:79], v[236:239], v[184:187]
	v_mfma_f32_16x16x32_bf16 v[144:147], v[60:63], v[160:163], v[44:47]
	v_mfma_f32_16x16x32_bf16 v[44:47], v[76:79], v[244:247], v[210:213]
	v_mfma_f32_16x16x32_bf16 v[96:99], v[60:63], v[192:195], v[96:99]
	v_mfma_f32_16x16x32_bf16 v[124:127], v[232:235], v[192:195], v[124:127]
	v_mfma_f32_16x16x32_bf16 v[112:115], v[60:63], v[206:209], v[112:115]
	v_mfma_f32_16x16x32_bf16 v[140:143], v[232:235], v[206:209], v[140:143]
	v_mfma_f32_16x16x32_bf16 v[128:131], v[60:63], v[240:243], v[128:131]
	v_mfma_f32_16x16x32_bf16 v[156:159], v[232:235], v[240:243], v[156:159]
	v_mfma_f32_16x16x32_bf16 v[160:163], v[232:235], v[160:163], v[44:47]
	s_setprio 0
	s_movk_i32 s6, 0x100
	v_cmp_gt_u32_e32 vcc, s6, v164
	s_barrier
	s_and_saveexec_b64 s[6:7], vcc
	s_cbranch_execz .LBB0_317
	s_barrier

.LBB0_568:
	ds_read_b128 v[140:143], v129
	ds_read_b128 v[144:147], v129 offset:1024
	ds_read_b128 v[148:151], v129 offset:2048
	ds_read_b128 v[152:155], v129 offset:3072
	s_add_u32 s28, s8, s10
	v_mov_b32_e32 v188, v130
	v_mov_b32_e32 v196, v128
	s_addc_u32 s29, s9, s11
	ds_read_b128 v[156:159], v136
	ds_read_b128 v[160:163], v136 offset:1024
	ds_read_b128 v[164:167], v135
	ds_read_b128 v[168:171], v135 offset:1024
	ds_read_b128 v[172:175], v134
	ds_read_b128 v[176:179], v134 offset:1024
	ds_read_b128 v[180:183], v133
	ds_read_b128 v[184:187], v133 offset:1024
	s_add_i32 s39, s68, 0xc000
	v_mov_b32_e32 v189, v197
	s_mov_b32 m0, s39
	s_add_i32 s38, s68, 0xe000
	s_add_u32 s98, s28, s44
	s_addc_u32 s99, s29, s45
	global_load_lds_dwordx4 v128, s[98:99]
	s_mov_b32 m0, s38
	s_nop 0
	global_load_lds_dwordx4 v130, s[98:99]
	s_waitcnt lgkmcnt(8)
	s_barrier
	s_waitcnt lgkmcnt(0)
	s_setprio 1
	s_waitcnt lgkmcnt(0)
	v_mfma_f32_16x16x32_bf16 v[124:127], v[140:143], v[156:159], v[124:127]
	v_mfma_f32_16x16x32_bf16 v[120:123], v[148:151], v[156:159], v[120:123]
	v_mfma_f32_16x16x32_bf16 v[116:119], v[140:143], v[164:167], v[116:119]
	v_mfma_f32_16x16x32_bf16 v[112:115], v[148:151], v[164:167], v[112:115]
	v_mfma_f32_16x16x32_bf16 v[108:111], v[140:143], v[172:175], v[108:111]
	v_mfma_f32_16x16x32_bf16 v[104:107], v[148:151], v[172:175], v[104:107]
	v_mfma_f32_16x16x32_bf16 v[100:103], v[140:143], v[180:183], v[100:103]
	v_mfma_f32_16x16x32_bf16 v[96:99], v[148:151], v[180:183], v[96:99]
	v_mfma_f32_16x16x32_bf16 v[124:127], v[144:147], v[160:163], v[124:127]
	v_mfma_f32_16x16x32_bf16 v[120:123], v[152:155], v[160:163], v[120:123]
	v_mfma_f32_16x16x32_bf16 v[116:119], v[144:147], v[168:171], v[116:119]
	v_mfma_f32_16x16x32_bf16 v[112:115], v[152:155], v[168:171], v[112:115]
	v_mfma_f32_16x16x32_bf16 v[108:111], v[144:147], v[176:179], v[108:111]
	v_mfma_f32_16x16x32_bf16 v[104:107], v[152:155], v[176:179], v[104:107]
	v_mfma_f32_16x16x32_bf16 v[100:103], v[144:147], v[184:187], v[100:103]
	v_mfma_f32_16x16x32_bf16 v[96:99], v[152:155], v[184:187], v[96:99]
	s_setprio 0
	s_barrier
	s_add_u32 s56, s6, s10
	v_mov_b32_e32 v210, v130
	v_mov_b32_e32 v196, v128
	s_addc_u32 s57, s7, s11
	ds_read_b128 v[188:191], v139
	ds_read_b128 v[192:195], v139 offset:1024
	ds_read_b128 v[202:205], v139 offset:2048
	ds_read_b128 v[206:209], v139 offset:3072
	v_mov_b32_e32 v211, v197
	s_add_i32 m0, s68, 0x10000
	s_add_u32 s98, s56, s0
	s_addc_u32 s99, s57, s1
	global_load_lds_dwordx4 v128, s[98:99]
	s_add_i32 m0, s68, 0x12000
	s_nop 0
	global_load_lds_dwordx4 v130, s[98:99]
	s_barrier
	s_waitcnt lgkmcnt(0)
	s_setprio 1
	s_waitcnt lgkmcnt(0)
	v_mfma_f32_16x16x32_bf16 v[92:95], v[188:191], v[156:159], v[92:95]
	v_mfma_f32_16x16x32_bf16 v[88:91], v[202:205], v[156:159], v[88:91]
	v_mfma_f32_16x16x32_bf16 v[84:87], v[188:191], v[164:167], v[84:87]
	v_mfma_f32_16x16x32_bf16 v[80:83], v[202:205], v[164:167], v[80:83]
	v_mfma_f32_16x16x32_bf16 v[76:79], v[188:191], v[172:175], v[76:79]
	v_mfma_f32_16x16x32_bf16 v[72:75], v[202:205], v[172:175], v[72:75]
	v_mfma_f32_16x16x32_bf16 v[68:71], v[188:191], v[180:183], v[68:71]
	v_mfma_f32_16x16x32_bf16 v[64:67], v[202:205], v[180:183], v[64:67]
	v_mfma_f32_16x16x32_bf16 v[92:95], v[192:195], v[160:163], v[92:95]
	v_mfma_f32_16x16x32_bf16 v[88:91], v[206:209], v[160:163], v[88:91]
	v_mfma_f32_16x16x32_bf16 v[84:87], v[192:195], v[168:171], v[84:87]
	v_mfma_f32_16x16x32_bf16 v[80:83], v[206:209], v[168:171], v[80:83]
	v_mfma_f32_16x16x32_bf16 v[76:79], v[192:195], v[176:179], v[76:79]
	v_mfma_f32_16x16x32_bf16 v[72:75], v[206:209], v[176:179], v[72:75]
	v_mfma_f32_16x16x32_bf16 v[68:71], v[192:195], v[184:187], v[68:71]
	v_mfma_f32_16x16x32_bf16 v[64:67], v[206:209], v[184:187], v[64:67]
	s_setprio 0
	v_mov_b32_e32 v210, v130
	v_mov_b32_e32 v196, v128
	s_barrier
	ds_read_b128 v[156:159], v136 offset:16384
	ds_read_b128 v[160:163], v136 offset:17408
	ds_read_b128 v[164:167], v135 offset:16384
	ds_read_b128 v[168:171], v135 offset:17408
	ds_read_b128 v[172:175], v134 offset:16384
	ds_read_b128 v[176:179], v134 offset:17408
	ds_read_b128 v[180:183], v133 offset:16384
	ds_read_b128 v[184:187], v133 offset:17408
	v_mov_b32_e32 v211, v197
	s_mov_b32 m0, s68
	s_add_u32 s98, s28, s0
	s_addc_u32 s99, s29, s1
	global_load_lds_dwordx4 v128, s[98:99]
	s_add_i32 m0, s68, 0x2000
	s_nop 0
	global_load_lds_dwordx4 v130, s[98:99]
	s_barrier
	s_waitcnt lgkmcnt(0)
	s_setprio 1
	s_waitcnt lgkmcnt(0)
	v_mfma_f32_16x16x32_bf16 v[60:63], v[140:143], v[156:159], v[60:63]
	v_mfma_f32_16x16x32_bf16 v[56:59], v[148:151], v[156:159], v[56:59]
	v_mfma_f32_16x16x32_bf16 v[52:55], v[140:143], v[164:167], v[52:55]
	v_mfma_f32_16x16x32_bf16 v[48:51], v[148:151], v[164:167], v[48:51]
	v_mfma_f32_16x16x32_bf16 v[44:47], v[140:143], v[172:175], v[44:47]
	v_mfma_f32_16x16x32_bf16 v[40:43], v[148:151], v[172:175], v[40:43]
	v_mfma_f32_16x16x32_bf16 v[36:39], v[140:143], v[180:183], v[36:39]
	v_mfma_f32_16x16x32_bf16 v[32:35], v[148:151], v[180:183], v[32:35]
	v_mfma_f32_16x16x32_bf16 v[60:63], v[144:147], v[160:163], v[60:63]
	v_mfma_f32_16x16x32_bf16 v[56:59], v[152:155], v[160:163], v[56:59]
	v_mfma_f32_16x16x32_bf16 v[52:55], v[144:147], v[168:171], v[52:55]
	v_mfma_f32_16x16x32_bf16 v[48:51], v[152:155], v[168:171], v[48:51]
	v_mfma_f32_16x16x32_bf16 v[44:47], v[144:147], v[176:179], v[44:47]
	v_mfma_f32_16x16x32_bf16 v[40:43], v[152:155], v[176:179], v[40:43]
	v_mfma_f32_16x16x32_bf16 v[36:39], v[144:147], v[184:187], v[36:39]
	v_mfma_f32_16x16x32_bf16 v[32:35], v[152:155], v[184:187], v[32:35]
	s_setprio 0
	s_barrier
	v_mov_b32_e32 v140, v130
	v_mov_b32_e32 v196, v128
	v_mov_b32_e32 v141, v197
	s_add_i32 m0, s68, 0x14000
	s_add_u32 s98, s56, s46
	s_addc_u32 s99, s57, s47
	global_load_lds_dwordx4 v128, s[98:99]
	s_add_i32 m0, s68, 0x16000
	s_nop 0
	global_load_lds_dwordx4 v130, s[98:99]
	s_waitcnt vmcnt(6)
	s_barrier
	s_setprio 1
	v_mfma_f32_16x16x32_bf16 v[28:31], v[188:191], v[156:159], v[28:31]
	v_mfma_f32_16x16x32_bf16 v[24:27], v[202:205], v[156:159], v[24:27]
	v_mfma_f32_16x16x32_bf16 v[20:23], v[188:191], v[164:167], v[20:23]
	v_mfma_f32_16x16x32_bf16 v[16:19], v[202:205], v[164:167], v[16:19]
	v_mfma_f32_16x16x32_bf16 v[12:15], v[188:191], v[172:175], v[12:15]
	v_mfma_f32_16x16x32_bf16 v[8:11], v[202:205], v[172:175], v[8:11]
	v_mfma_f32_16x16x32_bf16 v[4:7], v[188:191], v[180:183], v[4:7]
	v_mfma_f32_16x16x32_bf16 v[0:3], v[202:205], v[180:183], v[0:3]
	v_mfma_f32_16x16x32_bf16 v[28:31], v[192:195], v[160:163], v[28:31]
	v_mfma_f32_16x16x32_bf16 v[24:27], v[206:209], v[160:163], v[24:27]
	v_mfma_f32_16x16x32_bf16 v[20:23], v[192:195], v[168:171], v[20:23]
	v_mfma_f32_16x16x32_bf16 v[16:19], v[206:209], v[168:171], v[16:19]
	v_mfma_f32_16x16x32_bf16 v[12:15], v[192:195], v[176:179], v[12:15]
	v_mfma_f32_16x16x32_bf16 v[8:11], v[206:209], v[176:179], v[8:11]
	v_mfma_f32_16x16x32_bf16 v[4:7], v[192:195], v[184:187], v[4:7]
	v_mfma_f32_16x16x32_bf16 v[0:3], v[206:209], v[184:187], v[0:3]
	s_setprio 0
	s_barrier
	ds_read_b128 v[140:143], v138
	ds_read_b128 v[144:147], v138 offset:1024
	ds_read_b128 v[148:151], v138 offset:2048
	ds_read_b128 v[152:155], v138 offset:3072
	v_mov_b32_e32 v188, v130
	v_mov_b32_e32 v196, v128
	ds_read_b128 v[156:159], v136 offset:32768
	ds_read_b128 v[160:163], v136 offset:33792
	ds_read_b128 v[164:167], v135 offset:32768
	ds_read_b128 v[168:171], v135 offset:33792
	ds_read_b128 v[172:175], v134 offset:32768
	ds_read_b128 v[176:179], v134 offset:33792
	ds_read_b128 v[180:183], v133 offset:32768
	ds_read_b128 v[184:187], v133 offset:33792
	v_mov_b32_e32 v189, v197
	s_add_i32 m0, s68, 0x4000
	s_add_u32 s98, s28, s46
	s_addc_u32 s99, s29, s47
	global_load_lds_dwordx4 v128, s[98:99]
	s_add_i32 m0, s68, 0x6000
	s_nop 0
	global_load_lds_dwordx4 v130, s[98:99]
	s_waitcnt lgkmcnt(8)
	s_barrier
	s_waitcnt lgkmcnt(0)
	s_setprio 1
	s_waitcnt lgkmcnt(0)
	v_mfma_f32_16x16x32_bf16 v[124:127], v[140:143], v[156:159], v[124:127]
	v_mfma_f32_16x16x32_bf16 v[120:123], v[148:151], v[156:159], v[120:123]
	v_mfma_f32_16x16x32_bf16 v[116:119], v[140:143], v[164:167], v[116:119]
	v_mfma_f32_16x16x32_bf16 v[112:115], v[148:151], v[164:167], v[112:115]
	v_mfma_f32_16x16x32_bf16 v[108:111], v[140:143], v[172:175], v[108:111]
	v_mfma_f32_16x16x32_bf16 v[104:107], v[148:151], v[172:175], v[104:107]
	v_mfma_f32_16x16x32_bf16 v[100:103], v[140:143], v[180:183], v[100:103]
	v_mfma_f32_16x16x32_bf16 v[96:99], v[148:151], v[180:183], v[96:99]
	v_mfma_f32_16x16x32_bf16 v[124:127], v[144:147], v[160:163], v[124:127]
	v_mfma_f32_16x16x32_bf16 v[120:123], v[152:155], v[160:163], v[120:123]
	v_mfma_f32_16x16x32_bf16 v[116:119], v[144:147], v[168:171], v[116:119]
	v_mfma_f32_16x16x32_bf16 v[112:115], v[152:155], v[168:171], v[112:115]
	v_mfma_f32_16x16x32_bf16 v[108:111], v[144:147], v[176:179], v[108:111]
	v_mfma_f32_16x16x32_bf16 v[104:107], v[152:155], v[176:179], v[104:107]
	v_mfma_f32_16x16x32_bf16 v[100:103], v[144:147], v[184:187], v[100:103]
	v_mfma_f32_16x16x32_bf16 v[96:99], v[152:155], v[184:187], v[96:99]
	s_setprio 0
	s_barrier
	v_mov_b32_e32 v210, v130
	v_mov_b32_e32 v196, v128
	ds_read_b128 v[188:191], v137
	ds_read_b128 v[192:195], v137 offset:1024
	ds_read_b128 v[202:205], v137 offset:2048
	ds_read_b128 v[206:209], v137 offset:3072
	v_mov_b32_e32 v211, v197
	s_mov_b32 m0, s69
	s_add_u32 s98, s56, s30
	s_addc_u32 s99, s57, s31
	global_load_lds_dwordx4 v128, s[98:99]
	s_mov_b32 m0, s70
	s_nop 0
	global_load_lds_dwordx4 v130, s[98:99]
	s_barrier
	s_waitcnt lgkmcnt(0)
	s_setprio 1
	s_waitcnt lgkmcnt(0)
	v_mfma_f32_16x16x32_bf16 v[92:95], v[188:191], v[156:159], v[92:95]
	v_mfma_f32_16x16x32_bf16 v[88:91], v[202:205], v[156:159], v[88:91]
	v_mfma_f32_16x16x32_bf16 v[84:87], v[188:191], v[164:167], v[84:87]
	v_mfma_f32_16x16x32_bf16 v[80:83], v[202:205], v[164:167], v[80:83]
	v_mfma_f32_16x16x32_bf16 v[76:79], v[188:191], v[172:175], v[76:79]
	v_mfma_f32_16x16x32_bf16 v[72:75], v[202:205], v[172:175], v[72:75]
	v_mfma_f32_16x16x32_bf16 v[68:71], v[188:191], v[180:183], v[68:71]
	v_mfma_f32_16x16x32_bf16 v[64:67], v[202:205], v[180:183], v[64:67]
	v_mfma_f32_16x16x32_bf16 v[92:95], v[192:195], v[160:163], v[92:95]
	v_mfma_f32_16x16x32_bf16 v[88:91], v[206:209], v[160:163], v[88:91]
	v_mfma_f32_16x16x32_bf16 v[84:87], v[192:195], v[168:171], v[84:87]
	v_mfma_f32_16x16x32_bf16 v[80:83], v[206:209], v[168:171], v[80:83]
	v_mfma_f32_16x16x32_bf16 v[76:79], v[192:195], v[176:179], v[76:79]
	v_mfma_f32_16x16x32_bf16 v[72:75], v[206:209], v[176:179], v[72:75]
	v_mfma_f32_16x16x32_bf16 v[68:71], v[192:195], v[184:187], v[68:71]
	v_mfma_f32_16x16x32_bf16 v[64:67], v[206:209], v[184:187], v[64:67]
	s_setprio 0
	v_mov_b32_e32 v210, v130
	v_mov_b32_e32 v196, v128
	s_barrier
	ds_read_b128 v[156:159], v136 offset:49152
	ds_read_b128 v[160:163], v136 offset:50176
	ds_read_b128 v[164:167], v135 offset:49152
	ds_read_b128 v[168:171], v135 offset:50176
	ds_read_b128 v[172:175], v134 offset:49152
	ds_read_b128 v[176:179], v134 offset:50176
	ds_read_b128 v[180:183], v133 offset:49152
	ds_read_b128 v[184:187], v133 offset:50176
	v_mov_b32_e32 v211, v197
	s_mov_b32 m0, s71
	s_add_u32 s98, s28, s30
	s_addc_u32 s99, s29, s31
	global_load_lds_dwordx4 v128, s[98:99]
	s_mov_b32 m0, s33
	s_nop 0
	global_load_lds_dwordx4 v130, s[98:99]
	s_barrier
	s_waitcnt lgkmcnt(0)
	s_setprio 1
	s_waitcnt lgkmcnt(0)
	v_mfma_f32_16x16x32_bf16 v[60:63], v[140:143], v[156:159], v[60:63]
	v_mfma_f32_16x16x32_bf16 v[56:59], v[148:151], v[156:159], v[56:59]
	v_mfma_f32_16x16x32_bf16 v[52:55], v[140:143], v[164:167], v[52:55]
	v_mfma_f32_16x16x32_bf16 v[48:51], v[148:151], v[164:167], v[48:51]
	v_mfma_f32_16x16x32_bf16 v[44:47], v[140:143], v[172:175], v[44:47]
	v_mfma_f32_16x16x32_bf16 v[40:43], v[148:151], v[172:175], v[40:43]
	v_mfma_f32_16x16x32_bf16 v[36:39], v[140:143], v[180:183], v[36:39]
	v_mfma_f32_16x16x32_bf16 v[32:35], v[148:151], v[180:183], v[32:35]
	v_mfma_f32_16x16x32_bf16 v[60:63], v[144:147], v[160:163], v[60:63]
	v_mfma_f32_16x16x32_bf16 v[56:59], v[152:155], v[160:163], v[56:59]
	v_mfma_f32_16x16x32_bf16 v[52:55], v[144:147], v[168:171], v[52:55]
	v_mfma_f32_16x16x32_bf16 v[48:51], v[152:155], v[168:171], v[48:51]
	v_mfma_f32_16x16x32_bf16 v[44:47], v[144:147], v[176:179], v[44:47]
	v_mfma_f32_16x16x32_bf16 v[40:43], v[152:155], v[176:179], v[40:43]
	v_mfma_f32_16x16x32_bf16 v[36:39], v[144:147], v[184:187], v[36:39]
	v_mfma_f32_16x16x32_bf16 v[32:35], v[152:155], v[184:187], v[32:35]
	s_setprio 0
	s_barrier
	v_mov_b32_e32 v140, v130
	v_mov_b32_e32 v196, v128
	v_mov_b32_e32 v141, v197
	s_mov_b32 m0, s72
	s_add_u32 s98, s56, s48
	s_addc_u32 s99, s57, s49
	global_load_lds_dwordx4 v128, s[98:99]
	s_mov_b32 m0, s36
	s_nop 0
	global_load_lds_dwordx4 v130, s[98:99]
	s_waitcnt vmcnt(6)
	s_barrier
	s_setprio 1
	v_mfma_f32_16x16x32_bf16 v[28:31], v[188:191], v[156:159], v[28:31]
	v_mfma_f32_16x16x32_bf16 v[24:27], v[202:205], v[156:159], v[24:27]
	v_mfma_f32_16x16x32_bf16 v[20:23], v[188:191], v[164:167], v[20:23]
	v_mfma_f32_16x16x32_bf16 v[16:19], v[202:205], v[164:167], v[16:19]
	v_mfma_f32_16x16x32_bf16 v[12:15], v[188:191], v[172:175], v[12:15]
	v_mfma_f32_16x16x32_bf16 v[8:11], v[202:205], v[172:175], v[8:11]
	v_mfma_f32_16x16x32_bf16 v[4:7], v[188:191], v[180:183], v[4:7]
	v_mfma_f32_16x16x32_bf16 v[0:3], v[202:205], v[180:183], v[0:3]
	v_mfma_f32_16x16x32_bf16 v[28:31], v[192:195], v[160:163], v[28:31]
	v_mfma_f32_16x16x32_bf16 v[24:27], v[206:209], v[160:163], v[24:27]
	v_mfma_f32_16x16x32_bf16 v[20:23], v[192:195], v[168:171], v[20:23]
	v_mfma_f32_16x16x32_bf16 v[16:19], v[206:209], v[168:171], v[16:19]
	v_mfma_f32_16x16x32_bf16 v[12:15], v[192:195], v[176:179], v[12:15]
	v_mfma_f32_16x16x32_bf16 v[8:11], v[206:209], v[176:179], v[8:11]
	v_mfma_f32_16x16x32_bf16 v[4:7], v[192:195], v[184:187], v[4:7]
	v_mfma_f32_16x16x32_bf16 v[0:3], v[206:209], v[184:187], v[0:3]
	s_setprio 0
	s_add_i32 s37, s37, 2
	s_add_u32 s10, s10, 0x100
	s_addc_u32 s11, s11, 0
	s_cmp_lt_u32 s37, 28
	s_barrier
	s_cbranch_scc1 .LBB0_568
	s_lshl_b64 s[4:5], s[4:5], 12
	s_add_u32 s4, s67, s4
	s_addc_u32 s5, s53, s5
	ds_read_b128 v[140:143], v129
	ds_read_b128 v[144:147], v129 offset:1024
	ds_read_b128 v[148:151], v129 offset:2048
	ds_read_b128 v[152:155], v129 offset:3072
	ds_read_b128 v[156:159], v136
	ds_read_b128 v[160:163], v136 offset:1024
	ds_read_b128 v[164:167], v135
	ds_read_b128 v[168:171], v135 offset:1024
	ds_read_b128 v[172:175], v134
	ds_read_b128 v[176:179], v134 offset:1024
	ds_read_b128 v[180:183], v133
	ds_read_b128 v[184:187], v133 offset:1024
	v_mov_b32_e32 v129, v197
	v_lshl_add_u64 v[128:129], s[4:5], 0, v[128:129]
	s_mov_b64 s[6:7], 0xf80
	s_mov_b32 m0, s39
	v_lshl_add_u64 v[128:129], v[128:129], 0, s[6:7]
	v_mov_b32_e32 v131, v197
	global_load_lds_dwordx4 v[128:129], off
	v_lshl_add_u64 v[128:129], s[4:5], 0, v[130:131]
	v_lshl_add_u64 v[128:129], v[128:129], 0, s[6:7]
	s_mov_b32 m0, s38
	s_nop 0
	global_load_lds_dwordx4 v[128:129], off
	s_barrier
	s_waitcnt lgkmcnt(0)
	s_setprio 1
	s_waitcnt lgkmcnt(0)
	v_mfma_f32_16x16x32_bf16 v[124:127], v[140:143], v[156:159], v[124:127]
	v_mfma_f32_16x16x32_bf16 v[120:123], v[148:151], v[156:159], v[120:123]
	v_mfma_f32_16x16x32_bf16 v[116:119], v[140:143], v[164:167], v[116:119]
	v_mfma_f32_16x16x32_bf16 v[112:115], v[148:151], v[164:167], v[112:115]
	v_mfma_f32_16x16x32_bf16 v[100:103], v[140:143], v[180:183], v[100:103]
	v_mfma_f32_16x16x32_bf16 v[96:99], v[148:151], v[180:183], v[96:99]
	v_mfma_f32_16x16x32_bf16 v[124:127], v[144:147], v[160:163], v[124:127]
	v_mfma_f32_16x16x32_bf16 v[120:123], v[152:155], v[160:163], v[120:123]
	v_mfma_f32_16x16x32_bf16 v[116:119], v[144:147], v[168:171], v[116:119]
	v_mfma_f32_16x16x32_bf16 v[112:115], v[152:155], v[168:171], v[112:115]
	v_mfma_f32_16x16x32_bf16 v[108:111], v[140:143], v[172:175], v[108:111]
	v_mfma_f32_16x16x32_bf16 v[104:107], v[148:151], v[172:175], v[104:107]
	v_mfma_f32_16x16x32_bf16 v[100:103], v[144:147], v[184:187], v[100:103]
	v_mfma_f32_16x16x32_bf16 v[96:99], v[152:155], v[184:187], v[96:99]
	v_mfma_f32_16x16x32_bf16 v[128:131], v[144:147], v[176:179], v[108:111]
	v_mfma_f32_16x16x32_bf16 v[188:191], v[152:155], v[176:179], v[104:107]
	s_setprio 0
	s_barrier
	s_nop 1
	ds_read_b128 v[104:107], v139
	ds_read_b128 v[108:111], v139 offset:1024
	ds_read_b128 v[192:195], v139 offset:2048
	ds_read_b128 v[202:205], v139 offset:3072
	s_barrier
	s_waitcnt lgkmcnt(0)
	s_setprio 1
	s_waitcnt lgkmcnt(0)
	v_mfma_f32_16x16x32_bf16 v[84:87], v[104:107], v[164:167], v[84:87]
	v_mfma_f32_16x16x32_bf16 v[80:83], v[192:195], v[164:167], v[80:83]
	v_mfma_f32_16x16x32_bf16 v[68:71], v[104:107], v[180:183], v[68:71]
	v_mfma_f32_16x16x32_bf16 v[64:67], v[192:195], v[180:183], v[64:67]
	v_mfma_f32_16x16x32_bf16 v[92:95], v[104:107], v[156:159], v[92:95]
	v_mfma_f32_16x16x32_bf16 v[88:91], v[192:195], v[156:159], v[88:91]
	v_mfma_f32_16x16x32_bf16 v[84:87], v[108:111], v[168:171], v[84:87]
	v_mfma_f32_16x16x32_bf16 v[80:83], v[202:205], v[168:171], v[80:83]
	v_mfma_f32_16x16x32_bf16 v[76:79], v[104:107], v[172:175], v[76:79]
	v_mfma_f32_16x16x32_bf16 v[72:75], v[192:195], v[172:175], v[72:75]
	v_mfma_f32_16x16x32_bf16 v[68:71], v[108:111], v[184:187], v[68:71]
	v_mfma_f32_16x16x32_bf16 v[64:67], v[202:205], v[184:187], v[64:67]
	v_mfma_f32_16x16x32_bf16 v[206:209], v[108:111], v[160:163], v[92:95]
	v_mfma_f32_16x16x32_bf16 v[156:159], v[202:205], v[160:163], v[88:91]
	v_mfma_f32_16x16x32_bf16 v[160:163], v[108:111], v[176:179], v[76:79]
	v_mfma_f32_16x16x32_bf16 v[164:167], v[202:205], v[176:179], v[72:75]
	s_setprio 0
	s_barrier
	s_nop 0
	ds_read_b128 v[72:75], v136 offset:16384
	ds_read_b128 v[76:79], v136 offset:17408
	ds_read_b128 v[88:91], v135 offset:16384
	ds_read_b128 v[92:95], v135 offset:17408
	ds_read_b128 v[168:171], v134 offset:16384
	ds_read_b128 v[172:175], v134 offset:17408
	ds_read_b128 v[176:179], v133 offset:16384
	ds_read_b128 v[180:183], v133 offset:17408
	s_waitcnt vmcnt(4)
	s_barrier
	s_waitcnt lgkmcnt(0)
	s_setprio 1
	s_waitcnt lgkmcnt(0)
	v_mfma_f32_16x16x32_bf16 v[60:63], v[140:143], v[72:75], v[60:63]
	v_mfma_f32_16x16x32_bf16 v[56:59], v[148:151], v[72:75], v[56:59]
	v_mfma_f32_16x16x32_bf16 v[52:55], v[140:143], v[88:91], v[52:55]
	v_mfma_f32_16x16x32_bf16 v[48:51], v[148:151], v[88:91], v[48:51]
	v_mfma_f32_16x16x32_bf16 v[36:39], v[140:143], v[176:179], v[36:39]
	v_mfma_f32_16x16x32_bf16 v[32:35], v[148:151], v[176:179], v[32:35]
	v_mfma_f32_16x16x32_bf16 v[60:63], v[144:147], v[76:79], v[60:63]
	v_mfma_f32_16x16x32_bf16 v[56:59], v[152:155], v[76:79], v[56:59]
	v_mfma_f32_16x16x32_bf16 v[52:55], v[144:147], v[92:95], v[52:55]
	v_mfma_f32_16x16x32_bf16 v[48:51], v[152:155], v[92:95], v[48:51]
	v_mfma_f32_16x16x32_bf16 v[44:47], v[140:143], v[168:171], v[44:47]
	v_mfma_f32_16x16x32_bf16 v[40:43], v[148:151], v[168:171], v[40:43]
	v_mfma_f32_16x16x32_bf16 v[36:39], v[144:147], v[180:183], v[36:39]
	v_mfma_f32_16x16x32_bf16 v[32:35], v[152:155], v[180:183], v[32:35]
	v_mfma_f32_16x16x32_bf16 v[184:187], v[144:147], v[172:175], v[44:47]
	v_mfma_f32_16x16x32_bf16 v[210:213], v[152:155], v[172:175], v[40:43]
	s_setprio 0
	s_setprio 1
	v_mfma_f32_16x16x32_bf16 v[20:23], v[104:107], v[88:91], v[20:23]
	v_mfma_f32_16x16x32_bf16 v[16:19], v[192:195], v[88:91], v[16:19]
	v_mfma_f32_16x16x32_bf16 v[4:7], v[104:107], v[176:179], v[4:7]
	v_mfma_f32_16x16x32_bf16 v[0:3], v[192:195], v[176:179], v[0:3]
	v_mfma_f32_16x16x32_bf16 v[28:31], v[104:107], v[72:75], v[28:31]
	v_mfma_f32_16x16x32_bf16 v[24:27], v[192:195], v[72:75], v[24:27]
	v_mfma_f32_16x16x32_bf16 v[20:23], v[108:111], v[92:95], v[20:23]
	v_mfma_f32_16x16x32_bf16 v[16:19], v[202:205], v[92:95], v[16:19]
	v_mfma_f32_16x16x32_bf16 v[12:15], v[104:107], v[168:171], v[12:15]
	v_mfma_f32_16x16x32_bf16 v[8:11], v[192:195], v[168:171], v[8:11]
	v_mfma_f32_16x16x32_bf16 v[4:7], v[108:111], v[180:183], v[4:7]
	v_mfma_f32_16x16x32_bf16 v[0:3], v[202:205], v[180:183], v[0:3]
	v_mfma_f32_16x16x32_bf16 v[140:143], v[108:111], v[76:79], v[28:31]
	v_mfma_f32_16x16x32_bf16 v[144:147], v[202:205], v[76:79], v[24:27]
	v_mfma_f32_16x16x32_bf16 v[148:151], v[108:111], v[172:175], v[12:15]
	v_mfma_f32_16x16x32_bf16 v[152:155], v[202:205], v[172:175], v[8:11]
	s_setprio 0
	s_barrier
	s_nop 0
	ds_read_b128 v[8:11], v138
	ds_read_b128 v[12:15], v138 offset:1024
	ds_read_b128 v[168:171], v138 offset:2048
	ds_read_b128 v[172:175], v138 offset:3072
	ds_read_b128 v[24:27], v136 offset:32768
	ds_read_b128 v[28:31], v136 offset:33792
	ds_read_b128 v[40:43], v135 offset:32768
	ds_read_b128 v[44:47], v135 offset:33792
	ds_read_b128 v[176:179], v134 offset:32768
	ds_read_b128 v[180:183], v134 offset:33792
	ds_read_b128 v[192:195], v133 offset:32768
	ds_read_b128 v[202:205], v133 offset:33792
	s_waitcnt vmcnt(2)
	s_barrier
	s_waitcnt lgkmcnt(0)
	s_setprio 1
	s_waitcnt lgkmcnt(0)
	v_mfma_f32_16x16x32_bf16 v[72:75], v[8:11], v[24:27], v[124:127]
	v_mfma_f32_16x16x32_bf16 v[124:127], v[12:15], v[28:31], v[72:75]
	v_mfma_f32_16x16x32_bf16 v[72:75], v[168:171], v[24:27], v[120:123]
	v_mfma_f32_16x16x32_bf16 v[120:123], v[172:175], v[28:31], v[72:75]
	v_mfma_f32_16x16x32_bf16 v[72:75], v[8:11], v[40:43], v[116:119]
	v_mfma_f32_16x16x32_bf16 v[108:111], v[12:15], v[44:47], v[72:75]
	v_mfma_f32_16x16x32_bf16 v[72:75], v[168:171], v[40:43], v[112:115]
	v_mfma_f32_16x16x32_bf16 v[104:107], v[172:175], v[44:47], v[72:75]
	v_mfma_f32_16x16x32_bf16 v[72:75], v[8:11], v[176:179], v[128:131]
	v_mfma_f32_16x16x32_bf16 v[92:95], v[12:15], v[180:183], v[72:75]
	v_mfma_f32_16x16x32_bf16 v[72:75], v[168:171], v[176:179], v[188:191]
	v_mfma_f32_16x16x32_bf16 v[88:91], v[172:175], v[180:183], v[72:75]
	v_mfma_f32_16x16x32_bf16 v[72:75], v[8:11], v[192:195], v[100:103]
	v_mfma_f32_16x16x32_bf16 v[76:79], v[12:15], v[202:205], v[72:75]
	v_mfma_f32_16x16x32_bf16 v[72:75], v[168:171], v[192:195], v[96:99]
	v_mfma_f32_16x16x32_bf16 v[72:75], v[172:175], v[202:205], v[72:75]
	s_setprio 0
	s_barrier
	ds_read_b128 v[128:131], v137
	ds_read_b128 v[188:191], v137 offset:1024
	ds_read_b128 v[214:217], v137 offset:2048
	ds_read_b128 v[218:221], v137 offset:3072
	s_waitcnt vmcnt(0)
	s_barrier
	s_waitcnt lgkmcnt(0)
	s_setprio 1
	s_waitcnt lgkmcnt(0)
	v_mfma_f32_16x16x32_bf16 v[96:99], v[128:131], v[24:27], v[206:209]
	v_mfma_f32_16x16x32_bf16 v[24:27], v[214:217], v[24:27], v[156:159]
	v_mfma_f32_16x16x32_bf16 v[112:115], v[218:221], v[28:31], v[24:27]
	v_mfma_f32_16x16x32_bf16 v[24:27], v[128:131], v[40:43], v[84:87]
	v_mfma_f32_16x16x32_bf16 v[100:103], v[188:191], v[44:47], v[24:27]
	v_mfma_f32_16x16x32_bf16 v[24:27], v[214:217], v[40:43], v[80:83]
	v_mfma_f32_16x16x32_bf16 v[116:119], v[188:191], v[28:31], v[96:99]
	v_mfma_f32_16x16x32_bf16 v[96:99], v[218:221], v[44:47], v[24:27]
	v_mfma_f32_16x16x32_bf16 v[24:27], v[128:131], v[176:179], v[160:163]
	v_mfma_f32_16x16x32_bf16 v[84:87], v[188:191], v[180:183], v[24:27]
	v_mfma_f32_16x16x32_bf16 v[24:27], v[214:217], v[176:179], v[164:167]
	v_mfma_f32_16x16x32_bf16 v[80:83], v[218:221], v[180:183], v[24:27]
	v_mfma_f32_16x16x32_bf16 v[24:27], v[128:131], v[192:195], v[68:71]
	v_mfma_f32_16x16x32_bf16 v[68:71], v[188:191], v[202:205], v[24:27]
	v_mfma_f32_16x16x32_bf16 v[24:27], v[214:217], v[192:195], v[64:67]
	v_mfma_f32_16x16x32_bf16 v[64:67], v[218:221], v[202:205], v[24:27]
	s_setprio 0
	s_barrier
	ds_read_b128 v[156:159], v136 offset:49152
	ds_read_b128 v[136:139], v136 offset:50176
	ds_read_b128 v[160:163], v135 offset:49152
	ds_read_b128 v[164:167], v135 offset:50176
	ds_read_b128 v[176:179], v134 offset:49152
	ds_read_b128 v[180:183], v134 offset:50176
	ds_read_b128 v[192:195], v133 offset:49152
	ds_read_b128 v[202:205], v133 offset:50176
	s_barrier
	s_waitcnt lgkmcnt(0)
	s_setprio 1
	s_waitcnt lgkmcnt(0)
	v_mfma_f32_16x16x32_bf16 v[24:27], v[8:11], v[156:159], v[60:63]
	v_mfma_f32_16x16x32_bf16 v[60:63], v[12:15], v[136:139], v[24:27]
	v_mfma_f32_16x16x32_bf16 v[24:27], v[168:171], v[156:159], v[56:59]
	v_mfma_f32_16x16x32_bf16 v[56:59], v[172:175], v[136:139], v[24:27]
	v_mfma_f32_16x16x32_bf16 v[24:27], v[8:11], v[160:163], v[52:55]
	v_mfma_f32_16x16x32_bf16 v[44:47], v[12:15], v[164:167], v[24:27]
	v_mfma_f32_16x16x32_bf16 v[24:27], v[168:171], v[160:163], v[48:51]
	v_mfma_f32_16x16x32_bf16 v[40:43], v[172:175], v[164:167], v[24:27]
	v_mfma_f32_16x16x32_bf16 v[24:27], v[8:11], v[176:179], v[184:187]
	v_mfma_f32_16x16x32_bf16 v[8:11], v[8:11], v[192:195], v[36:39]
	v_mfma_f32_16x16x32_bf16 v[28:31], v[12:15], v[180:183], v[24:27]
	v_mfma_f32_16x16x32_bf16 v[24:27], v[168:171], v[176:179], v[210:213]
	v_mfma_f32_16x16x32_bf16 v[12:15], v[12:15], v[202:205], v[8:11]
	v_mfma_f32_16x16x32_bf16 v[8:11], v[168:171], v[192:195], v[32:35]
	v_mfma_f32_16x16x32_bf16 v[24:27], v[172:175], v[180:183], v[24:27]
	v_mfma_f32_16x16x32_bf16 v[8:11], v[172:175], v[202:205], v[8:11]
	s_setprio 0
	s_setprio 1
	v_mfma_f32_16x16x32_bf16 v[32:35], v[128:131], v[156:159], v[140:143]
	v_mfma_f32_16x16x32_bf16 v[52:55], v[188:191], v[136:139], v[32:35]
	v_mfma_f32_16x16x32_bf16 v[32:35], v[214:217], v[156:159], v[144:147]
	v_mfma_f32_16x16x32_bf16 v[16:19], v[214:217], v[160:163], v[16:19]
	v_mfma_f32_16x16x32_bf16 v[48:51], v[218:221], v[136:139], v[32:35]
	v_mfma_f32_16x16x32_bf16 v[20:23], v[128:131], v[160:163], v[20:23]
	v_mfma_f32_16x16x32_bf16 v[32:35], v[218:221], v[164:167], v[16:19]
	v_mfma_f32_16x16x32_bf16 v[16:19], v[128:131], v[176:179], v[148:151]
	v_mfma_f32_16x16x32_bf16 v[36:39], v[188:191], v[164:167], v[20:23]
	v_mfma_f32_16x16x32_bf16 v[20:23], v[188:191], v[180:183], v[16:19]
	v_mfma_f32_16x16x32_bf16 v[16:19], v[214:217], v[176:179], v[152:155]
	v_mfma_f32_16x16x32_bf16 v[4:7], v[128:131], v[192:195], v[4:7]
	v_mfma_f32_16x16x32_bf16 v[0:3], v[214:217], v[192:195], v[0:3]
	v_mfma_f32_16x16x32_bf16 v[16:19], v[218:221], v[180:183], v[16:19]
	v_mfma_f32_16x16x32_bf16 v[4:7], v[188:191], v[202:205], v[4:7]
	v_mfma_f32_16x16x32_bf16 v[0:3], v[218:221], v[202:205], v[0:3]
	s_setprio 0
	s_movk_i32 s4, 0x100
	v_cmp_gt_u32_e32 vcc, s4, v132
	s_barrier
	s_and_saveexec_b64 s[4:5], vcc
	s_cbranch_execz .LBB0_571
	s_barrier

	.amdhsa_kernel _Z4mega6Params
		.amdhsa_group_segment_fixed_size 131072
		.amdhsa_private_segment_fixed_size 0
		.amdhsa_kernarg_size 488
		.amdhsa_user_sgpr_count 2
		.amdhsa_user_sgpr_dispatch_ptr 0
		.amdhsa_user_sgpr_queue_ptr 0
		.amdhsa_user_sgpr_kernarg_segment_ptr 1
		.amdhsa_user_sgpr_dispatch_id 0
		.amdhsa_user_sgpr_kernarg_preload_length 0
		.amdhsa_user_sgpr_kernarg_preload_offset 0
		.amdhsa_user_sgpr_private_segment_size 0
		.amdhsa_uses_dynamic_stack 0
		.amdhsa_enable_private_segment 0
		.amdhsa_system_sgpr_workgroup_id_x 1
		.amdhsa_system_sgpr_workgroup_id_y 0
		.amdhsa_system_sgpr_workgroup_id_z 0
		.amdhsa_system_sgpr_workgroup_info 0
		.amdhsa_system_vgpr_workitem_id 2
		.amdhsa_next_free_vgpr 256
		.amdhsa_next_free_sgpr 100
		.amdhsa_accum_offset 256
		.amdhsa_reserve_vcc 1
		.amdhsa_float_round_mode_32 0
		.amdhsa_float_round_mode_16_64 0
		.amdhsa_float_denorm_mode_32 3
		.amdhsa_float_denorm_mode_16_64 3
		.amdhsa_dx10_clamp 1
		.amdhsa_ieee_mode 1
		.amdhsa_fp16_overflow 0
		.amdhsa_tg_split 0
		.amdhsa_exception_fp_ieee_invalid_op 0
		.amdhsa_exception_fp_denorm_src 0
		.amdhsa_exception_fp_ieee_div_zero 0
		.amdhsa_exception_fp_ieee_overflow 0
		.amdhsa_exception_fp_ieee_underflow 0
		.amdhsa_exception_fp_ieee_inexact 0
		.amdhsa_exception_int_div_zero 0
	.end_amdhsa_kernel

amdhsa.kernels:
  - .agpr_count:     0
    .args:
      - .offset:         0
        .size:           232
        .value_kind:     by_value
      - .offset:         232
        .size:           4
        .value_kind:     hidden_block_count_x
      - .offset:         236
        .size:           4
        .value_kind:     hidden_block_count_y
      - .offset:         240
        .size:           4
        .value_kind:     hidden_block_count_z
      - .offset:         244
        .size:           2
        .value_kind:     hidden_group_size_x
      - .offset:         246
        .size:           2
        .value_kind:     hidden_group_size_y
      - .offset:         248
        .size:           2
        .value_kind:     hidden_group_size_z
      - .offset:         250
        .size:           2
        .value_kind:     hidden_remainder_x
      - .offset:         252
        .size:           2
        .value_kind:     hidden_remainder_y
      - .offset:         254
        .size:           2
        .value_kind:     hidden_remainder_z
      - .offset:         272
        .size:           8
        .value_kind:     hidden_global_offset_x
      - .offset:         280
        .size:           8
        .value_kind:     hidden_global_offset_y
      - .offset:         288
        .size:           8
        .value_kind:     hidden_global_offset_z
      - .offset:         296
        .size:           2
        .value_kind:     hidden_grid_dims
      - .offset:         320
        .size:           8
        .value_kind:     hidden_multigrid_sync_arg
    .group_segment_fixed_size: 131072
    .kernarg_segment_align: 8
    .kernarg_segment_size: 488
    .language:       OpenCL C
    .language_version:
      - 2
      - 0
    .max_flat_workgroup_size: 512
    .name:           _Z4mega6Params
    .private_segment_fixed_size: 0
    .sgpr_count:     106
    .sgpr_spill_count: 150
    .symbol:         _Z4mega6Params.kd
    .uniform_work_group_size: 1
    .uses_dynamic_stack: false
    .vgpr_count:     256
    .vgpr_spill_count: 0
    .wavefront_size: 64
